# adds: P6 query epilogue rewritten (quarter-row ssq loads + bpermute exchange, cvt_pk packs), quant_h2 loads of both passes batched
# speedup vs baseline: 1.0318x; 1.0045x over previous
;     __device__ __forceinline__ void fused(pg8::f32x4 (&acc)[2][2][4][2], const pg8::Unit& u, int wr, int wc, int fr, int fq, PG8_LAS unsigned char* lds, int wid, int lane) const {
;     ...
;             for (int n = 0; n < 2; ++n) bv[bj][n] = *(const f32x4*)(biasq + (size_t)b * 2048 + col0 + bj * 128 + 4 * n);
;     ...
;                 const int rl = ai * 128 + wr * 64 + m * 16 + fr; const size_t row = (size_t)u.pm * 256 + rl;
;                 const f32x4 s0 = *(const f32x4*)(ssq + row * 16), s1 = *(const f32x4*)(ssq + row * 16 + 4), s2 = *(const f32x4*)(ssq + row * 16 + 8), s3 = *(const f32x4*)(ssq + row * 16 + 12);
;                 const float tot = ((s0.x + s0.y) + (s0.z + s0.w)) + ((s1.x + s1.y) + (s1.z + s1.w)) + ((s2.x + s2.y) + (s2.z + s2.w)) + ((s3.x + s3.y) + (s3.z + s3.w));
;                 const float rstd = rsqrtf(tot * (1.f / D) + EPS);
.LBB0_807:
	s_barrier
	s_mov_b32 s58, vcc_lo
	v_bfe_u32 v234, v167, 4, 2
	v_and_b32_e32 v235, 15, v100
	s_ashr_i32 s0, s24, 3
	s_lshl_b32 s0, s0, 13
	v_readlane_b32 s16, v240, 12
	v_readlane_b32 s17, v240, 13
	s_add_u32 s36, s16, s0
	s_addc_u32 s37, s17, 0
	s_lshl_b32 s0, s58, 5
	s_lshl_b32 s1, s22, 8
	s_or_b32 s0, s0, s1
	v_lshl_or_b32 v244, v234, 3, s0
	v_lshlrev_b32_e32 v244, 2, v244
	global_load_dwordx4 v[170:173], v244, s[36:37]
	global_load_dwordx4 v[174:177], v244, s[36:37] offset:16
	global_load_dwordx4 v[178:181], v244, s[36:37] offset:512
	global_load_dwordx4 v[182:185], v244, s[36:37] offset:528
	s_lshl_b32 s0, s24, 14
	s_add_u32 s40, s8, s0
	s_addc_u32 s41, s9, 0
	v_lshlrev_b32_e32 v243, 6, v100
	v_lshl_or_b32 v243, v234, 4, v243
	v_add_u32_e32 v246, 0x2000, v243
	global_load_dwordx4 v[186:189], v243, s[40:41]
	global_load_dwordx4 v[190:193], v243, s[40:41] offset:1024
	global_load_dwordx4 v[194:197], v243, s[40:41] offset:2048
	global_load_dwordx4 v[198:201], v243, s[40:41] offset:3072
	global_load_dwordx4 v[202:205], v246, s[40:41]
	global_load_dwordx4 v[206:209], v246, s[40:41] offset:1024
	global_load_dwordx4 v[210:213], v246, s[40:41] offset:2048
	global_load_dwordx4 v[214:217], v246, s[40:41] offset:3072
	v_lshlrev_b32_e32 v236, 2, v235
	v_add_u32_e32 v237, 64, v236
	v_add_u32_e32 v238, 0x80, v236
	v_add_u32_e32 v239, 0xc0, v236
	v_lshrrev_b32_e32 v241, 6, v100
	v_lshlrev_b32_e32 v241, 15, v241
	v_lshl_or_b32 v241, v235, 4, v241
	s_lshl_b32 s0, s58, 11
	v_lshl_or_b32 v241, v234, 9, v241
	v_or_b32_e32 v241, s0, v241
	v_add_u32_e32 v242, 0x10000, v241
	v_mov_b32_e32 v245, 0x358637bd
	s_waitcnt vmcnt(0)
	v_add_f32_e32 v186, v186, v187
	v_add_f32_e32 v188, v188, v189
	v_add_f32_e32 v218, v186, v188
	v_add_f32_e32 v190, v190, v191
	v_add_f32_e32 v192, v192, v193
	v_add_f32_e32 v220, v190, v192
	v_add_f32_e32 v194, v194, v195
	v_add_f32_e32 v196, v196, v197
	v_add_f32_e32 v222, v194, v196
	v_add_f32_e32 v198, v198, v199
	v_add_f32_e32 v200, v200, v201
	v_add_f32_e32 v224, v198, v200
	v_add_f32_e32 v202, v202, v203
	v_add_f32_e32 v204, v204, v205
	v_add_f32_e32 v226, v202, v204
	v_add_f32_e32 v206, v206, v207
	v_add_f32_e32 v208, v208, v209
	v_add_f32_e32 v228, v206, v208
	v_add_f32_e32 v210, v210, v211
	v_add_f32_e32 v212, v212, v213
	v_add_f32_e32 v230, v210, v212
	v_add_f32_e32 v214, v214, v215
	v_add_f32_e32 v216, v216, v217
	v_add_f32_e32 v232, v214, v216
	ds_bpermute_b32 v186, v236, v218
	ds_bpermute_b32 v187, v237, v218
	ds_bpermute_b32 v188, v238, v218
	ds_bpermute_b32 v189, v239, v218
	ds_bpermute_b32 v190, v236, v220
	ds_bpermute_b32 v191, v237, v220
	ds_bpermute_b32 v192, v238, v220
	ds_bpermute_b32 v193, v239, v220
	ds_bpermute_b32 v194, v236, v222
	ds_bpermute_b32 v195, v237, v222
	ds_bpermute_b32 v196, v238, v222
	ds_bpermute_b32 v197, v239, v222
	ds_bpermute_b32 v198, v236, v224
	ds_bpermute_b32 v199, v237, v224
	ds_bpermute_b32 v200, v238, v224
	ds_bpermute_b32 v201, v239, v224
	s_waitcnt lgkmcnt(12)
	v_add_f32_e32 v186, v186, v187
	v_add_f32_e32 v186, v186, v188
	v_add_f32_e32 v186, v186, v189
	v_fmamk_f32 v186, v186, 0x3a800000, v245
	v_rsq_f32_e32 v218, v186
	s_waitcnt lgkmcnt(8)
	v_add_f32_e32 v190, v190, v191
	v_add_f32_e32 v190, v190, v192
	v_add_f32_e32 v190, v190, v193
	v_fmamk_f32 v190, v190, 0x3a800000, v245
	v_rsq_f32_e32 v220, v190
	s_waitcnt lgkmcnt(4)
	v_add_f32_e32 v194, v194, v195
	v_add_f32_e32 v194, v194, v196
	v_add_f32_e32 v194, v194, v197
	v_fmamk_f32 v194, v194, 0x3a800000, v245
	v_rsq_f32_e32 v222, v194
	s_waitcnt lgkmcnt(0)
	v_add_f32_e32 v198, v198, v199
	v_add_f32_e32 v198, v198, v200
	v_add_f32_e32 v198, v198, v201
	v_fmamk_f32 v198, v198, 0x3a800000, v245
	v_rsq_f32_e32 v224, v198
	ds_bpermute_b32 v202, v236, v226
	ds_bpermute_b32 v203, v237, v226
	ds_bpermute_b32 v204, v238, v226
	ds_bpermute_b32 v205, v239, v226
	ds_bpermute_b32 v206, v236, v228
	ds_bpermute_b32 v207, v237, v228
	ds_bpermute_b32 v208, v238, v228
	ds_bpermute_b32 v209, v239, v228
	ds_bpermute_b32 v210, v236, v230
	ds_bpermute_b32 v211, v237, v230
	ds_bpermute_b32 v212, v238, v230
	ds_bpermute_b32 v213, v239, v230
	ds_bpermute_b32 v214, v236, v232
	ds_bpermute_b32 v215, v237, v232
	ds_bpermute_b32 v216, v238, v232
	ds_bpermute_b32 v217, v239, v232
	s_waitcnt lgkmcnt(12)
	v_add_f32_e32 v202, v202, v203
	v_add_f32_e32 v202, v202, v204
	v_add_f32_e32 v202, v202, v205
	v_fmamk_f32 v202, v202, 0x3a800000, v245
	v_rsq_f32_e32 v226, v202
	s_waitcnt lgkmcnt(8)
	v_add_f32_e32 v206, v206, v207
	v_add_f32_e32 v206, v206, v208
	v_add_f32_e32 v206, v206, v209
	v_fmamk_f32 v206, v206, 0x3a800000, v245
	v_rsq_f32_e32 v228, v206
	s_waitcnt lgkmcnt(4)
	v_add_f32_e32 v210, v210, v211
	v_add_f32_e32 v210, v210, v212
	v_add_f32_e32 v210, v210, v213
	v_fmamk_f32 v210, v210, 0x3a800000, v245
	v_rsq_f32_e32 v230, v210
	s_waitcnt lgkmcnt(0)
; #define LAS __attribute__((address_space(3)))
; __device__ __forceinline__ unsigned pk2(float lo, float hi) { return f2bf(lo) | (f2bf(hi) << 16); }
;     __device__ __forceinline__ void fused(pg8::f32x4 (&acc)[2][2][4][2], const pg8::Unit& u, int wr, int wc, int fr, int fq, PG8_LAS unsigned char* lds, int wid, int lane) const {
;     ...
; #pragma unroll
;                 for (int bj = 0; bj < 2; ++bj) { const f32x4 v0 = acc[ai][bj][m][0] * rstd + bv[bj][0], v1 = acc[ai][bj][m][1] * rstd + bv[bj][1];
;                     v4u w; w.x = pk2(v0.x, v0.y); w.y = pk2(v0.z, v0.w); w.z = pk2(v1.x, v1.y); w.w = pk2(v1.z, v1.w);
;                     *(LAS v4u*)(lds + ((((rl >> 5) * 2 + bj) * 16 + kg) * 512 + (rl & 31) * 16)) = w; }
	v_add_f32_e32 v214, v214, v215
	v_add_f32_e32 v214, v214, v216
	v_add_f32_e32 v214, v214, v217
	v_fmamk_f32 v214, v214, 0x3a800000, v245
	v_rsq_f32_e32 v232, v214
	s_nop 0
	v_pk_fma_f32 v[142:143], v[142:143], v[218:219], v[170:171] op_sel_hi:[1,0,1]
	v_pk_fma_f32 v[144:145], v[144:145], v[218:219], v[172:173] op_sel_hi:[1,0,1]
	v_pk_fma_f32 v[138:139], v[138:139], v[218:219], v[174:175] op_sel_hi:[1,0,1]
	v_pk_fma_f32 v[140:141], v[140:141], v[218:219], v[176:177] op_sel_hi:[1,0,1]
	v_cvt_pk_bf16_f32 v142, v142, v143
	v_cvt_pk_bf16_f32 v143, v144, v145
	v_cvt_pk_bf16_f32 v144, v138, v139
	v_cvt_pk_bf16_f32 v145, v140, v141
	ds_write_b128 v241, v[142:145]
	v_pk_fma_f32 v[134:135], v[134:135], v[218:219], v[178:179] op_sel_hi:[1,0,1]
	v_pk_fma_f32 v[136:137], v[136:137], v[218:219], v[180:181] op_sel_hi:[1,0,1]
	v_pk_fma_f32 v[130:131], v[130:131], v[218:219], v[182:183] op_sel_hi:[1,0,1]
	v_pk_fma_f32 v[132:133], v[132:133], v[218:219], v[184:185] op_sel_hi:[1,0,1]
	v_cvt_pk_bf16_f32 v134, v134, v135
	v_cvt_pk_bf16_f32 v135, v136, v137
	v_cvt_pk_bf16_f32 v136, v130, v131
	v_cvt_pk_bf16_f32 v137, v132, v133
	ds_write_b128 v241, v[134:137] offset:8192
	v_pk_fma_f32 v[126:127], v[126:127], v[220:221], v[170:171] op_sel_hi:[1,0,1]
	v_pk_fma_f32 v[128:129], v[128:129], v[220:221], v[172:173] op_sel_hi:[1,0,1]
	v_pk_fma_f32 v[122:123], v[122:123], v[220:221], v[174:175] op_sel_hi:[1,0,1]
	v_pk_fma_f32 v[124:125], v[124:125], v[220:221], v[176:177] op_sel_hi:[1,0,1]
	v_cvt_pk_bf16_f32 v126, v126, v127
	v_cvt_pk_bf16_f32 v127, v128, v129
	v_cvt_pk_bf16_f32 v128, v122, v123
	v_cvt_pk_bf16_f32 v129, v124, v125
	ds_write_b128 v241, v[126:129] offset:256
	v_pk_fma_f32 v[118:119], v[118:119], v[220:221], v[178:179] op_sel_hi:[1,0,1]
	v_pk_fma_f32 v[120:121], v[120:121], v[220:221], v[180:181] op_sel_hi:[1,0,1]
	v_pk_fma_f32 v[114:115], v[114:115], v[220:221], v[182:183] op_sel_hi:[1,0,1]
	v_pk_fma_f32 v[116:117], v[116:117], v[220:221], v[184:185] op_sel_hi:[1,0,1]
	v_cvt_pk_bf16_f32 v118, v118, v119
	v_cvt_pk_bf16_f32 v119, v120, v121
	v_cvt_pk_bf16_f32 v120, v114, v115
	v_cvt_pk_bf16_f32 v121, v116, v117
	ds_write_b128 v241, v[118:121] offset:8448
	v_pk_fma_f32 v[94:95], v[94:95], v[222:223], v[170:171] op_sel_hi:[1,0,1]
	v_pk_fma_f32 v[96:97], v[96:97], v[222:223], v[172:173] op_sel_hi:[1,0,1]
	v_pk_fma_f32 v[90:91], v[90:91], v[222:223], v[174:175] op_sel_hi:[1,0,1]
	v_pk_fma_f32 v[92:93], v[92:93], v[222:223], v[176:177] op_sel_hi:[1,0,1]
	v_cvt_pk_bf16_f32 v94, v94, v95
	v_cvt_pk_bf16_f32 v95, v96, v97
	v_cvt_pk_bf16_f32 v96, v90, v91
	v_cvt_pk_bf16_f32 v97, v92, v93
	ds_write_b128 v241, v[94:97] offset:16384
	v_pk_fma_f32 v[86:87], v[86:87], v[222:223], v[178:179] op_sel_hi:[1,0,1]
	v_pk_fma_f32 v[88:89], v[88:89], v[222:223], v[180:181] op_sel_hi:[1,0,1]
	v_pk_fma_f32 v[82:83], v[82:83], v[222:223], v[182:183] op_sel_hi:[1,0,1]
	v_pk_fma_f32 v[84:85], v[84:85], v[222:223], v[184:185] op_sel_hi:[1,0,1]
	v_cvt_pk_bf16_f32 v86, v86, v87
	v_cvt_pk_bf16_f32 v87, v88, v89
	v_cvt_pk_bf16_f32 v88, v82, v83
	v_cvt_pk_bf16_f32 v89, v84, v85
	ds_write_b128 v241, v[86:89] offset:24576
	v_pk_fma_f32 v[78:79], v[78:79], v[224:225], v[170:171] op_sel_hi:[1,0,1]
	v_pk_fma_f32 v[80:81], v[80:81], v[224:225], v[172:173] op_sel_hi:[1,0,1]
	v_pk_fma_f32 v[74:75], v[74:75], v[224:225], v[174:175] op_sel_hi:[1,0,1]
	v_pk_fma_f32 v[76:77], v[76:77], v[224:225], v[176:177] op_sel_hi:[1,0,1]
	v_cvt_pk_bf16_f32 v78, v78, v79
	v_cvt_pk_bf16_f32 v79, v80, v81
	v_cvt_pk_bf16_f32 v80, v74, v75
	v_cvt_pk_bf16_f32 v81, v76, v77
	ds_write_b128 v241, v[78:81] offset:16640
	v_pk_fma_f32 v[70:71], v[70:71], v[224:225], v[178:179] op_sel_hi:[1,0,1]
	v_pk_fma_f32 v[72:73], v[72:73], v[224:225], v[180:181] op_sel_hi:[1,0,1]
	v_pk_fma_f32 v[66:67], v[66:67], v[224:225], v[182:183] op_sel_hi:[1,0,1]
	v_pk_fma_f32 v[68:69], v[68:69], v[224:225], v[184:185] op_sel_hi:[1,0,1]
	v_cvt_pk_bf16_f32 v70, v70, v71
	v_cvt_pk_bf16_f32 v71, v72, v73
	v_cvt_pk_bf16_f32 v72, v66, v67
	v_cvt_pk_bf16_f32 v73, v68, v69
	ds_write_b128 v241, v[70:73] offset:24832
	v_pk_fma_f32 v[62:63], v[62:63], v[226:227], v[170:171] op_sel_hi:[1,0,1]
	v_pk_fma_f32 v[64:65], v[64:65], v[226:227], v[172:173] op_sel_hi:[1,0,1]
	v_pk_fma_f32 v[58:59], v[58:59], v[226:227], v[174:175] op_sel_hi:[1,0,1]
	v_pk_fma_f32 v[60:61], v[60:61], v[226:227], v[176:177] op_sel_hi:[1,0,1]
	v_cvt_pk_bf16_f32 v62, v62, v63
	v_cvt_pk_bf16_f32 v63, v64, v65
	v_cvt_pk_bf16_f32 v64, v58, v59
	v_cvt_pk_bf16_f32 v65, v60, v61
	ds_write_b128 v242, v[62:65]
	v_pk_fma_f32 v[54:55], v[54:55], v[226:227], v[178:179] op_sel_hi:[1,0,1]
	v_pk_fma_f32 v[56:57], v[56:57], v[226:227], v[180:181] op_sel_hi:[1,0,1]
	v_pk_fma_f32 v[50:51], v[50:51], v[226:227], v[182:183] op_sel_hi:[1,0,1]
	v_pk_fma_f32 v[52:53], v[52:53], v[226:227], v[184:185] op_sel_hi:[1,0,1]
	v_cvt_pk_bf16_f32 v54, v54, v55
	v_cvt_pk_bf16_f32 v55, v56, v57
	v_cvt_pk_bf16_f32 v56, v50, v51
	v_cvt_pk_bf16_f32 v57, v52, v53
	ds_write_b128 v242, v[54:57] offset:8192
	v_pk_fma_f32 v[46:47], v[46:47], v[228:229], v[170:171] op_sel_hi:[1,0,1]
	v_pk_fma_f32 v[48:49], v[48:49], v[228:229], v[172:173] op_sel_hi:[1,0,1]
	v_pk_fma_f32 v[42:43], v[42:43], v[228:229], v[174:175] op_sel_hi:[1,0,1]
	v_pk_fma_f32 v[44:45], v[44:45], v[228:229], v[176:177] op_sel_hi:[1,0,1]
	v_cvt_pk_bf16_f32 v46, v46, v47
	v_cvt_pk_bf16_f32 v47, v48, v49
	v_cvt_pk_bf16_f32 v48, v42, v43
	v_cvt_pk_bf16_f32 v49, v44, v45
	ds_write_b128 v242, v[46:49] offset:256
	v_pk_fma_f32 v[38:39], v[38:39], v[228:229], v[178:179] op_sel_hi:[1,0,1]
	v_pk_fma_f32 v[40:41], v[40:41], v[228:229], v[180:181] op_sel_hi:[1,0,1]
; #define LAS __attribute__((address_space(3)))
; __device__ __forceinline__ unsigned pk2(float lo, float hi) { return f2bf(lo) | (f2bf(hi) << 16); }
; __device__ __forceinline__ void topk_p_lds(const bf16* __restrict__ skf, const char* qlds, int r32, int hi, unsigned (&Lst)[16]) {
;     bf16x8 bq[8];
; #pragma unroll
;     for (int ks = 0; ks < 8; ++ks) bq[ks] = *reinterpret_cast<const bf16x8*>(qlds + ((2 * ks + hi) * 32 + r32) * 16);
; #pragma unroll
;     for (int kb = 0; kb < 4; ++kb) {
;         bf16x8 a[8];
; #pragma unroll
;         for (int ks = 0; ks < 8; ++ks) a[ks] = *reinterpret_cast<const bf16x8*>(skf + (size_t)((((kb * 8 + ks) * 2 + hi) * 32 + r32) * 8));
;         f32x16 acc = {};
; #pragma unroll
;         for (int ks = 0; ks < 8; ++ks) acc = __builtin_amdgcn_mfma_f32_32x32x16_bf16(a[ks], bq[ks], acc, 0, 0, 0);
;     __device__ __forceinline__ void fused(pg8::f32x4 (&acc)[2][2][4][2], const pg8::Unit& u, int wr, int wc, int fr, int fq, PG8_LAS unsigned char* lds, int wid, int lane) const {
;     ...
;                 for (int bj = 0; bj < 2; ++bj) { const f32x4 v0 = acc[ai][bj][m][0] * rstd + bv[bj][0], v1 = acc[ai][bj][m][1] * rstd + bv[bj][1];
;                     v4u w; w.x = pk2(v0.x, v0.y); w.y = pk2(v0.z, v0.w); w.z = pk2(v1.x, v1.y); w.w = pk2(v1.z, v1.w);
;                     *(LAS v4u*)(lds + ((((rl >> 5) * 2 + bj) * 16 + kg) * 512 + (rl & 31) * 16)) = w; }
;             }
;         asm volatile("s_waitcnt lgkmcnt(0)" ::: "memory"); __builtin_amdgcn_s_barrier(); asm volatile("" ::: "memory");
;         peer::select_wave_lds(skf + (size_t)u.pn * (2 * 4 * 8 * 2 * 32 * 8), (char*)lds, u.pn, pidx + (size_t)u.pm * 256 * 128, pgate + (size_t)u.pm * 256 * 128, wid, lane);
	v_pk_fma_f32 v[34:35], v[34:35], v[228:229], v[182:183] op_sel_hi:[1,0,1]
	v_pk_fma_f32 v[36:37], v[36:37], v[228:229], v[184:185] op_sel_hi:[1,0,1]
	v_cvt_pk_bf16_f32 v38, v38, v39
	v_cvt_pk_bf16_f32 v39, v40, v41
	v_cvt_pk_bf16_f32 v40, v34, v35
	v_cvt_pk_bf16_f32 v41, v36, v37
	ds_write_b128 v242, v[38:41] offset:8448
	v_pk_fma_f32 v[30:31], v[30:31], v[230:231], v[170:171] op_sel_hi:[1,0,1]
	v_pk_fma_f32 v[32:33], v[32:33], v[230:231], v[172:173] op_sel_hi:[1,0,1]
	v_pk_fma_f32 v[26:27], v[26:27], v[230:231], v[174:175] op_sel_hi:[1,0,1]
	v_pk_fma_f32 v[28:29], v[28:29], v[230:231], v[176:177] op_sel_hi:[1,0,1]
	v_cvt_pk_bf16_f32 v30, v30, v31
	v_cvt_pk_bf16_f32 v31, v32, v33
	v_cvt_pk_bf16_f32 v32, v26, v27
	v_cvt_pk_bf16_f32 v33, v28, v29
	ds_write_b128 v242, v[30:33] offset:16384
	v_pk_fma_f32 v[22:23], v[22:23], v[230:231], v[178:179] op_sel_hi:[1,0,1]
	v_pk_fma_f32 v[24:25], v[24:25], v[230:231], v[180:181] op_sel_hi:[1,0,1]
	v_pk_fma_f32 v[18:19], v[18:19], v[230:231], v[182:183] op_sel_hi:[1,0,1]
	v_pk_fma_f32 v[20:21], v[20:21], v[230:231], v[184:185] op_sel_hi:[1,0,1]
	v_cvt_pk_bf16_f32 v22, v22, v23
	v_cvt_pk_bf16_f32 v23, v24, v25
	v_cvt_pk_bf16_f32 v24, v18, v19
	v_cvt_pk_bf16_f32 v25, v20, v21
	ds_write_b128 v242, v[22:25] offset:24576
	v_pk_fma_f32 v[14:15], v[14:15], v[232:233], v[170:171] op_sel_hi:[1,0,1]
	v_pk_fma_f32 v[16:17], v[16:17], v[232:233], v[172:173] op_sel_hi:[1,0,1]
	v_pk_fma_f32 v[10:11], v[10:11], v[232:233], v[174:175] op_sel_hi:[1,0,1]
	v_pk_fma_f32 v[12:13], v[12:13], v[232:233], v[176:177] op_sel_hi:[1,0,1]
	v_cvt_pk_bf16_f32 v14, v14, v15
	v_cvt_pk_bf16_f32 v15, v16, v17
	v_cvt_pk_bf16_f32 v16, v10, v11
	v_cvt_pk_bf16_f32 v17, v12, v13
	ds_write_b128 v242, v[14:17] offset:16640
	v_pk_fma_f32 v[6:7], v[6:7], v[232:233], v[178:179] op_sel_hi:[1,0,1]
	v_pk_fma_f32 v[8:9], v[8:9], v[232:233], v[180:181] op_sel_hi:[1,0,1]
	v_pk_fma_f32 v[2:3], v[2:3], v[232:233], v[182:183] op_sel_hi:[1,0,1]
	v_pk_fma_f32 v[4:5], v[4:5], v[232:233], v[184:185] op_sel_hi:[1,0,1]
	v_cvt_pk_bf16_f32 v6, v6, v7
	v_cvt_pk_bf16_f32 v7, v8, v9
	v_cvt_pk_bf16_f32 v8, v2, v3
	v_cvt_pk_bf16_f32 v9, v4, v5
	ds_write_b128 v242, v[6:9] offset:24832
	s_movk_i32 s19, 0x3000
	s_movk_i32 s33, 0x49
	v_and_b32_e32 v70, 63, v167
	v_bfe_u32 v62, v167, 5, 1
	v_lshlrev_b32_e32 v72, 2, v62
	s_movk_i32 s15, 0xff80
	s_lshl_b64 s[0:1], s[22:23], 16
	v_readlane_b32 s16, v240, 17
	v_readlane_b32 s17, v240, 18
	s_nop 3
	s_add_u32 s0, s16, s0
	v_and_b32_e32 v2, 0x1f0, v168
	s_waitcnt lgkmcnt(0)
	s_barrier
	s_addc_u32 s1, s17, s1
	v_lshl_or_b32 v148, v62, 9, v2
	global_load_dwordx4 v[2:5], v148, s[0:1]
	global_load_dwordx4 v[22:25], v148, s[0:1] offset:1024
	s_lshl_b32 s3, s72, 14
	s_add_i32 s3, s3, 0
	v_lshl_add_u32 v71, v70, 4, s3
	ds_read_b128 v[30:33], v71
	ds_read_b128 v[18:21], v71 offset:1024
	global_load_dwordx4 v[34:37], v148, s[0:1] offset:2048
	global_load_dwordx4 v[42:45], v148, s[0:1] offset:3072
	s_waitcnt vmcnt(3) lgkmcnt(1)
	v_mfma_f32_32x32x16_bf16 v[2:17], v[2:5], v[30:33], 0
	ds_read_b128 v[38:41], v71 offset:2048
	ds_read_b128 v[26:29], v71 offset:3072
	v_lshl_add_u64 v[66:67], s[0:1], 0, v[148:149]
	s_movk_i32 s0, 0x2000
	v_add_co_u32_e32 v54, vcc, s0, v66
	s_movk_i32 s0, 0x1000
	s_nop 0
	v_addc_co_u32_e32 v55, vcc, 0, v67, vcc
	s_waitcnt vmcnt(2) lgkmcnt(2)
	v_mfma_f32_32x32x16_bf16 v[2:17], v[22:25], v[18:21], v[2:17]
	global_load_dwordx4 v[46:49], v[54:55], off offset:-4096
	v_add_co_u32_e32 v60, vcc, s0, v66
	s_movk_i32 s0, 0x4000
	s_nop 0
	v_addc_co_u32_e32 v61, vcc, 0, v67, vcc
	v_add_co_u32_e32 v64, vcc, s19, v66
	s_waitcnt vmcnt(2) lgkmcnt(1)
	v_mfma_f32_32x32x16_bf16 v[2:17], v[34:37], v[38:41], v[2:17]
	v_addc_co_u32_e32 v65, vcc, 0, v67, vcc
	s_movk_i32 s16, 0x4b
	s_movk_i32 s17, 0x53
	s_movk_i32 s3, 0x41
	s_movk_i32 s23, 0x58
	s_waitcnt vmcnt(1) lgkmcnt(0)
	v_mfma_f32_32x32x16_bf16 v[2:17], v[42:45], v[26:29], v[2:17]
	global_load_dwordx4 v[42:45], v[60:61], off offset:1024
	ds_read_b128 v[34:37], v71 offset:4096
	ds_read_b128 v[22:25], v71 offset:5120
	global_load_dwordx4 v[50:53], v[54:55], off
	global_load_dwordx4 v[56:59], v[60:61], off offset:2048
	s_waitcnt vmcnt(3) lgkmcnt(1)
	v_mfma_f32_32x32x16_bf16 v[2:17], v[46:49], v[34:37], v[2:17]
	s_waitcnt vmcnt(2) lgkmcnt(0)
	v_mfma_f32_32x32x16_bf16 v[2:17], v[42:45], v[22:25], v[2:17]
	ds_read_b128 v[46:49], v71 offset:6144
	ds_read_b128 v[42:45], v71 offset:7168
	global_load_dwordx4 v[78:81], v[54:55], off offset:3072
	global_load_dwordx4 v[74:77], v[54:55], off offset:2048
	s_waitcnt vmcnt(2) lgkmcnt(1)
	v_mfma_f32_32x32x16_bf16 v[2:17], v[56:59], v[46:49], v[2:17]
	global_load_dwordx4 v[56:59], v[60:61], off offset:3072
	s_nop 0
	global_load_dwordx4 v[60:63], v[64:65], off offset:1024
	s_waitcnt vmcnt(1) lgkmcnt(0)
; __device__ __forceinline__ int crow(int r, int hi) { return (r & 3) + 8 * (r >> 2) + 4 * hi; }
; #define PEER_CE(i, j) do { const unsigned mx_ = kmax(a[i], a[j]), mn_ = kmin(a[i], a[j]); a[i] = mx_; a[j] = mn_; } while (0)
; __device__ __forceinline__ void sort16_desc(unsigned (&a)[16]) {
;     ...
;     PEER_CE(0, 13); PEER_CE(1, 12); PEER_CE(2, 15); PEER_CE(3, 14); PEER_CE(4, 8); PEER_CE(5, 6); PEER_CE(7, 11); PEER_CE(9, 10);
;     PEER_CE(0, 5); PEER_CE(1, 7); PEER_CE(2, 9); PEER_CE(3, 4); PEER_CE(6, 13); PEER_CE(8, 14); PEER_CE(10, 15); PEER_CE(11, 12);
;     PEER_CE(0, 1); PEER_CE(2, 3); PEER_CE(4, 5); PEER_CE(6, 8); PEER_CE(7, 9); PEER_CE(10, 11); PEER_CE(12, 13); PEER_CE(14, 15);
;     PEER_CE(0, 2); PEER_CE(1, 3); PEER_CE(4, 10); PEER_CE(5, 11); PEER_CE(6, 7); PEER_CE(8, 9); PEER_CE(12, 14); PEER_CE(13, 15);
;     PEER_CE(1, 2); PEER_CE(3, 12); PEER_CE(4, 6); PEER_CE(5, 7); PEER_CE(8, 10); PEER_CE(9, 11); PEER_CE(13, 14);
;     PEER_CE(1, 4); PEER_CE(2, 6); PEER_CE(5, 8); PEER_CE(7, 10); PEER_CE(9, 13); PEER_CE(11, 14);
;     PEER_CE(2, 4); PEER_CE(3, 6); PEER_CE(9, 12); PEER_CE(11, 13);
;     PEER_CE(3, 5); PEER_CE(6, 8); PEER_CE(7, 9); PEER_CE(10, 12);
;     PEER_CE(3, 4); PEER_CE(5, 6); PEER_CE(7, 8); PEER_CE(9, 10); PEER_CE(11, 12);
;     PEER_CE(6, 7); PEER_CE(8, 9);
;     ...
; }
; __device__ __forceinline__ void topk_p_lds(const bf16* __restrict__ skf, const char* qlds, int r32, int hi, unsigned (&Lst)[16]) {
;     ...
;         unsigned S[16];
; #pragma unroll
;         for (int r = 0; r < 16; ++r) S[r] = (__float_as_uint(acc[r]) & ~127u) | (unsigned)(32 * kb + crow(r, hi));
;         sort16_desc(S);
;         if (kb == 0) {
; #pragma unroll
;             for (int r = 0; r < 16; ++r) Lst[r] = S[r];
;         } else merge_top16(Lst, S);
	v_mfma_f32_32x32x16_bf16 v[2:17], v[56:59], v[42:45], v[2:17]
	global_load_dwordx4 v[56:59], v[54:55], off offset:1024
	v_add_co_u32_e32 v54, vcc, s0, v66
	s_movk_i32 s0, 0x6000
	s_nop 0
	v_addc_co_u32_e32 v55, vcc, 0, v67, vcc
	global_load_dwordx4 v[82:85], v[54:55], off offset:-4096
	s_nop 5
	v_and_b32_e32 v7, 0xffffff80, v7
	v_and_b32_e32 v8, 0xffffff80, v8
	v_and_b32_e32 v15, 0xffffff80, v15
	v_and_b32_e32 v6, 0xffffff80, v6
	v_and_b32_e32 v10, 0xffffff80, v10
	v_and_b32_e32 v5, 0xffffff80, v5
	v_and_b32_e32 v16, 0xffffff80, v16
	v_or3_b32 v7, v72, v7, 9
	v_or3_b32 v8, v72, v8, 10
	v_and_or_b32 v2, v2, s15, v72
	v_or3_b32 v15, v72, v15, 25
	v_or3_b32 v6, v72, v6, 8
	v_or3_b32 v10, v72, v10, 16
	v_or3_b32 v5, v72, v5, 3
	v_or3_b32 v16, v72, v16, 26
	v_max_f32_e32 v8, v8, v8
	v_max_f32_e32 v7, v7, v7
	v_max_f32_e32 v2, v2, v2
	v_max_f32_e32 v15, v15, v15
	v_max_f32_e32 v10, v10, v10
	v_max_f32_e32 v6, v6, v6
	v_max_f32_e32 v16, v16, v16
	v_max_f32_e32 v5, v5, v5
	v_min_f32_e32 v86, v7, v8
	v_min_f32_e32 v87, v2, v15
	v_min_f32_e32 v88, v6, v10
	v_min_f32_e32 v89, v5, v16
	v_min_f32_e32 v94, v86, v87
	v_min_f32_e32 v96, v88, v89
	v_max_f32_e32 v100, v86, v87
	v_max_f32_e32 v101, v88, v89
	global_load_dwordx4 v[86:89], v[64:65], off offset:2048
	v_and_b32_e32 v11, 0xffffff80, v11
	v_and_b32_e32 v12, 0xffffff80, v12
	v_and_b32_e32 v4, 0xffffff80, v4
	v_and_b32_e32 v17, 0xffffff80, v17
	v_or3_b32 v11, v72, v11, 17
	v_or3_b32 v12, v72, v12, 18
	v_or3_b32 v4, v72, v4, 2
	v_or3_b32 v17, v72, v17, 27
	v_max_f32_e32 v12, v12, v12
	v_max_f32_e32 v11, v11, v11
	v_max_f32_e32 v17, v17, v17
	v_max_f32_e32 v4, v4, v4
	v_min_f32_e32 v90, v11, v12
	v_min_f32_e32 v91, v4, v17
	v_min_f32_e32 v97, v90, v91
	v_max_f32_e32 v108, v6, v10
	v_max_f32_e32 v10, v90, v91
	global_load_dwordx4 v[90:93], v[64:65], off offset:3072
	v_and_b32_e32 v9, 0xffffff80, v9
	v_and_b32_e32 v13, 0xffffff80, v13
	v_and_b32_e32 v3, 0xffffff80, v3
	v_and_b32_e32 v14, 0xffffff80, v14
	v_or3_b32 v9, v72, v9, 11
	v_or3_b32 v13, v72, v13, 19
	v_or3_b32 v3, v72, v3, 1
	v_or3_b32 v14, v72, v14, 24
	v_max_f32_e32 v13, v13, v13
	v_max_f32_e32 v9, v9, v9
	v_max_f32_e32 v14, v14, v14
	v_max_f32_e32 v3, v3, v3
	v_min_f32_e32 v68, v9, v13
	v_min_f32_e32 v69, v3, v14
	v_max_f32_e32 v103, v3, v14
	v_max_f32_e32 v104, v9, v13
	v_max_f32_e32 v105, v4, v17
	v_max_f32_e32 v106, v11, v12
	v_max_f32_e32 v107, v5, v16
	v_max_f32_e32 v2, v2, v15
	v_max_f32_e32 v6, v7, v8
	v_min_f32_e32 v73, v68, v69
	v_min_f32_e32 v3, v103, v104
	v_min_f32_e32 v4, v105, v106
	v_min_f32_e32 v5, v107, v108
	v_min_f32_e32 v7, v2, v6
	v_max_f32_e32 v12, v68, v69
	v_min_f32_e32 v95, v73, v94
	v_min_f32_e32 v98, v96, v97
	v_min_f32_e32 v102, v100, v101
	v_min_f32_e32 v9, v3, v4
	v_min_f32_e32 v8, v5, v7
	v_min_f32_e32 v13, v10, v12
	v_max_f32_e32 v64, v73, v94
	v_max_f32_e32 v65, v96, v97
	v_min_f32_e32 v11, v102, v9
	v_min_f32_e32 v14, v8, v13
	v_max_f32_e32 v16, v95, v98
	v_min_f32_e32 v17, v64, v65
	v_min_f32_e32 v15, v11, v14
	v_min_f32_e32 v68, v16, v17
	v_max_f32_e32 v11, v11, v14
	v_max_f32_e32 v14, v16, v17
	v_min_f32_e32 v73, v15, v68
	v_max_f32_e32 v15, v15, v68
	v_min_f32_e32 v16, v11, v14
	v_min_f32_e32 v99, v95, v98
	v_min_f32_e32 v94, v15, v16
	v_max_f32_e32 v95, v15, v16
	v_max_f32_e32 v68, v8, v13
	v_max_f32_e32 v69, v100, v101
	v_max_f32_e32 v96, v3, v4
	v_max_f32_e32 v100, v102, v9
	v_max_f32_e32 v101, v5, v7
	v_max_f32_e32 v102, v10, v12
	v_max_f32_e32 v112, v11, v14
	v_max_f32_e32 v113, v2, v6
	v_mfma_f32_32x32x16_bf16 v[2:17], v[50:53], v[30:33], 0
	v_max_f32_e32 v50, v103, v104
	v_max_f32_e32 v52, v105, v106
	v_max_f32_e32 v53, v107, v108
	v_min_f32_e32 v51, v113, v50
	v_min_f32_e32 v103, v52, v53
	v_min_f32_e32 v97, v69, v96
	v_min_f32_e32 v109, v101, v102
	s_waitcnt vmcnt(3)
	v_mfma_f32_32x32x16_bf16 v[2:17], v[56:59], v[18:21], v[2:17]
	v_min_f32_e32 v104, v51, v103
	v_max_f32_e32 v64, v64, v65
	v_min_f32_e32 v98, v68, v97
	v_min_f32_e32 v110, v100, v109
	v_min_f32_e32 v56, v104, v64
	v_max_f32_e32 v50, v113, v50
	v_max_f32_e32 v52, v52, v53
	v_mfma_f32_32x32x16_bf16 v[2:17], v[74:77], v[38:41], v[2:17]
	v_min_f32_e32 v57, v112, v56
	v_max_f32_e32 v58, v98, v110
	v_max_f32_e32 v56, v112, v56
	v_max_f32_e32 v51, v51, v103
	v_min_f32_e32 v53, v50, v52
	v_max_f32_e32 v65, v101, v102
	v_max_f32_e32 v69, v69, v96
	v_mfma_f32_32x32x16_bf16 v[2:17], v[78:81], v[26:29], v[2:17]
	v_min_f32_e32 v59, v58, v56
	v_max_f32_e32 v56, v58, v56
	v_max_f32_e32 v58, v104, v64
	v_min_f32_e32 v64, v51, v53
	v_min_f32_e32 v74, v65, v69
	v_min_f32_e32 v75, v64, v74
	v_max_f32_e32 v68, v68, v97
	v_max_f32_e32 v77, v100, v109
	v_min_f32_e32 v76, v58, v75
	v_min_f32_e32 v78, v68, v77
	v_min_f32_e32 v79, v76, v78
	v_min_f32_e32 v96, v56, v79
	v_max_f32_e32 v102, v76, v78
	v_max_f32_e32 v104, v56, v79
	global_load_dwordx4 v[78:81], v[54:55], off offset:2048
	s_waitcnt vmcnt(3)
	v_mfma_f32_32x32x16_bf16 v[2:17], v[82:85], v[34:37], v[2:17]
	v_min_f32_e32 v111, v98, v110
	v_min_f32_e32 v105, v111, v57
	v_max_f32_e32 v57, v111, v57
	v_min_f32_e32 v98, v59, v57
	v_max_f32_e32 v97, v59, v57
	v_max_f32_e32 v57, v58, v75
	v_max_f32_e32 v58, v68, v77
	v_mfma_f32_32x32x16_bf16 v[2:17], v[60:63], v[22:25], v[2:17]
	v_min_f32_e32 v101, v57, v58
	v_max_f32_e32 v51, v51, v53
	v_max_f32_e32 v53, v65, v69
	global_load_dwordx4 v[82:85], v[54:55], off offset:3072
	v_min_f32_e32 v103, v101, v102
	v_min_f32_e32 v106, v95, v105
	v_min_f32_e32 v100, v96, v97
	s_waitcnt vmcnt(3)
	v_mfma_f32_32x32x16_bf16 v[2:17], v[86:89], v[46:49], v[2:17]
	v_max_f32_e32 v86, v57, v58
	v_max_f32_e32 v87, v64, v74
	v_min_f32_e32 v88, v51, v53
	v_min_f32_e32 v89, v87, v88
	v_min_f32_e32 v107, v103, v104
	v_min_f32_e32 v108, v86, v89
	s_waitcnt vmcnt(2)
; __device__ __forceinline__ int crow(int r, int hi) { return (r & 3) + 8 * (r >> 2) + 4 * hi; }
; __device__ __forceinline__ unsigned kmax(unsigned a, unsigned b) { return __float_as_uint(__builtin_fmaxf(__uint_as_float(a), __uint_as_float(b))); }
; __device__ __forceinline__ void merge_top16(unsigned (&Lst)[16], const unsigned (&S)[16]) {
; #pragma unroll
;     for (int i = 0; i < 16; ++i) Lst[i] = kmax(Lst[i], S[15 - i]);
;     bitonic_merge_desc<16>(Lst);
; }
; __device__ __forceinline__ void topk_p_lds(const bf16* __restrict__ skf, const char* qlds, int r32, int hi, unsigned (&Lst)[16]) {
;     ...
;         unsigned S[16];
; #pragma unroll
;         for (int r = 0; r < 16; ++r) S[r] = (__float_as_uint(acc[r]) & ~127u) | (unsigned)(32 * kb + crow(r, hi));
;         sort16_desc(S);
;         if (kb == 0) {
; #pragma unroll
;             for (int r = 0; r < 16; ++r) Lst[r] = S[r];
;         } else merge_top16(Lst, S);
	v_mfma_f32_32x32x16_bf16 v[2:17], v[90:93], v[42:45], v[2:17]
	s_nop 11
	v_and_b32_e32 v9, 0xffffff80, v9
	v_and_b32_e32 v13, 0xffffff80, v13
	v_and_b32_e32 v3, 0xffffff80, v3
	v_and_b32_e32 v14, 0xffffff80, v14
	v_and_b32_e32 v7, 0xffffff80, v7
	v_and_b32_e32 v8, 0xffffff80, v8
	v_and_b32_e32 v2, 0xffffff80, v2
	v_and_b32_e32 v15, 0xffffff80, v15
	v_and_b32_e32 v6, 0xffffff80, v6
	v_and_b32_e32 v10, 0xffffff80, v10
	v_and_b32_e32 v5, 0xffffff80, v5
	v_and_b32_e32 v16, 0xffffff80, v16
	v_and_b32_e32 v11, 0xffffff80, v11
	v_and_b32_e32 v12, 0xffffff80, v12
	v_and_b32_e32 v4, 0xffffff80, v4
	v_and_b32_e32 v17, 0xffffff80, v17
	v_or3_b32 v9, v72, v9, 43
	v_or3_b32 v13, v72, v13, 51
	v_or3_b32 v3, v72, v3, 33
	v_or3_b32 v14, v72, v14, 56
	v_or3_b32 v7, v72, v7, 41
	v_or3_b32 v8, v72, v8, 42
	v_or3_b32 v2, v72, v2, 32
	v_or3_b32 v15, v72, v15, 57
	v_or3_b32 v6, v72, v6, 40
	v_or3_b32 v10, v72, v10, 48
	v_or3_b32 v5, v72, v5, 35
	v_or3_b32 v16, v72, v16, 58
	v_or3_b32 v11, v72, v11, 49
	v_or3_b32 v12, v72, v12, 50
	v_or3_b32 v4, v72, v4, 34
	v_or3_b32 v17, v72, v17, 59
	v_max_f32_e32 v13, v13, v13
	v_max_f32_e32 v9, v9, v9
	v_max_f32_e32 v14, v14, v14
	v_max_f32_e32 v3, v3, v3
	v_max_f32_e32 v8, v8, v8
	v_max_f32_e32 v7, v7, v7
	v_max_f32_e32 v15, v15, v15
	v_max_f32_e32 v2, v2, v2
	v_max_f32_e32 v10, v10, v10
	v_max_f32_e32 v6, v6, v6
	v_max_f32_e32 v16, v16, v16
	v_max_f32_e32 v5, v5, v5
	v_max_f32_e32 v12, v12, v12
	v_max_f32_e32 v11, v11, v11
	v_max_f32_e32 v17, v17, v17
	v_max_f32_e32 v4, v4, v4
	v_min_f32_e32 v56, v9, v13
	v_min_f32_e32 v57, v3, v14
	v_min_f32_e32 v59, v7, v8
	v_min_f32_e32 v60, v2, v15
	v_min_f32_e32 v63, v6, v10
	v_min_f32_e32 v64, v5, v16
	v_min_f32_e32 v68, v11, v12
	v_min_f32_e32 v69, v4, v17
	v_max_f32_e32 v3, v3, v14
	v_max_f32_e32 v9, v9, v13
	v_max_f32_e32 v4, v4, v17
	v_max_f32_e32 v11, v11, v12
	v_max_f32_e32 v5, v5, v16
	v_max_f32_e32 v6, v6, v10
	v_max_f32_e32 v2, v2, v15
	v_max_f32_e32 v7, v7, v8
	v_min_f32_e32 v13, v3, v9
	v_min_f32_e32 v12, v4, v11
	v_min_f32_e32 v10, v5, v6
	v_min_f32_e32 v8, v2, v7
	v_max_f32_e32 v7, v2, v7
	v_max_f32_e32 v9, v3, v9
	v_max_f32_e32 v11, v4, v11
	v_max_f32_e32 v6, v5, v6
	global_load_dwordx4 v[2:5], v[54:55], off
	v_min_f32_e32 v58, v56, v57
	v_min_f32_e32 v61, v59, v60
	v_min_f32_e32 v65, v63, v64
	v_min_f32_e32 v74, v68, v69
	v_min_f32_e32 v62, v58, v61
	v_min_f32_e32 v75, v65, v74
	v_min_f32_e32 v90, v62, v75
	v_max_f32_e32 v62, v62, v75
	v_max_f32_e32 v58, v58, v61
	v_max_f32_e32 v61, v65, v74
	global_load_dwordx4 v[74:77], v[54:55], off offset:1024
	v_max_f32_e32 v59, v59, v60
	v_max_f32_e32 v60, v63, v64
	v_max_f32_e32 v16, v68, v69
	v_max_f32_e32 v56, v56, v57
	v_min_f32_e32 v63, v59, v60
	v_min_f32_e32 v14, v13, v12
	v_min_f32_e32 v15, v10, v8
	v_min_f32_e32 v57, v16, v56
	v_min_f32_e32 v17, v63, v14
	v_min_f32_e32 v64, v15, v57
	v_min_f32_e32 v65, v58, v61
	v_min_f32_e32 v68, v17, v64
	v_min_f32_e32 v69, v62, v65
	v_max_f32_e32 v17, v17, v64
	v_max_f32_e32 v62, v62, v65
	v_min_f32_e32 v91, v68, v69
	v_max_f32_e32 v68, v68, v69
	v_min_f32_e32 v64, v17, v62
	v_max_f32_e32 v15, v15, v57
	v_max_f32_e32 v57, v59, v60
	v_max_f32_e32 v12, v13, v12
	v_max_f32_e32 v14, v63, v14
	v_max_f32_e32 v8, v10, v8
	v_max_f32_e32 v10, v16, v56
	v_max_f32_e32 v17, v17, v62
	v_min_f32_e32 v62, v7, v9
	v_min_f32_e32 v63, v11, v6
	v_min_f32_e32 v92, v68, v64
	v_max_f32_e32 v93, v68, v64
	v_min_f32_e32 v13, v57, v12
	v_min_f32_e32 v16, v8, v10
	v_min_f32_e32 v64, v62, v63
	v_max_f32_e32 v58, v58, v61
	v_min_f32_e32 v59, v15, v13
	v_min_f32_e32 v56, v14, v16
	v_min_f32_e32 v61, v64, v58
	v_add_co_u32_e32 v68, vcc, s0, v66
	v_min_f32_e32 v60, v59, v56
	v_min_f32_e32 v65, v17, v61
	v_max_f32_e32 v56, v59, v56
	v_max_f32_e32 v17, v17, v61
	v_addc_co_u32_e32 v69, vcc, 0, v67, vcc
	v_min_f32_e32 v109, v60, v65
	v_min_f32_e32 v59, v56, v17
	v_max_f32_e32 v60, v60, v65
	v_max_f32_e32 v17, v56, v17
	v_max_f32_e32 v56, v64, v58
	v_max_f32_e32 v112, v62, v63
	global_load_dwordx4 v[62:65], v[68:69], off offset:-4096
	v_max_f32_e32 v9, v7, v9
	v_max_f32_e32 v11, v11, v6
	v_min_f32_e32 v113, v9, v11
	v_max_f32_e32 v8, v8, v10
	v_max_f32_e32 v10, v57, v12
	v_min_f32_e32 v58, v112, v113
	v_min_f32_e32 v12, v8, v10
	v_min_f32_e32 v6, v58, v12
	s_movk_i32 s0, 0x5000
	v_min_f32_e32 v111, v59, v60
	v_min_f32_e32 v61, v56, v6
	v_max_f32_e32 v7, v15, v13
	v_max_f32_e32 v13, v14, v16
	v_max_f32_e32 v114, v59, v60
	v_max_f32_e32 v59, v56, v6
	v_add_co_u32_e32 v6, vcc, s0, v66
	v_min_f32_e32 v14, v7, v13
	v_max_f32_e32 v13, v7, v13
	v_addc_co_u32_e32 v7, vcc, 0, v67, vcc
	v_max3_f32 v90, v50, v52, v90
	v_max3_f32 v91, v51, v53, v91
	global_load_dwordx4 v[50:53], v[6:7], off offset:3072
	global_load_dwordx4 v[54:57], v[6:7], off offset:1024
	v_min_f32_e32 v15, v61, v14
	v_min_f32_e32 v116, v59, v13
	v_max_f32_e32 v14, v61, v14
	v_max_f32_e32 v13, v59, v13
	v_max_f32_e32 v12, v58, v12
	global_load_dwordx4 v[58:61], v[6:7], off offset:2048
	v_max_f32_e32 v112, v112, v113
	v_max_f32_e32 v8, v8, v10
	v_min_f32_e32 v10, v112, v8
	v_min_f32_e32 v16, v17, v15
	v_min_f32_e32 v117, v116, v14
	v_max_f32_e32 v15, v17, v15
	v_min_f32_e32 v113, v12, v10
	v_min_f32_e32 v110, v93, v109
	v_min_f32_e32 v17, v117, v15
	v_min_f32_e32 v118, v13, v113
	v_min_f32_e32 v115, v16, v114
	v_max3_f32 v6, v87, v88, v92
	v_max3_f32 v7, v86, v89, v110
	v_max3_f32 v86, v108, v93, v109
	v_max3_f32 v87, v101, v102, v111
	v_max3_f32 v89, v107, v16, v114
	v_max3_f32 v16, v96, v97, v17
	v_max3_f32 v15, v100, v117, v15
	v_max3_f32 v14, v98, v116, v14
	v_max3_f32 v17, v95, v105, v118
	v_max3_f32 v13, v106, v13, v113
	v_max3_f32 v10, v94, v12, v10
	v_max3_f32 v73, v73, v112, v8
	v_max3_f32 v92, v99, v9, v11
	v_max_f32_e32 v93, v90, v16
	v_min_f32_e32 v90, v90, v16
	v_max_f32_e32 v94, v91, v15
	v_min_f32_e32 v91, v91, v15
	v_max_f32_e32 v95, v6, v14
	v_min_f32_e32 v96, v6, v14
	v_max_f32_e32 v97, v7, v17
	v_min_f32_e32 v98, v7, v17
	v_max_f32_e32 v99, v86, v13
	v_min_f32_e32 v86, v86, v13
	v_max_f32_e32 v100, v87, v10
	v_min_f32_e32 v87, v87, v10
	s_waitcnt vmcnt(5)
; __device__ __forceinline__ int crow(int r, int hi) { return (r & 3) + 8 * (r >> 2) + 4 * hi; }
; __device__ __forceinline__ unsigned kmax(unsigned a, unsigned b) { return __float_as_uint(__builtin_fmaxf(__uint_as_float(a), __uint_as_float(b))); }
; __device__ __forceinline__ void merge_top16(unsigned (&Lst)[16], const unsigned (&S)[16]) {
; #pragma unroll
;     for (int i = 0; i < 16; ++i) Lst[i] = kmax(Lst[i], S[15 - i]);
;     bitonic_merge_desc<16>(Lst);
; }
; __device__ __forceinline__ void topk_p_lds(const bf16* __restrict__ skf, const char* qlds, int r32, int hi, unsigned (&Lst)[16]) {
;     ...
; #pragma unroll
;         for (int ks = 0; ks < 8; ++ks) acc = __builtin_amdgcn_mfma_f32_32x32x16_bf16(a[ks], bq[ks], acc, 0, 0, 0);
;         unsigned S[16];
; #pragma unroll
;         for (int r = 0; r < 16; ++r) S[r] = (__float_as_uint(acc[r]) & ~127u) | (unsigned)(32 * kb + crow(r, hi));
;         sort16_desc(S);
;         if (kb == 0) {
; #pragma unroll
;             for (int r = 0; r < 16; ++r) Lst[r] = S[r];
;         } else merge_top16(Lst, S);
	v_mfma_f32_32x32x16_bf16 v[2:17], v[2:5], v[30:33], 0
	v_max3_f32 v88, v103, v104, v115
	v_max_f32_e32 v101, v88, v73
	v_min_f32_e32 v73, v88, v73
	v_max_f32_e32 v88, v89, v92
	v_min_f32_e32 v89, v89, v92
	s_movk_i32 s0, 0x7000
	v_max_f32_e32 v92, v93, v99
	s_waitcnt vmcnt(4)
	v_mfma_f32_32x32x16_bf16 v[2:17], v[74:77], v[18:21], v[2:17]
	v_max_f32_e32 v76, v97, v88
	v_min_f32_e32 v77, v97, v88
	v_max_f32_e32 v88, v90, v86
	v_min_f32_e32 v86, v90, v86
	v_max_f32_e32 v90, v91, v87
	v_min_f32_e32 v93, v93, v99
	v_max_f32_e32 v99, v94, v100
	v_mfma_f32_32x32x16_bf16 v[2:17], v[78:81], v[38:41], v[2:17]
	v_max_f32_e32 v80, v98, v89
	v_max_f32_e32 v104, v90, v80
	v_min_f32_e32 v105, v90, v80
	v_add_co_u32_e32 v90, vcc, s0, v66
	v_min_f32_e32 v78, v91, v87
	v_max_f32_e32 v79, v96, v73
	v_mfma_f32_32x32x16_bf16 v[2:17], v[82:85], v[26:29], v[2:17]
	v_min_f32_e32 v73, v96, v73
	v_addc_co_u32_e32 v91, vcc, 0, v67, vcc
	v_min_f32_e32 v81, v98, v89
	v_max_f32_e32 v102, v88, v79
	v_min_f32_e32 v103, v88, v79
	v_max_f32_e32 v106, v86, v73
	v_min_f32_e32 v73, v86, v73
	global_load_dwordx4 v[86:89], v[90:91], off offset:2048
	s_waitcnt vmcnt(4)
	v_mfma_f32_32x32x16_bf16 v[2:17], v[62:65], v[34:37], v[2:17]
	v_min_f32_e32 v94, v94, v100
	v_max_f32_e32 v74, v95, v101
	v_min_f32_e32 v75, v95, v101
	v_max_f32_e32 v95, v92, v74
	v_min_f32_e32 v96, v92, v74
	v_max_f32_e32 v97, v99, v76
	v_min_f32_e32 v98, v99, v76
	s_waitcnt vmcnt(2)
	v_mfma_f32_32x32x16_bf16 v[2:17], v[54:57], v[22:25], v[2:17]
	v_max_f32_e32 v99, v93, v75
	v_min_f32_e32 v100, v93, v75
	v_max_f32_e32 v101, v94, v77
	v_min_f32_e32 v94, v94, v77
	global_load_dwordx4 v[74:77], v[68:69], off
	v_max_f32_e32 v107, v78, v81
	v_min_f32_e32 v108, v78, v81
	s_waitcnt vmcnt(2)
	v_mfma_f32_32x32x16_bf16 v[2:17], v[58:61], v[46:49], v[2:17]
	global_load_dwordx4 v[54:57], v[90:91], off offset:1024
	s_mov_b32 s0, 0x8000
	v_min_f32_e32 v109, v95, v97
	v_min_f32_e32 v113, v102, v104
	v_min_f32_e32 v112, v100, v94
	v_min_f32_e32 v114, v103, v105
	v_min_f32_e32 v115, v106, v107
	v_mfma_f32_32x32x16_bf16 v[2:17], v[50:53], v[42:45], v[2:17]
	v_min_f32_e32 v116, v73, v108
	v_min_f32_e32 v110, v96, v98
	v_min_f32_e32 v111, v99, v101
	s_nop 8
	v_and_b32_e32 v9, 0xffffff80, v9
	v_and_b32_e32 v13, 0xffffff80, v13
	v_and_b32_e32 v3, 0xffffff80, v3
	v_and_b32_e32 v14, 0xffffff80, v14
	v_and_b32_e32 v7, 0xffffff80, v7
	v_and_b32_e32 v8, 0xffffff80, v8
	v_and_b32_e32 v2, 0xffffff80, v2
	v_and_b32_e32 v15, 0xffffff80, v15
	v_and_b32_e32 v6, 0xffffff80, v6
	v_and_b32_e32 v10, 0xffffff80, v10
	v_and_b32_e32 v5, 0xffffff80, v5
	v_and_b32_e32 v16, 0xffffff80, v16
	v_and_b32_e32 v11, 0xffffff80, v11
	v_and_b32_e32 v12, 0xffffff80, v12
	v_and_b32_e32 v4, 0xffffff80, v4
	v_and_b32_e32 v17, 0xffffff80, v17
	v_or3_b32 v9, v72, v9, s16
	v_or3_b32 v13, v72, v13, s17
	v_or3_b32 v3, v72, v3, s3
	v_or3_b32 v14, v72, v14, s23
	v_or3_b32 v7, v72, v7, s33
	v_or3_b32 v8, v72, v8, s68
	v_or3_b32 v2, v72, v2, 64
	v_or3_b32 v15, v72, v15, s69
	v_or3_b32 v6, v72, v6, s70
	v_or3_b32 v10, v72, v10, s71
	v_or3_b32 v5, v72, v5, s76
	v_or3_b32 v16, v72, v16, s77
	v_or3_b32 v11, v72, v11, s78
	v_or3_b32 v12, v72, v12, s79
	v_or3_b32 v4, v72, v4, s80
	v_or3_b32 v17, v72, v17, s81
	v_max_f32_e32 v13, v13, v13
	v_max_f32_e32 v9, v9, v9
	v_max_f32_e32 v14, v14, v14
	v_max_f32_e32 v3, v3, v3
	v_max_f32_e32 v8, v8, v8
	v_max_f32_e32 v7, v7, v7
	v_max_f32_e32 v15, v15, v15
	v_max_f32_e32 v2, v2, v2
	v_max_f32_e32 v10, v10, v10
	v_max_f32_e32 v6, v6, v6
	v_max_f32_e32 v16, v16, v16
	v_max_f32_e32 v5, v5, v5
	v_max_f32_e32 v12, v12, v12
	v_max_f32_e32 v11, v11, v11
	v_max_f32_e32 v17, v17, v17
	v_max_f32_e32 v4, v4, v4
	v_min_f32_e32 v50, v9, v13
	v_min_f32_e32 v51, v3, v14
	v_min_f32_e32 v53, v7, v8
	v_min_f32_e32 v58, v2, v15
	v_min_f32_e32 v61, v6, v10
	v_min_f32_e32 v62, v5, v16
	v_min_f32_e32 v64, v11, v12
	v_min_f32_e32 v65, v4, v17
	v_max_f32_e32 v3, v3, v14
	v_max_f32_e32 v9, v9, v13
	v_max_f32_e32 v4, v4, v17
	v_max_f32_e32 v11, v11, v12
	v_max_f32_e32 v5, v5, v16
	v_max_f32_e32 v6, v6, v10
	v_max_f32_e32 v2, v2, v15
	v_max_f32_e32 v7, v7, v8
	v_min_f32_e32 v52, v50, v51
	v_min_f32_e32 v59, v53, v58
	v_min_f32_e32 v63, v61, v62
	v_min_f32_e32 v78, v64, v65
	v_max_f32_e32 v53, v53, v58
	v_max_f32_e32 v58, v61, v62
	v_min_f32_e32 v13, v3, v9
	v_min_f32_e32 v12, v4, v11
	v_min_f32_e32 v10, v5, v6
	v_min_f32_e32 v8, v2, v7
	v_max_f32_e32 v16, v64, v65
	v_max_f32_e32 v50, v50, v51
	v_min_f32_e32 v60, v52, v59
	v_min_f32_e32 v79, v63, v78
	v_min_f32_e32 v61, v53, v58
	v_min_f32_e32 v14, v13, v12
	v_min_f32_e32 v15, v10, v8
	v_min_f32_e32 v51, v16, v50
	v_max_f32_e32 v52, v52, v59
	v_max_f32_e32 v59, v63, v78
	v_min_f32_e32 v117, v60, v79
	v_min_f32_e32 v17, v61, v14
	v_min_f32_e32 v62, v15, v51
	v_max_f32_e32 v60, v60, v79
	v_min_f32_e32 v63, v52, v59
	v_min_f32_e32 v64, v17, v62
	v_min_f32_e32 v65, v60, v63
	v_max_f32_e32 v17, v17, v62
	v_max_f32_e32 v60, v60, v63
	v_min_f32_e32 v62, v17, v60
	v_max_f32_e32 v15, v15, v51
	v_max_f32_e32 v51, v53, v58
	v_max_f32_e32 v14, v61, v14
	v_max_f32_e32 v17, v17, v60
	v_max_f32_e32 v4, v4, v11
	v_max_f32_e32 v11, v52, v59
	global_load_dwordx4 v[58:61], v[68:69], off offset:1024
	v_max_f32_e32 v2, v2, v7
	v_max_f32_e32 v3, v3, v9
	v_max_f32_e32 v5, v5, v6
	v_max_f32_e32 v12, v13, v12
	v_max_f32_e32 v8, v10, v8
	v_max_f32_e32 v10, v16, v50
	v_min_f32_e32 v7, v2, v3
	v_min_f32_e32 v6, v4, v5
	v_min_f32_e32 v13, v51, v12
	v_min_f32_e32 v16, v8, v10
	v_min_f32_e32 v9, v7, v6
	v_min_f32_e32 v118, v64, v65
	v_max_f32_e32 v64, v64, v65
	v_min_f32_e32 v53, v15, v13
	v_min_f32_e32 v50, v14, v16
	v_min_f32_e32 v52, v9, v11
; __device__ __forceinline__ unsigned kmax(unsigned a, unsigned b) { return __float_as_uint(__builtin_fmaxf(__uint_as_float(a), __uint_as_float(b))); }
; __device__ __forceinline__ void merge_top16(unsigned (&Lst)[16], const unsigned (&S)[16]) {
; #pragma unroll
;     for (int i = 0; i < 16; ++i) Lst[i] = kmax(Lst[i], S[15 - i]);
;     bitonic_merge_desc<16>(Lst);
; }
; __device__ __forceinline__ void topk_p_lds(const bf16* __restrict__ skf, const char* qlds, int r32, int hi, unsigned (&Lst)[16]) {
;     ...
; #pragma unroll
;         for (int ks = 0; ks < 8; ++ks) acc = __builtin_amdgcn_mfma_f32_32x32x16_bf16(a[ks], bq[ks], acc, 0, 0, 0);
	v_min_f32_e32 v119, v64, v62
	v_max_f32_e32 v62, v64, v62
	v_min_f32_e32 v63, v53, v50
	v_min_f32_e32 v64, v17, v52
	v_min_f32_e32 v65, v63, v64
	v_min_f32_e32 v120, v62, v65
	v_max_f32_e32 v121, v62, v65
	v_max_f32_e32 v50, v53, v50
	v_max_f32_e32 v53, v63, v64
	global_load_dwordx4 v[62:65], v[68:69], off offset:2048
	global_load_dwordx4 v[78:81], v[68:69], off offset:3072
	v_max_f32_e32 v17, v17, v52
	v_min_f32_e32 v52, v50, v17
	v_max_f32_e32 v17, v50, v17
	v_add_co_u32_e32 v50, vcc, s0, v66
	v_max_f32_e32 v6, v7, v6
	v_max_f32_e32 v7, v8, v10
	v_max_f32_e32 v8, v51, v12
	v_addc_co_u32_e32 v51, vcc, 0, v67, vcc
	global_load_dwordx4 v[82:85], v[50:51], off offset:-4096
	v_max_f32_e32 v2, v2, v3
	global_load_dwordx4 v[90:93], v[90:91], off offset:3072
	v_max_f32_e32 v3, v4, v5
	v_min_f32_e32 v4, v2, v3
	v_min_f32_e32 v5, v6, v4
	v_min_f32_e32 v10, v7, v8
	v_max_f32_e32 v9, v9, v11
	v_min_f32_e32 v11, v5, v10
	v_max_f32_e32 v13, v15, v13
	v_max_f32_e32 v14, v14, v16
	v_min_f32_e32 v12, v9, v11
	v_min_f32_e32 v15, v13, v14
	v_max_f32_e32 v9, v9, v11
	v_max_f32_e32 v11, v13, v14
	v_min_f32_e32 v16, v12, v15
	v_min_f32_e32 v13, v9, v11
	v_max_f32_e32 v12, v12, v15
	v_max_f32_e32 v4, v6, v4
	v_max_f32_e32 v6, v7, v8
	v_min_f32_e32 v14, v13, v12
	v_max_f32_e32 v15, v17, v16
	v_max_f32_e32 v5, v5, v10
	v_min_f32_e32 v7, v4, v6
	v_min_f32_e32 v122, v52, v53
	v_min_f32_e32 v68, v17, v16
	v_max_f32_e32 v52, v52, v53
	v_min_f32_e32 v16, v14, v15
	v_max_f32_e32 v12, v13, v12
	v_max_f32_e32 v9, v9, v11
	v_min_f32_e32 v8, v5, v7
	v_min_f32_e32 v53, v68, v52
	v_min_f32_e32 v10, v9, v8
	v_max_f32_e32 v8, v9, v8
	v_max_f32_e32 v4, v4, v6
	v_max3_f32 v6, v95, v97, v117
	v_max_f32_e32 v9, v109, v118
	v_max3_f32 v11, v96, v98, v119
	v_max3_f32 v13, v102, v104, v16
	v_max3_f32 v14, v113, v14, v15
	v_max3_f32 v12, v103, v105, v12
	v_max3_f32 v95, v99, v101, v121
	v_max3_f32 v53, v100, v94, v53
	v_max3_f32 v52, v112, v68, v52
	v_max_f32_e32 v68, v114, v10
	v_max3_f32 v94, v106, v107, v8
	v_max3_f32 v97, v115, v5, v7
	v_max3_f32 v73, v73, v108, v4
	v_max3_f32 v98, v116, v2, v3
	v_max_f32_e32 v99, v6, v13
	v_min_f32_e32 v100, v6, v13
	v_max_f32_e32 v101, v9, v14
	v_min_f32_e32 v102, v9, v14
	v_max_f32_e32 v103, v11, v12
	v_min_f32_e32 v104, v11, v12
	s_waitcnt vmcnt(6)
	v_mfma_f32_32x32x16_bf16 v[2:17], v[74:77], v[30:33], 0
	v_max_f32_e32 v69, v110, v120
	v_max_f32_e32 v105, v69, v68
	v_min_f32_e32 v30, v69, v68
	v_max_f32_e32 v31, v95, v94
	v_max_f32_e32 v69, v53, v73
	v_min_f32_e32 v53, v53, v73
	v_max_f32_e32 v96, v111, v122
	s_waitcnt vmcnt(4)
	v_mfma_f32_32x32x16_bf16 v[2:17], v[58:61], v[18:21], v[2:17]
	v_max_f32_e32 v18, v52, v98
	v_min_f32_e32 v19, v52, v98
	v_max_f32_e32 v20, v99, v31
	v_max_f32_e32 v52, v103, v69
	v_min_f32_e32 v32, v95, v94
	v_min_f32_e32 v68, v96, v97
	v_min_f32_e32 v58, v102, v68
	s_waitcnt vmcnt(3)
	v_mfma_f32_32x32x16_bf16 v[2:17], v[62:65], v[38:41], v[2:17]
	v_max_f32_e32 v40, v100, v32
	v_min_f32_e32 v32, v100, v32
	v_max_f32_e32 v33, v96, v97
	v_min_f32_e32 v21, v99, v31
	v_max_f32_e32 v31, v101, v33
	v_min_f32_e32 v33, v101, v33
	v_min_f32_e32 v38, v103, v69
	s_waitcnt vmcnt(2)
	v_mfma_f32_32x32x16_bf16 v[2:17], v[78:81], v[26:29], v[2:17]
	v_max_f32_e32 v29, v20, v52
	v_min_f32_e32 v20, v20, v52
	v_max_f32_e32 v26, v104, v53
	v_min_f32_e32 v27, v104, v53
	v_max_f32_e32 v28, v30, v19
	v_min_f32_e32 v19, v30, v19
	v_max_f32_e32 v39, v105, v18
	s_waitcnt vmcnt(1)
	v_mfma_f32_32x32x16_bf16 v[2:17], v[82:85], v[34:37], v[2:17]
	v_min_f32_e32 v18, v105, v18
	v_max_f32_e32 v41, v102, v68
	v_max_f32_e32 v30, v31, v39
	v_min_f32_e32 v31, v31, v39
	v_max_f32_e32 v34, v21, v38
	v_min_f32_e32 v21, v21, v38
	v_max_f32_e32 v35, v33, v18
	v_mfma_f32_32x32x16_bf16 v[2:17], v[54:57], v[22:25], v[2:17]
	v_max_f32_e32 v24, v32, v27
	v_min_f32_e32 v25, v32, v27
	v_max_f32_e32 v27, v58, v19
	v_min_f32_e32 v19, v58, v19
	v_min_f32_e32 v18, v33, v18
	v_max_f32_e32 v33, v40, v26
	v_min_f32_e32 v26, v40, v26
	v_mfma_f32_32x32x16_bf16 v[2:17], v[86:89], v[46:49], v[2:17]
	v_max_f32_e32 v22, v41, v28
	v_min_f32_e32 v23, v41, v28
	v_min_f32_e32 v28, v29, v30
	v_min_f32_e32 v32, v20, v31
	v_min_f32_e32 v36, v34, v35
	v_min_f32_e32 v37, v21, v18
	v_min_f32_e32 v38, v33, v22
	s_waitcnt vmcnt(0)
; __device__ __forceinline__ int crow(int r, int hi) { return (r & 3) + 8 * (r >> 2) + 4 * hi; }
; __device__ __forceinline__ unsigned kmax(unsigned a, unsigned b) { return __float_as_uint(__builtin_fmaxf(__uint_as_float(a), __uint_as_float(b))); }
; #define PEER_CE(i, j) do { const unsigned mx_ = kmax(a[i], a[j]), mn_ = kmin(a[i], a[j]); a[i] = mx_; a[j] = mn_; } while (0)
; __device__ __forceinline__ void sort16_desc(unsigned (&a)[16]) {
;     ...
;     PEER_CE(0, 13); PEER_CE(1, 12); PEER_CE(2, 15); PEER_CE(3, 14); PEER_CE(4, 8); PEER_CE(5, 6); PEER_CE(7, 11); PEER_CE(9, 10);
;     PEER_CE(0, 5); PEER_CE(1, 7); PEER_CE(2, 9); PEER_CE(3, 4); PEER_CE(6, 13); PEER_CE(8, 14); PEER_CE(10, 15); PEER_CE(11, 12);
;     PEER_CE(0, 1); PEER_CE(2, 3); PEER_CE(4, 5); PEER_CE(6, 8); PEER_CE(7, 9); PEER_CE(10, 11); PEER_CE(12, 13); PEER_CE(14, 15);
;     PEER_CE(0, 2); PEER_CE(1, 3); PEER_CE(4, 10); PEER_CE(5, 11); PEER_CE(6, 7); PEER_CE(8, 9); PEER_CE(12, 14); PEER_CE(13, 15);
;     PEER_CE(1, 2); PEER_CE(3, 12); PEER_CE(4, 6); PEER_CE(5, 7); PEER_CE(8, 10); PEER_CE(9, 11); PEER_CE(13, 14);
;     PEER_CE(1, 4); PEER_CE(2, 6); PEER_CE(5, 8); PEER_CE(7, 10); PEER_CE(9, 13); PEER_CE(11, 14);
;     PEER_CE(2, 4); PEER_CE(3, 6); PEER_CE(9, 12); PEER_CE(11, 13);
;     PEER_CE(3, 5); PEER_CE(6, 8); PEER_CE(7, 9); PEER_CE(10, 12);
;     PEER_CE(3, 4); PEER_CE(5, 6); PEER_CE(7, 8); PEER_CE(9, 10); PEER_CE(11, 12);
;     PEER_CE(6, 7); PEER_CE(8, 9);
;     ...
; }
; __device__ __forceinline__ void merge_top16(unsigned (&Lst)[16], const unsigned (&S)[16]) {
; #pragma unroll
;     for (int i = 0; i < 16; ++i) Lst[i] = kmax(Lst[i], S[15 - i]);
;     bitonic_merge_desc<16>(Lst);
; }
; __device__ __forceinline__ void topk_p_lds(const bf16* __restrict__ skf, const char* qlds, int r32, int hi, unsigned (&Lst)[16]) {
;     ...
;         unsigned S[16];
; #pragma unroll
;         for (int r = 0; r < 16; ++r) S[r] = (__float_as_uint(acc[r]) & ~127u) | (unsigned)(32 * kb + crow(r, hi));
;         sort16_desc(S);
;         if (kb == 0) {
; #pragma unroll
;             for (int r = 0; r < 16; ++r) Lst[r] = S[r];
;         } else merge_top16(Lst, S);
	v_mfma_f32_32x32x16_bf16 v[2:17], v[90:93], v[42:45], v[2:17]
	v_min_f32_e32 v39, v26, v23
	v_min_f32_e32 v40, v24, v27
	v_min_f32_e32 v41, v25, v19
	v_cmp_gt_u32_e32 vcc, 32, v70
	s_mov_b64 s[0:1], 0x8000
	s_nop 6
	v_and_b32_e32 v5, 0xffffff80, v5
	v_and_b32_e32 v16, 0xffffff80, v16
	v_and_b32_e32 v6, 0xffffff80, v6
	v_and_b32_e32 v10, 0xffffff80, v10
	v_and_b32_e32 v2, 0xffffff80, v2
	v_and_b32_e32 v15, 0xffffff80, v15
	v_and_b32_e32 v7, 0xffffff80, v7
	v_and_b32_e32 v8, 0xffffff80, v8
	v_and_b32_e32 v11, 0xffffff80, v11
	v_and_b32_e32 v12, 0xffffff80, v12
	v_and_b32_e32 v4, 0xffffff80, v4
	v_and_b32_e32 v17, 0xffffff80, v17
	v_and_b32_e32 v9, 0xffffff80, v9
	v_and_b32_e32 v13, 0xffffff80, v13
	v_and_b32_e32 v3, 0xffffff80, v3
	v_and_b32_e32 v14, 0xffffff80, v14
	v_or3_b32 v5, v72, v5, s82
	v_or3_b32 v16, v72, v16, s83
	v_or3_b32 v6, v72, v6, s84
	v_or3_b32 v10, v72, v10, s85
	v_or3_b32 v2, v72, v2, s86
	v_or3_b32 v15, v72, v15, s87
	v_or3_b32 v7, v72, v7, s88
	v_or3_b32 v8, v72, v8, s89
	v_or3_b32 v11, v72, v11, s90
	v_or3_b32 v12, v72, v12, s91
	v_or3_b32 v4, v72, v4, s92
	v_or3_b32 v17, v72, v17, s93
	v_or3_b32 v9, v72, v9, s94
	v_or3_b32 v13, v72, v13, s95
	v_or3_b32 v3, v72, v3, s96
	v_or3_b32 v14, v72, v14, s97
	v_max_f32_e32 v16, v16, v16
	v_max_f32_e32 v5, v5, v5
	v_max_f32_e32 v10, v10, v10
	v_max_f32_e32 v6, v6, v6
	v_max_f32_e32 v15, v15, v15
	v_max_f32_e32 v2, v2, v2
	v_max_f32_e32 v8, v8, v8
	v_max_f32_e32 v7, v7, v7
	v_max_f32_e32 v12, v12, v12
	v_max_f32_e32 v11, v11, v11
	v_max_f32_e32 v17, v17, v17
	v_max_f32_e32 v4, v4, v4
	v_max_f32_e32 v13, v13, v13
	v_max_f32_e32 v9, v9, v9
	v_max_f32_e32 v14, v14, v14
	v_max_f32_e32 v3, v3, v3
	v_max_f32_e32 v42, v5, v16
	v_max_f32_e32 v43, v6, v10
	v_max_f32_e32 v45, v2, v15
	v_max_f32_e32 v46, v7, v8
	v_min_f32_e32 v49, v11, v12
	v_min_f32_e32 v52, v4, v17
	v_min_f32_e32 v54, v9, v13
	v_min_f32_e32 v55, v3, v14
	v_min_f32_e32 v7, v7, v8
	v_min_f32_e32 v2, v2, v15
	v_min_f32_e32 v6, v6, v10
	v_min_f32_e32 v5, v5, v16
	v_max_f32_e32 v3, v3, v14
	v_max_f32_e32 v9, v9, v13
	v_max_f32_e32 v4, v4, v17
	v_max_f32_e32 v11, v11, v12
	v_min_f32_e32 v44, v42, v43
	v_min_f32_e32 v47, v45, v46
	v_max_f32_e32 v53, v49, v52
	v_max_f32_e32 v56, v54, v55
	v_max_f32_e32 v8, v7, v2
	v_max_f32_e32 v10, v6, v5
	v_min_f32_e32 v13, v3, v9
	v_min_f32_e32 v12, v4, v11
	v_min_f32_e32 v54, v54, v55
	v_min_f32_e32 v2, v7, v2
	v_min_f32_e32 v5, v6, v5
	v_min_f32_e32 v6, v49, v52
	v_max_f32_e32 v45, v45, v46
	v_max_f32_e32 v3, v3, v9
	v_max_f32_e32 v4, v4, v11
	v_max_f32_e32 v11, v42, v43
	v_min_f32_e32 v48, v44, v47
	v_min_f32_e32 v57, v53, v56
	v_max_f32_e32 v15, v8, v10
	v_max_f32_e32 v14, v13, v12
	v_min_f32_e32 v8, v8, v10
	v_min_f32_e32 v10, v13, v12
	v_max_f32_e32 v13, v44, v47
	v_max_f32_e32 v44, v53, v56
	v_min_f32_e32 v7, v54, v2
	v_min_f32_e32 v49, v5, v6
	v_max_f32_e32 v2, v54, v2
	v_max_f32_e32 v5, v5, v6
	v_min_f32_e32 v9, v45, v3
	v_min_f32_e32 v42, v4, v11
	v_max_f32_e32 v3, v45, v3
	v_max_f32_e32 v4, v4, v11
	v_min_f32_e32 v16, v15, v14
	v_max_f32_e32 v12, v8, v10
	v_min_f32_e32 v47, v13, v44
	v_min_f32_e32 v8, v8, v10
	v_min_f32_e32 v10, v48, v57
	v_max_f32_e32 v52, v7, v49
	v_min_f32_e32 v6, v2, v5
	v_min_f32_e32 v43, v9, v42
	v_max_f32_e32 v9, v9, v42
	v_min_f32_e32 v11, v3, v4
	v_max_f32_e32 v13, v13, v44
	v_max_f32_e32 v14, v15, v14
	v_max_f32_e32 v58, v48, v57
	v_max_f32_e32 v48, v8, v10
	v_max_f32_e32 v54, v52, v6
	v_max_f32_e32 v2, v2, v5
	v_min_f32_e32 v42, v9, v11
	v_min_f32_e32 v15, v13, v14
	v_min_f32_e32 v17, v58, v16
	v_min_f32_e32 v53, v12, v47
	v_max_f32_e32 v55, v48, v54
	v_min_f32_e32 v5, v43, v2
	v_max_f32_e32 v2, v43, v2
	v_min_f32_e32 v43, v42, v15
	v_max_f32_e32 v16, v58, v16
	v_max_f32_e32 v12, v12, v47
	v_max_f32_e32 v56, v17, v53
	v_max_f32_e32 v46, v55, v5
	v_min_f32_e32 v44, v2, v43
	v_min_f32_e32 v45, v16, v12
	v_min_f32_e32 v17, v17, v53
	v_min_f32_e32 v5, v55, v5
	v_max_f32_e32 v2, v2, v43
	v_max_f32_e32 v12, v16, v12
	v_min_f32_e32 v8, v8, v10
	v_min_f32_e32 v6, v52, v6
	v_max_f32_e32 v9, v9, v11
	v_max_f32_e32 v11, v13, v14
	v_max_f32_e32 v57, v56, v46
	v_min_f32_e32 v47, v44, v45
	v_min_f32_e32 v46, v56, v46
	v_max_f32_e32 v53, v17, v5
	v_min_f32_e32 v16, v2, v12
	v_max_f32_e32 v43, v44, v45
	v_max_f32_e32 v10, v8, v6
	v_min_f32_e32 v48, v48, v54
	v_max_f32_e32 v2, v2, v12
	v_max_f32_e32 v12, v42, v15
	v_min_f32_e32 v13, v9, v11
	v_min_f32_e32 v58, v57, v47
	v_max_f32_e32 v55, v46, v53
	v_min_f32_e32 v44, v16, v43
	v_max_f32_e32 v45, v57, v47
	v_max_f32_e32 v52, v10, v48
	v_min_f32_e32 v5, v17, v5
	v_min_f32_e32 v14, v12, v13
	v_min_f32_e32 v56, v58, v55
	v_min_f32_e32 v47, v44, v45
	v_min_f32_e32 v17, v52, v5
	v_max_f32_e32 v5, v52, v5
	v_min_f32_e32 v46, v46, v53
	v_max_f32_e32 v16, v16, v43
	v_min_f32_e32 v15, v2, v14
	v_max_f32_e32 v2, v2, v14
	v_min_f32_e32 v10, v10, v48
	v_min_f32_e32 v6, v8, v6
	v_max_f32_e32 v8, v9, v11
	v_min_f32_e32 v7, v7, v49
	v_max3_f32 v7, v29, v30, v7
	v_max_f32_e32 v6, v28, v6
	v_max3_f32 v9, v20, v31, v10
	v_max_f32_e32 v10, v32, v17
	v_max3_f32 v5, v34, v35, v5
	v_max_f32_e32 v11, v36, v46
	v_max3_f32 v14, v21, v18, v56
	v_max3_f32 v17, v37, v58, v55
	v_max3_f32 v18, v33, v22, v47
	v_max3_f32 v20, v38, v44, v45
	v_max3_f32 v16, v26, v23, v16
	v_max_f32_e32 v15, v39, v15
	v_max3_f32 v2, v24, v27, v2
	v_max3_f32 v12, v40, v12, v13
	v_max3_f32 v8, v25, v19, v8
	v_max3_f32 v3, v41, v3, v4
	v_max_f32_e32 v4, v7, v18
	v_min_f32_e32 v7, v7, v18
	v_max_f32_e32 v13, v6, v20
	v_max_f32_e32 v18, v9, v16
	v_min_f32_e32 v9, v9, v16
	v_max_f32_e32 v16, v10, v15
	v_min_f32_e32 v10, v10, v15
	v_max_f32_e32 v15, v5, v2
	v_min_f32_e32 v2, v5, v2
; __device__ __forceinline__ void topk_p_lds(const bf16* __restrict__ skf, const char* qlds, int r32, int hi, unsigned (&Lst)[16]) {
;     ...
;     for (int ks = 0; ks < 8; ++ks) bq[ks] = *reinterpret_cast<const bf16x8*>(qlds + ((2 * ks + hi) * 32 + r32) * 16);
; #pragma unroll
;     for (int kb = 0; kb < 4; ++kb) {
;         bf16x8 a[8];
; #pragma unroll
;         for (int ks = 0; ks < 8; ++ks) a[ks] = *reinterpret_cast<const bf16x8*>(skf + (size_t)((((kb * 8 + ks) * 2 + hi) * 32 + r32) * 8));
;         f32x16 acc = {};
; #pragma unroll
;         for (int ks = 0; ks < 8; ++ks) acc = __builtin_amdgcn_mfma_f32_32x32x16_bf16(a[ks], bq[ks], acc, 0, 0, 0);
;     ...
;     unsigned Y[16];
; #pragma unroll
;     for (int s = 0; s < 16; ++s) { auto rr = __builtin_amdgcn_permlane32_swap(Lst[s], Lst[s], false, false); Y[s] = hi ? rr[0] : rr[1]; }
;     merge_top16(Lst, Y);
; __device__ __forceinline__ void select_wave_lds(const bf16* __restrict__ skf_h, char* qtile, int h, int* __restrict__ pidx, float* __restrict__ pgate, int wid, int lane) {
;     ...
;     topk_p_lds(skf_h + 4 * 8 * 2 * 32 * 8, qtile + (wid * 2 + 1) * 8192, r32, hi, T1);
	v_max_f32_e32 v5, v11, v12
	v_min_f32_e32 v11, v11, v12
	v_max_f32_e32 v12, v14, v8
	v_min_f32_e32 v8, v14, v8
	v_max_f32_e32 v14, v17, v3
	v_min_f32_e32 v6, v6, v20
	v_min_f32_e32 v3, v17, v3
	v_max_f32_e32 v17, v4, v15
	v_min_f32_e32 v4, v4, v15
	v_max_f32_e32 v15, v13, v5
	v_min_f32_e32 v5, v13, v5
	v_max_f32_e32 v13, v18, v12
	v_min_f32_e32 v12, v18, v12
	v_max_f32_e32 v18, v16, v14
	v_min_f32_e32 v14, v16, v14
	v_max_f32_e32 v16, v7, v2
	v_min_f32_e32 v2, v7, v2
	v_max_f32_e32 v7, v6, v11
	v_min_f32_e32 v6, v6, v11
	v_max_f32_e32 v11, v9, v8
	v_min_f32_e32 v8, v9, v8
	v_max_f32_e32 v9, v10, v3
	v_min_f32_e32 v3, v10, v3
	v_max_f32_e32 v10, v17, v13
	v_min_f32_e32 v13, v17, v13
	v_max_f32_e32 v17, v15, v18
	v_min_f32_e32 v15, v15, v18
	v_max_f32_e32 v18, v4, v12
	v_min_f32_e32 v4, v4, v12
	v_max_f32_e32 v12, v5, v14
	v_min_f32_e32 v5, v5, v14
	v_max_f32_e32 v14, v16, v11
	v_min_f32_e32 v11, v16, v11
	v_max_f32_e32 v16, v7, v9
	v_min_f32_e32 v7, v7, v9
	v_max_f32_e32 v9, v2, v8
	v_min_f32_e32 v2, v2, v8
	v_max_f32_e32 v8, v6, v3
	v_min_f32_e32 v3, v6, v3
	v_max_f32_e32 v26, v10, v17
	v_max_f32_e32 v33, v9, v8
	v_min_f32_e32 v8, v9, v8
	v_max_f32_e32 v9, v2, v3
	v_min_f32_e32 v34, v2, v3
	v_mov_b32_e32 v2, v26
	v_mov_b32_e32 v3, v26
	v_min_f32_e32 v10, v10, v17
	s_nop 0
	v_permlane32_swap_b32_e32 v2, v3
	v_cndmask_b32_e32 v35, v2, v3, vcc
	v_mov_b32_e32 v2, v10
	v_mov_b32_e32 v3, v10
	v_max_f32_e32 v17, v13, v15
	s_nop 0
	v_permlane32_swap_b32_e32 v2, v3
	v_cndmask_b32_e32 v36, v2, v3, vcc
	v_mov_b32_e32 v2, v17
	v_mov_b32_e32 v3, v17
	v_min_f32_e32 v13, v13, v15
	s_nop 0
	v_permlane32_swap_b32_e32 v2, v3
	v_cndmask_b32_e32 v37, v2, v3, vcc
	v_mov_b32_e32 v2, v13
	v_mov_b32_e32 v3, v13
	v_max_f32_e32 v15, v18, v12
	s_nop 0
	v_permlane32_swap_b32_e32 v2, v3
	v_cndmask_b32_e32 v38, v2, v3, vcc
	v_mov_b32_e32 v2, v15
	v_mov_b32_e32 v3, v15
	v_min_f32_e32 v12, v18, v12
	s_nop 0
	v_permlane32_swap_b32_e32 v2, v3
	v_cndmask_b32_e32 v39, v2, v3, vcc
	v_mov_b32_e32 v2, v12
	v_mov_b32_e32 v3, v12
	v_max_f32_e32 v30, v4, v5
	s_nop 0
	v_permlane32_swap_b32_e32 v2, v3
	v_cndmask_b32_e32 v40, v2, v3, vcc
	v_mov_b32_e32 v2, v30
	v_mov_b32_e32 v3, v30
	v_min_f32_e32 v31, v4, v5
	s_nop 0
	v_permlane32_swap_b32_e32 v2, v3
	v_cndmask_b32_e32 v41, v2, v3, vcc
	v_mov_b32_e32 v2, v31
	v_mov_b32_e32 v3, v31
	v_max_f32_e32 v32, v14, v16
	s_nop 0
	v_permlane32_swap_b32_e32 v2, v3
	v_cndmask_b32_e32 v46, v2, v3, vcc
	v_mov_b32_e32 v2, v32
	v_mov_b32_e32 v3, v32
	v_min_f32_e32 v14, v14, v16
	s_nop 0
	v_permlane32_swap_b32_e32 v2, v3
	v_cndmask_b32_e32 v47, v2, v3, vcc
	v_mov_b32_e32 v2, v14
	v_mov_b32_e32 v3, v14
	v_max_f32_e32 v16, v11, v7
	s_nop 0
	v_permlane32_swap_b32_e32 v2, v3
	v_cndmask_b32_e32 v48, v2, v3, vcc
	v_mov_b32_e32 v2, v16
	v_mov_b32_e32 v3, v16
	v_min_f32_e32 v11, v11, v7
	s_nop 0
	v_permlane32_swap_b32_e32 v2, v3
	v_cndmask_b32_e32 v42, v2, v3, vcc
	v_mov_b32_e32 v2, v11
	v_mov_b32_e32 v3, v11
	s_nop 1
	v_permlane32_swap_b32_e32 v2, v3
	v_cndmask_b32_e32 v43, v2, v3, vcc
	v_mov_b32_e32 v2, v33
	v_mov_b32_e32 v3, v33
	s_nop 1
	v_permlane32_swap_b32_e32 v2, v3
	v_cndmask_b32_e32 v27, v2, v3, vcc
	global_load_dwordx4 v[2:5], v[50:51], off
	v_mov_b32_e32 v6, v8
	v_mov_b32_e32 v7, v8
	s_nop 1
	v_permlane32_swap_b32_e32 v6, v7
	v_cndmask_b32_e32 v28, v6, v7, vcc
	v_lshl_add_u64 v[6:7], v[66:67], 0, s[0:1]
	global_load_dwordx4 v[18:21], v[6:7], off offset:1024
	v_mov_b32_e32 v22, v9
	v_mov_b32_e32 v23, v9
	s_nop 1
	v_permlane32_swap_b32_e32 v22, v23
	v_cndmask_b32_e32 v29, v22, v23, vcc
	v_mov_b32_e32 v22, v34
	v_mov_b32_e32 v23, v34
	s_nop 1
	v_permlane32_swap_b32_e32 v22, v23
	v_cndmask_b32_e32 v22, v22, v23, vcc
	v_max_f32_e32 v44, v22, v22
	global_load_dwordx4 v[22:25], v[6:7], off offset:2048
	v_max_f32_e32 v49, v26, v44
	v_max_f32_e32 v26, v29, v29
	v_max_f32_e32 v10, v10, v26
	v_max_f32_e32 v26, v28, v28
	v_max_f32_e32 v17, v17, v26
	v_max_f32_e32 v26, v27, v27
	v_max_f32_e32 v13, v13, v26
	global_load_dwordx4 v[26:29], v[6:7], off offset:3072
	s_mov_b32 s0, 0xa000
	v_add_co_u32_e64 v50, s[0:1], s0, v66
	v_max_f32_e32 v6, v43, v43
	s_nop 0
	v_addc_co_u32_e64 v51, s[0:1], 0, v67, s[0:1]
	v_max_f32_e32 v15, v15, v6
	v_max_f32_e32 v6, v42, v42
	global_load_dwordx4 v[42:45], v[50:51], off offset:-4096
	v_max_f32_e32 v12, v12, v6
	v_max_f32_e32 v6, v48, v48
	s_mov_b32 s0, 0x9000
	v_max_f32_e32 v30, v30, v6
	v_add_co_u32_e64 v6, s[0:1], s0, v66
	v_max_f32_e32 v46, v46, v46
	s_nop 0
	v_addc_co_u32_e64 v7, s[0:1], 0, v67, s[0:1]
	global_load_dwordx4 v[52:55], v[6:7], off offset:1024
	global_load_dwordx4 v[56:59], v[6:7], off offset:2048
	global_load_dwordx4 v[60:63], v[6:7], off offset:3072
	v_max_f32_e32 v47, v47, v47
	v_max_f32_e32 v32, v32, v46
	v_max_f32_e32 v6, v36, v36
	v_max_f32_e32 v7, v35, v35
	v_max_f32_e32 v31, v31, v47
	v_max_f32_e32 v6, v9, v6
	v_max_f32_e32 v7, v34, v7
	v_max_f32_e32 v9, v49, v32
	v_min_f32_e32 v34, v49, v32
	ds_read_b128 v[46:49], v71 offset:8192
	v_max_f32_e32 v41, v41, v41
	v_max_f32_e32 v39, v39, v39
	v_max_f32_e32 v38, v38, v38
	v_max_f32_e32 v37, v37, v37
	v_max_f32_e32 v14, v14, v41
	v_max_f32_e32 v40, v40, v40
	v_max_f32_e32 v11, v11, v39
	v_max_f32_e32 v33, v33, v38
	v_max_f32_e32 v8, v8, v37
	v_max_f32_e32 v16, v16, v40
	v_max_f32_e32 v32, v10, v14
	v_min_f32_e32 v35, v10, v14
	v_max_f32_e32 v38, v13, v11
	v_min_f32_e32 v39, v13, v11
	v_max_f32_e32 v10, v15, v33
	v_max_f32_e32 v11, v12, v8
	v_max_f32_e32 v36, v17, v16
	v_min_f32_e32 v37, v17, v16
	v_min_f32_e32 v40, v15, v33
	v_min_f32_e32 v41, v12, v8
	v_max_f32_e32 v64, v30, v6
	v_min_f32_e32 v65, v30, v6
	v_max_f32_e32 v68, v31, v7
	v_min_f32_e32 v69, v31, v7
	v_max_f32_e32 v73, v9, v10
	v_min_f32_e32 v74, v9, v10
	v_max_f32_e32 v75, v32, v11
	v_min_f32_e32 v76, v32, v11
	ds_read_b128 v[30:33], v71 offset:9216
	s_waitcnt vmcnt(7) lgkmcnt(1)
; __device__ __forceinline__ int crow(int r, int hi) { return (r & 3) + 8 * (r >> 2) + 4 * hi; }
; __device__ __forceinline__ void topk_p_lds(const bf16* __restrict__ skf, const char* qlds, int r32, int hi, unsigned (&Lst)[16]) {
;     ...
;     for (int ks = 0; ks < 8; ++ks) bq[ks] = *reinterpret_cast<const bf16x8*>(qlds + ((2 * ks + hi) * 32 + r32) * 16);
; #pragma unroll
;     for (int kb = 0; kb < 4; ++kb) {
;         bf16x8 a[8];
; #pragma unroll
;         for (int ks = 0; ks < 8; ++ks) a[ks] = *reinterpret_cast<const bf16x8*>(skf + (size_t)((((kb * 8 + ks) * 2 + hi) * 32 + r32) * 8));
;         f32x16 acc = {};
; #pragma unroll
;         for (int ks = 0; ks < 8; ++ks) acc = __builtin_amdgcn_mfma_f32_32x32x16_bf16(a[ks], bq[ks], acc, 0, 0, 0);
;         unsigned S[16];
; #pragma unroll
;         for (int r = 0; r < 16; ++r) S[r] = (__float_as_uint(acc[r]) & ~127u) | (unsigned)(32 * kb + crow(r, hi));
;         sort16_desc(S);
;         if (kb == 0) {
; #pragma unroll
;             for (int r = 0; r < 16; ++r) Lst[r] = S[r];
;         } else merge_top16(Lst, S);
	v_mfma_f32_32x32x16_bf16 v[2:17], v[2:5], v[46:49], 0
	v_max_f32_e32 v77, v36, v64
	v_min_f32_e32 v64, v36, v64
	v_max_f32_e32 v78, v38, v68
	v_min_f32_e32 v38, v38, v68
	v_max_f32_e32 v68, v34, v40
	v_min_f32_e32 v79, v34, v40
	v_max_f32_e32 v80, v35, v41
	s_waitcnt vmcnt(6) lgkmcnt(0)
	v_mfma_f32_32x32x16_bf16 v[2:17], v[18:21], v[30:33], v[2:17]
	v_min_f32_e32 v81, v35, v41
	v_max_f32_e32 v40, v37, v65
	v_min_f32_e32 v65, v37, v65
	ds_read_b128 v[34:37], v71 offset:10240
	ds_read_b128 v[18:21], v71 offset:11264
	v_max_f32_e32 v82, v39, v69
	v_min_f32_e32 v69, v39, v69
	s_waitcnt vmcnt(5) lgkmcnt(1)
	v_mfma_f32_32x32x16_bf16 v[2:17], v[22:25], v[34:37], v[2:17]
	v_max_f32_e32 v85, v76, v38
	v_min_f32_e32 v87, v76, v38
	v_max_f32_e32 v89, v68, v40
	v_min_f32_e32 v68, v68, v40
	ds_read_b128 v[38:41], v71 offset:12288
	ds_read_b128 v[22:25], v71 offset:13312
	v_max_f32_e32 v83, v73, v77
	s_waitcnt vmcnt(4) lgkmcnt(2)
	v_mfma_f32_32x32x16_bf16 v[2:17], v[26:29], v[18:21], v[2:17]
	ds_read_b128 v[26:29], v71 offset:15360
	v_max_f32_e32 v84, v75, v78
	v_max_f32_e32 v90, v80, v82
	v_min_f32_e32 v82, v80, v82
	v_max_f32_e32 v91, v79, v65
	v_max_f32_e32 v92, v81, v69
	v_min_f32_e32 v77, v73, v77
	s_waitcnt vmcnt(3) lgkmcnt(2)
	v_mfma_f32_32x32x16_bf16 v[2:17], v[42:45], v[38:41], v[2:17]
	ds_read_b128 v[42:45], v71 offset:14336
	v_min_f32_e32 v75, v75, v78
	v_max_f32_e32 v78, v74, v64
	v_min_f32_e32 v64, v74, v64
	v_min_f32_e32 v65, v79, v65
	v_min_f32_e32 v69, v81, v69
	v_max_f32_e32 v73, v83, v84
	s_waitcnt vmcnt(2) lgkmcnt(2)
	v_mfma_f32_32x32x16_bf16 v[2:17], v[52:55], v[22:25], v[2:17]
	v_min_f32_e32 v74, v83, v84
	v_max_f32_e32 v79, v68, v82
	v_min_f32_e32 v81, v68, v82
	v_max_f32_e32 v82, v91, v92
	v_min_f32_e32 v83, v91, v92
	global_load_dwordx4 v[92:95], v[50:51], off offset:1024
	global_load_dwordx4 v[96:99], v[50:51], off offset:2048
	global_load_dwordx4 v[100:103], v[50:51], off offset:3072
	s_waitcnt vmcnt(4) lgkmcnt(0)
	v_mfma_f32_32x32x16_bf16 v[2:17], v[56:59], v[42:45], v[2:17]
	s_mov_b32 s0, 0xc000
	v_add_co_u32_e64 v68, s[0:1], s0, v66
	v_max_f32_e32 v76, v77, v75
	v_min_f32_e32 v80, v77, v75
	v_max_f32_e32 v84, v78, v85
	v_min_f32_e32 v86, v78, v85
	s_waitcnt vmcnt(3)
	v_mfma_f32_32x32x16_bf16 v[2:17], v[60:63], v[26:29], v[2:17]
	v_max_f32_e32 v88, v64, v87
	v_min_f32_e32 v75, v64, v87
	v_max_f32_e32 v85, v65, v69
	v_min_f32_e32 v87, v65, v69
	v_addc_co_u32_e64 v69, s[0:1], 0, v67, s[0:1]
	global_load_dwordx4 v[62:65], v[68:69], off offset:-4096
	s_nop 5
	v_and_b32_e32 v7, 0xffffff80, v7
	v_or3_b32 v7, v72, v7, 9
	v_and_b32_e32 v6, 0xffffff80, v6
	v_and_b32_e32 v9, 0xffffff80, v9
	v_max_f32_e32 v60, v7, v7
	v_and_b32_e32 v7, 0xffffff80, v15
	v_or3_b32 v6, v72, v6, 8
	v_or3_b32 v9, v72, v9, 11
	v_or3_b32 v7, v72, v7, 25
	v_max_f32_e32 v55, v6, v6
	v_and_b32_e32 v6, 0xffffff80, v16
	v_max_f32_e32 v52, v9, v9
	v_and_b32_e32 v9, 0xffffff80, v14
	v_and_b32_e32 v8, 0xffffff80, v8
	v_max_f32_e32 v61, v7, v7
	v_and_b32_e32 v7, 0xffffff80, v10
	v_or3_b32 v6, v72, v6, 26
	v_or3_b32 v9, v72, v9, 24
	v_or3_b32 v8, v72, v8, 10
	v_or3_b32 v7, v72, v7, 16
	v_max_f32_e32 v16, v6, v6
	v_and_b32_e32 v6, 0xffffff80, v11
	v_max_f32_e32 v14, v9, v9
	v_max_f32_e32 v59, v8, v8
	v_max_f32_e32 v10, v7, v7
	v_or3_b32 v11, v72, v6, 17
	global_load_dwordx4 v[6:9], v[50:51], off
	v_and_or_b32 v2, v2, s15, v72
	v_and_b32_e32 v3, 0xffffff80, v3
	v_max_f32_e32 v15, v2, v2
	v_and_b32_e32 v5, 0xffffff80, v5
	v_or3_b32 v3, v72, v3, 1
	v_min_f32_e32 v54, v60, v59
	v_min_f32_e32 v2, v15, v61
	v_or3_b32 v5, v72, v5, 3
	s_mov_b32 s0, 0xb000
	v_max_f32_e32 v3, v3, v3
	v_min_f32_e32 v91, v54, v2
	v_max_f32_e32 v5, v5, v5
	v_max_f32_e32 v110, v54, v2
	v_add_co_u32_e64 v2, s[0:1], s0, v66
	v_min_f32_e32 v58, v3, v14
	v_min_f32_e32 v56, v55, v10
	v_min_f32_e32 v57, v5, v16
	v_max_f32_e32 v14, v3, v14
	v_addc_co_u32_e64 v3, s[0:1], 0, v67, s[0:1]
	v_min_f32_e32 v105, v56, v57
	v_max_f32_e32 v111, v56, v57
	v_max_f32_e32 v10, v55, v10
	global_load_dwordx4 v[54:57], v[2:3], off offset:1024
	v_and_b32_e32 v13, 0xffffff80, v13
	v_and_b32_e32 v12, 0xffffff80, v12
	v_and_b32_e32 v4, 0xffffff80, v4
	v_and_b32_e32 v17, 0xffffff80, v17
	v_or3_b32 v13, v72, v13, 19
	v_or3_b32 v12, v72, v12, 18
	v_or3_b32 v4, v72, v4, 2
	v_or3_b32 v17, v72, v17, 27
	v_max_f32_e32 v13, v13, v13
	v_max_f32_e32 v12, v12, v12
	v_max_f32_e32 v11, v11, v11
	v_max_f32_e32 v17, v17, v17
	v_max_f32_e32 v4, v4, v4
	v_min_f32_e32 v53, v52, v13
	v_min_f32_e32 v106, v11, v12
	v_min_f32_e32 v107, v4, v17
	v_max_f32_e32 v77, v89, v90
	v_min_f32_e32 v78, v89, v90
	v_min_f32_e32 v90, v53, v58
	v_min_f32_e32 v108, v106, v107
	v_max_f32_e32 v15, v15, v61
	v_max_f32_e32 v115, v60, v59
	v_max_f32_e32 v106, v106, v107
	v_max_f32_e32 v107, v53, v58
	global_load_dwordx4 v[58:61], v[2:3], off offset:2048
	v_max_f32_e32 v13, v52, v13
	global_load_dwordx4 v[50:53], v[2:3], off offset:3072
	v_max_f32_e32 v4, v4, v17
	v_max_f32_e32 v11, v11, v12
	v_max_f32_e32 v5, v5, v16
	v_min_f32_e32 v104, v90, v91
	v_min_f32_e32 v109, v105, v108
	v_min_f32_e32 v113, v14, v13
	v_min_f32_e32 v12, v4, v11
	v_min_f32_e32 v16, v5, v10
	v_min_f32_e32 v116, v15, v115
	v_min_f32_e32 v89, v104, v109
	v_min_f32_e32 v112, v110, v111
	v_min_f32_e32 v17, v113, v12
	v_min_f32_e32 v117, v16, v116
	v_min_f32_e32 v118, v106, v107
	v_max_f32_e32 v104, v104, v109
	v_max_f32_e32 v109, v90, v91
	v_max_f32_e32 v105, v105, v108
	v_min_f32_e32 v114, v112, v17
	v_min_f32_e32 v119, v117, v118
	v_min_f32_e32 v91, v109, v105
	v_min_f32_e32 v120, v114, v119
	v_min_f32_e32 v2, v104, v91
	v_max_f32_e32 v3, v114, v119
	v_max_f32_e32 v104, v104, v91
	v_min_f32_e32 v90, v120, v2
	v_max_f32_e32 v2, v120, v2
	v_min_f32_e32 v108, v3, v104
	v_min_f32_e32 v91, v2, v108
	v_max_f32_e32 v114, v2, v108
	v_max_f32_e32 v110, v110, v111
	v_max_f32_e32 v111, v113, v12
	v_max_f32_e32 v112, v112, v17
	v_max_f32_e32 v116, v16, v116
	v_max_f32_e32 v104, v3, v104
	v_max_f32_e32 v115, v15, v115
	v_max_f32_e32 v120, v14, v13
	v_max_f32_e32 v122, v4, v11
	v_max_f32_e32 v123, v5, v10
	s_waitcnt vmcnt(3)
; __device__ __forceinline__ int crow(int r, int hi) { return (r & 3) + 8 * (r >> 2) + 4 * hi; }
; __device__ __forceinline__ void topk_p_lds(const bf16* __restrict__ skf, const char* qlds, int r32, int hi, unsigned (&Lst)[16]) {
;     ...
; #pragma unroll
;     for (int kb = 0; kb < 4; ++kb) {
;         bf16x8 a[8];
; #pragma unroll
;         for (int ks = 0; ks < 8; ++ks) a[ks] = *reinterpret_cast<const bf16x8*>(skf + (size_t)((((kb * 8 + ks) * 2 + hi) * 32 + r32) * 8));
;         f32x16 acc = {};
; #pragma unroll
;         for (int ks = 0; ks < 8; ++ks) acc = __builtin_amdgcn_mfma_f32_32x32x16_bf16(a[ks], bq[ks], acc, 0, 0, 0);
;         unsigned S[16];
; #pragma unroll
;         for (int r = 0; r < 16; ++r) S[r] = (__float_as_uint(acc[r]) & ~127u) | (unsigned)(32 * kb + crow(r, hi));
;         sort16_desc(S);
;         if (kb == 0) {
; #pragma unroll
;             for (int r = 0; r < 16; ++r) Lst[r] = S[r];
;         } else merge_top16(Lst, S);
	v_mfma_f32_32x32x16_bf16 v[2:17], v[6:9], v[46:49], 0
	v_max_f32_e32 v106, v106, v107
	v_min_f32_e32 v121, v115, v120
	v_min_f32_e32 v124, v122, v123
	v_max_f32_e32 v108, v117, v118
	v_min_f32_e32 v113, v110, v111
	v_min_f32_e32 v107, v116, v106
	v_min_f32_e32 v125, v121, v124
	v_mfma_f32_32x32x16_bf16 v[2:17], v[92:95], v[30:33], v[2:17]
	v_max_f32_e32 v105, v109, v105
	v_min_f32_e32 v117, v108, v113
	v_min_f32_e32 v118, v112, v107
	v_min_f32_e32 v109, v125, v105
	v_min_f32_e32 v119, v117, v118
	v_min_f32_e32 v126, v104, v109
	v_max_f32_e32 v117, v117, v118
	v_mfma_f32_32x32x16_bf16 v[2:17], v[96:99], v[34:37], v[2:17]
	v_max_f32_e32 v104, v104, v109
	v_max_f32_e32 v115, v115, v120
	v_max_f32_e32 v120, v122, v123
	v_min_f32_e32 v109, v117, v104
	v_max_f32_e32 v104, v117, v104
	v_max_f32_e32 v117, v121, v124
	v_min_f32_e32 v96, v115, v120
	v_mfma_f32_32x32x16_bf16 v[2:17], v[100:103], v[18:21], v[2:17]
	v_max_f32_e32 v98, v116, v106
	v_max_f32_e32 v99, v110, v111
	v_min_f32_e32 v97, v117, v96
	v_min_f32_e32 v106, v98, v99
	v_max_f32_e32 v105, v125, v105
	v_min_f32_e32 v110, v97, v106
	v_max_f32_e32 v101, v108, v113
	v_mfma_f32_32x32x16_bf16 v[2:17], v[62:65], v[38:41], v[2:17]
	v_max_f32_e32 v102, v112, v107
	global_load_dwordx4 v[92:95], v[68:69], off
	v_max_f32_e32 v118, v119, v126
	v_max_f32_e32 v62, v105, v110
	v_max_f32_e32 v63, v101, v102
	v_min_f32_e32 v127, v119, v126
	v_min_f32_e32 v119, v109, v118
	s_waitcnt vmcnt(3)
	v_mfma_f32_32x32x16_bf16 v[2:17], v[54:57], v[22:25], v[2:17]
	v_max_f32_e32 v113, v109, v118
	v_min_f32_e32 v118, v62, v63
	v_max_f32_e32 v125, v62, v63
	v_max_f32_e32 v117, v117, v96
	v_max_f32_e32 v126, v97, v106
	s_mov_b32 s0, 0xd000
	v_min_f32_e32 v100, v105, v110
	s_waitcnt vmcnt(2)
	v_mfma_f32_32x32x16_bf16 v[2:17], v[58:61], v[42:45], v[2:17]
	v_min_f32_e32 v103, v101, v102
	v_add_co_u32_e64 v108, s[0:1], s0, v66
	v_min_f32_e32 v107, v100, v103
	s_nop 0
	v_addc_co_u32_e64 v109, s[0:1], 0, v67, s[0:1]
	v_min_f32_e32 v112, v104, v107
	s_waitcnt vmcnt(1)
	v_mfma_f32_32x32x16_bf16 v[2:17], v[50:53], v[26:29], v[2:17]
	v_max_f32_e32 v123, v104, v107
	v_max_f32_e32 v129, v98, v99
	global_load_dwordx4 v[54:57], v[108:109], off offset:1024
	s_mov_b32 s0, 0xe000
	v_max_f32_e32 v121, v100, v103
	v_min_f32_e32 v116, v112, v113
	v_min_f32_e32 v122, v118, v121
	s_nop 4
	v_and_b32_e32 v9, 0xffffff80, v9
	v_and_b32_e32 v13, 0xffffff80, v13
	v_and_b32_e32 v3, 0xffffff80, v3
	v_and_b32_e32 v14, 0xffffff80, v14
	v_and_b32_e32 v7, 0xffffff80, v7
	v_and_b32_e32 v8, 0xffffff80, v8
	v_and_b32_e32 v2, 0xffffff80, v2
	v_and_b32_e32 v15, 0xffffff80, v15
	v_and_b32_e32 v6, 0xffffff80, v6
	v_and_b32_e32 v10, 0xffffff80, v10
	v_and_b32_e32 v5, 0xffffff80, v5
	v_and_b32_e32 v16, 0xffffff80, v16
	v_and_b32_e32 v11, 0xffffff80, v11
	v_and_b32_e32 v12, 0xffffff80, v12
	v_and_b32_e32 v4, 0xffffff80, v4
	v_and_b32_e32 v17, 0xffffff80, v17
	v_or3_b32 v9, v72, v9, 43
	v_or3_b32 v13, v72, v13, 51
	v_or3_b32 v3, v72, v3, 33
	v_or3_b32 v14, v72, v14, 56
	v_or3_b32 v7, v72, v7, 41
	v_or3_b32 v8, v72, v8, 42
	v_or3_b32 v2, v72, v2, 32
	v_or3_b32 v15, v72, v15, 57
	v_or3_b32 v6, v72, v6, 40
	v_or3_b32 v10, v72, v10, 48
	v_or3_b32 v5, v72, v5, 35
	v_or3_b32 v16, v72, v16, 58
	v_or3_b32 v11, v72, v11, 49
	v_or3_b32 v12, v72, v12, 50
	v_or3_b32 v4, v72, v4, 34
	v_or3_b32 v17, v72, v17, 59
	v_max_f32_e32 v13, v13, v13
	v_max_f32_e32 v9, v9, v9
	v_max_f32_e32 v14, v14, v14
	v_max_f32_e32 v3, v3, v3
	v_max_f32_e32 v8, v8, v8
	v_max_f32_e32 v7, v7, v7
	v_max_f32_e32 v15, v15, v15
	v_max_f32_e32 v2, v2, v2
	v_max_f32_e32 v10, v10, v10
	v_max_f32_e32 v6, v6, v6
	v_max_f32_e32 v16, v16, v16
	v_max_f32_e32 v5, v5, v5
	v_max_f32_e32 v12, v12, v12
	v_max_f32_e32 v11, v11, v11
	v_max_f32_e32 v17, v17, v17
	v_max_f32_e32 v4, v4, v4
	v_min_f32_e32 v50, v9, v13
	v_min_f32_e32 v51, v3, v14
	v_min_f32_e32 v53, v7, v8
	v_min_f32_e32 v58, v2, v15
	v_min_f32_e32 v61, v6, v10
	v_min_f32_e32 v62, v5, v16
	v_min_f32_e32 v64, v11, v12
	v_min_f32_e32 v65, v4, v17
	v_max_f32_e32 v3, v3, v14
	v_max_f32_e32 v9, v9, v13
	v_max_f32_e32 v4, v4, v17
	v_max_f32_e32 v11, v11, v12
	v_max_f32_e32 v5, v5, v16
	v_max_f32_e32 v6, v6, v10
	v_max_f32_e32 v2, v2, v15
	v_max_f32_e32 v7, v7, v8
	v_min_f32_e32 v52, v50, v51
	v_min_f32_e32 v59, v53, v58
	v_min_f32_e32 v63, v61, v62
	v_min_f32_e32 v96, v64, v65
	v_max_f32_e32 v53, v53, v58
	v_max_f32_e32 v58, v61, v62
	v_min_f32_e32 v13, v3, v9
	v_min_f32_e32 v12, v4, v11
	v_min_f32_e32 v10, v5, v6
	v_min_f32_e32 v8, v2, v7
	v_max_f32_e32 v16, v64, v65
	v_max_f32_e32 v50, v50, v51
	v_min_f32_e32 v60, v52, v59
	v_min_f32_e32 v97, v63, v96
	v_min_f32_e32 v61, v53, v58
	v_min_f32_e32 v14, v13, v12
	v_min_f32_e32 v15, v10, v8
	v_min_f32_e32 v51, v16, v50
	v_max_f32_e32 v52, v52, v59
	v_max_f32_e32 v63, v63, v96
	v_min_f32_e32 v133, v60, v97
	v_min_f32_e32 v17, v61, v14
	v_min_f32_e32 v62, v15, v51
	v_max_f32_e32 v60, v60, v97
	v_min_f32_e32 v59, v52, v63
	v_min_f32_e32 v64, v17, v62
	v_min_f32_e32 v65, v60, v59
	v_max_f32_e32 v17, v17, v62
	v_max_f32_e32 v59, v60, v59
	v_min_f32_e32 v134, v64, v65
	v_max_f32_e32 v64, v64, v65
	v_min_f32_e32 v60, v17, v59
	v_min_f32_e32 v135, v64, v60
	v_max_f32_e32 v136, v64, v60
	v_max_f32_e32 v53, v53, v58
	v_max_f32_e32 v14, v61, v14
	v_max_f32_e32 v17, v17, v59
	global_load_dwordx4 v[58:61], v[68:69], off offset:1024
	v_max_f32_e32 v4, v4, v11
	v_max_f32_e32 v11, v52, v63
	global_load_dwordx4 v[62:65], v[68:69], off offset:2048
	v_max_f32_e32 v2, v2, v7
	v_max_f32_e32 v3, v3, v9
	v_max_f32_e32 v5, v5, v6
	v_max_f32_e32 v12, v13, v12
	v_max_f32_e32 v8, v10, v8
	v_max_f32_e32 v10, v16, v50
	v_min_f32_e32 v7, v2, v3
; __device__ __forceinline__ unsigned kmax(unsigned a, unsigned b) { return __float_as_uint(__builtin_fmaxf(__uint_as_float(a), __uint_as_float(b))); }
; __device__ __forceinline__ void merge_top16(unsigned (&Lst)[16], const unsigned (&S)[16]) {
; #pragma unroll
;     for (int i = 0; i < 16; ++i) Lst[i] = kmax(Lst[i], S[15 - i]);
;     bitonic_merge_desc<16>(Lst);
; }
; __device__ __forceinline__ void topk_p_lds(const bf16* __restrict__ skf, const char* qlds, int r32, int hi, unsigned (&Lst)[16]) {
;     ...
; #pragma unroll
;         for (int ks = 0; ks < 8; ++ks) acc = __builtin_amdgcn_mfma_f32_32x32x16_bf16(a[ks], bq[ks], acc, 0, 0, 0);
	v_min_f32_e32 v6, v4, v5
	v_max_f32_e32 v15, v15, v51
	v_min_f32_e32 v13, v53, v12
	v_min_f32_e32 v16, v8, v10
	v_min_f32_e32 v9, v7, v6
	v_min_f32_e32 v51, v15, v13
	v_min_f32_e32 v50, v14, v16
	v_min_f32_e32 v52, v9, v11
	v_min_f32_e32 v96, v51, v50
	v_min_f32_e32 v97, v17, v52
	v_min_f32_e32 v137, v96, v97
	v_max_f32_e32 v104, v96, v97
	global_load_dwordx4 v[96:99], v[68:69], off offset:3072
	v_max_f32_e32 v50, v51, v50
	v_max_f32_e32 v17, v17, v52
	v_min_f32_e32 v52, v50, v17
	v_max_f32_e32 v17, v50, v17
	v_add_co_u32_e64 v50, s[0:1], s0, v66
	v_min_f32_e32 v139, v52, v104
	s_nop 0
	v_addc_co_u32_e64 v51, s[0:1], 0, v67, s[0:1]
	global_load_dwordx4 v[100:103], v[50:51], off offset:-4096
	v_max_f32_e32 v52, v52, v104
	global_load_dwordx4 v[104:107], v[108:109], off offset:2048
	v_max_f32_e32 v2, v2, v3
	global_load_dwordx4 v[108:111], v[108:109], off offset:3072
	v_max_f32_e32 v3, v4, v5
	v_max_f32_e32 v6, v7, v6
	v_min_f32_e32 v4, v2, v3
	v_max_f32_e32 v7, v8, v10
	v_max_f32_e32 v8, v53, v12
	v_min_f32_e32 v5, v6, v4
	v_min_f32_e32 v10, v7, v8
	v_max_f32_e32 v9, v9, v11
	v_min_f32_e32 v11, v5, v10
	v_max_f32_e32 v13, v15, v13
	v_max_f32_e32 v14, v14, v16
	v_min_f32_e32 v12, v9, v11
	v_min_f32_e32 v15, v13, v14
	v_max_f32_e32 v9, v9, v11
	v_max_f32_e32 v11, v13, v14
	v_min_f32_e32 v16, v12, v15
	v_min_f32_e32 v13, v9, v11
	v_max_f32_e32 v12, v12, v15
	v_max_f32_e32 v4, v6, v4
	v_max_f32_e32 v6, v7, v8
	v_min_f32_e32 v14, v13, v12
	v_max_f32_e32 v15, v17, v16
	v_max_f32_e32 v5, v5, v10
	v_min_f32_e32 v7, v4, v6
	v_min_f32_e32 v130, v117, v129
	v_min_f32_e32 v53, v17, v16
	v_min_f32_e32 v16, v14, v15
	v_max_f32_e32 v9, v9, v11
	v_min_f32_e32 v8, v5, v7
	v_min_f32_e32 v128, v114, v127
	v_min_f32_e32 v124, v122, v123
	v_min_f32_e32 v10, v9, v8
	v_max3_f32 v11, v115, v120, v133
	v_max3_f32 v17, v117, v129, v134
	v_max3_f32 v69, v126, v130, v135
	v_max3_f32 v16, v112, v113, v16
	v_max3_f32 v14, v116, v14, v15
	v_max3_f32 v12, v119, v13, v12
	v_min_f32_e32 v68, v53, v52
	v_max3_f32 v52, v124, v53, v52
	v_max3_f32 v53, v114, v127, v10
	v_max3_f32 v112, v128, v9, v8
	v_max3_f32 v91, v91, v5, v7
	v_max3_f32 v90, v90, v4, v6
	v_max3_f32 v89, v89, v2, v3
	v_max_f32_e32 v113, v11, v16
	v_min_f32_e32 v114, v11, v16
	v_max_f32_e32 v116, v17, v14
	v_min_f32_e32 v119, v17, v14
	v_max_f32_e32 v120, v69, v12
	v_min_f32_e32 v69, v69, v12
	s_waitcnt vmcnt(7)
	v_mfma_f32_32x32x16_bf16 v[2:17], v[92:95], v[46:49], 0
	v_min_f32_e32 v131, v126, v130
	v_min_f32_e32 v132, v125, v131
	v_min_f32_e32 v138, v136, v137
	v_max3_f32 v115, v125, v131, v138
	v_max3_f32 v117, v132, v136, v137
	v_max3_f32 v118, v118, v121, v139
	v_max3_f32 v68, v122, v123, v68
	s_waitcnt vmcnt(5)
	v_mfma_f32_32x32x16_bf16 v[2:17], v[58:61], v[30:33], v[2:17]
	v_max_f32_e32 v121, v115, v53
	v_min_f32_e32 v53, v115, v53
	v_max_f32_e32 v92, v117, v112
	v_min_f32_e32 v93, v117, v112
	v_max_f32_e32 v94, v118, v91
	v_min_f32_e32 v91, v118, v91
	v_max_f32_e32 v95, v68, v90
	s_waitcnt vmcnt(4)
	v_mfma_f32_32x32x16_bf16 v[2:17], v[62:65], v[34:37], v[2:17]
	v_min_f32_e32 v68, v68, v90
	v_max_f32_e32 v58, v52, v89
	v_min_f32_e32 v52, v52, v89
	v_max_f32_e32 v59, v113, v92
	v_min_f32_e32 v60, v113, v92
	v_max_f32_e32 v61, v116, v94
	v_max_f32_e32 v90, v120, v95
	s_waitcnt vmcnt(3)
	v_mfma_f32_32x32x16_bf16 v[2:17], v[96:99], v[18:21], v[2:17]
	v_min_f32_e32 v62, v120, v95
	v_max_f32_e32 v63, v121, v58
	v_max_f32_e32 v64, v114, v93
	v_min_f32_e32 v65, v114, v93
	v_max_f32_e32 v92, v119, v91
	v_min_f32_e32 v91, v119, v91
	v_max_f32_e32 v93, v69, v68
	s_waitcnt vmcnt(2)
	v_mfma_f32_32x32x16_bf16 v[2:17], v[100:103], v[38:41], v[2:17]
	v_min_f32_e32 v68, v69, v68
	v_max_f32_e32 v69, v53, v52
	v_min_f32_e32 v52, v53, v52
	v_min_f32_e32 v58, v121, v58
	v_max_f32_e32 v112, v59, v90
	v_min_f32_e32 v113, v59, v90
	v_max_f32_e32 v114, v61, v63
	v_mfma_f32_32x32x16_bf16 v[2:17], v[54:57], v[22:25], v[2:17]
	v_min_f32_e32 v102, v61, v63
	v_max_f32_e32 v103, v60, v62
	v_min_f32_e32 v115, v60, v62
	v_max_f32_e32 v121, v91, v52
	v_min_f32_e32 v122, v91, v52
	v_min_f32_e32 v89, v116, v94
	v_max_f32_e32 v117, v64, v93
	s_waitcnt vmcnt(1)
	v_mfma_f32_32x32x16_bf16 v[2:17], v[104:107], v[42:45], v[2:17]
	v_min_f32_e32 v118, v64, v93
	v_max_f32_e32 v116, v89, v58
	v_min_f32_e32 v89, v89, v58
	v_max_f32_e32 v120, v65, v68
	v_min_f32_e32 v68, v65, v68
	v_max_f32_e32 v119, v92, v69
	v_min_f32_e32 v69, v92, v69
	s_waitcnt vmcnt(0)
; __device__ __forceinline__ int crow(int r, int hi) { return (r & 3) + 8 * (r >> 2) + 4 * hi; }
; __device__ __forceinline__ void topk_p_lds(const bf16* __restrict__ skf, const char* qlds, int r32, int hi, unsigned (&Lst)[16]) {
;     ...
; #pragma unroll
;     for (int kb = 0; kb < 4; ++kb) {
;         bf16x8 a[8];
; #pragma unroll
;         for (int ks = 0; ks < 8; ++ks) a[ks] = *reinterpret_cast<const bf16x8*>(skf + (size_t)((((kb * 8 + ks) * 2 + hi) * 32 + r32) * 8));
;     ...
;         unsigned S[16];
; #pragma unroll
;         for (int r = 0; r < 16; ++r) S[r] = (__float_as_uint(acc[r]) & ~127u) | (unsigned)(32 * kb + crow(r, hi));
;         sort16_desc(S);
;         if (kb == 0) {
; #pragma unroll
;             for (int r = 0; r < 16; ++r) Lst[r] = S[r];
;         } else merge_top16(Lst, S);
	v_mfma_f32_32x32x16_bf16 v[2:17], v[108:111], v[26:29], v[2:17]
	s_mov_b32 s0, 0xf000
	v_min_f32_e32 v123, v112, v114
	v_min_f32_e32 v107, v117, v119
	v_min_f32_e32 v104, v113, v102
	v_min_f32_e32 v105, v103, v116
	v_min_f32_e32 v106, v115, v89
	v_min_f32_e32 v124, v118, v69
	s_nop 4
	v_and_b32_e32 v9, 0xffffff80, v9
	v_and_b32_e32 v13, 0xffffff80, v13
	v_and_b32_e32 v3, 0xffffff80, v3
	v_and_b32_e32 v14, 0xffffff80, v14
	v_and_b32_e32 v7, 0xffffff80, v7
	v_and_b32_e32 v8, 0xffffff80, v8
	v_and_b32_e32 v2, 0xffffff80, v2
	v_and_b32_e32 v15, 0xffffff80, v15
	v_and_b32_e32 v6, 0xffffff80, v6
	v_and_b32_e32 v10, 0xffffff80, v10
	v_and_b32_e32 v5, 0xffffff80, v5
	v_and_b32_e32 v16, 0xffffff80, v16
	v_and_b32_e32 v11, 0xffffff80, v11
	v_and_b32_e32 v12, 0xffffff80, v12
	v_and_b32_e32 v4, 0xffffff80, v4
	v_and_b32_e32 v17, 0xffffff80, v17
	v_or3_b32 v9, v72, v9, s16
	v_or3_b32 v13, v72, v13, s17
	v_or3_b32 v3, v72, v3, s3
	v_or3_b32 v14, v72, v14, s23
	v_or3_b32 v7, v72, v7, s33
	v_or3_b32 v8, v72, v8, s68
	v_or3_b32 v2, v72, v2, 64
	v_or3_b32 v15, v72, v15, s69
	v_or3_b32 v6, v72, v6, s70
	v_or3_b32 v10, v72, v10, s71
	v_or3_b32 v5, v72, v5, s76
	v_or3_b32 v16, v72, v16, s77
	v_or3_b32 v11, v72, v11, s78
	v_or3_b32 v12, v72, v12, s79
	v_or3_b32 v4, v72, v4, s80
	v_or3_b32 v17, v72, v17, s81
	v_max_f32_e32 v13, v13, v13
	v_max_f32_e32 v9, v9, v9
	v_max_f32_e32 v14, v14, v14
	v_max_f32_e32 v3, v3, v3
	v_max_f32_e32 v8, v8, v8
	v_max_f32_e32 v7, v7, v7
	v_max_f32_e32 v15, v15, v15
	v_max_f32_e32 v2, v2, v2
	v_max_f32_e32 v10, v10, v10
	v_max_f32_e32 v6, v6, v6
	v_max_f32_e32 v16, v16, v16
	v_max_f32_e32 v5, v5, v5
	v_max_f32_e32 v12, v12, v12
	v_max_f32_e32 v11, v11, v11
	v_max_f32_e32 v17, v17, v17
	v_max_f32_e32 v4, v4, v4
	v_min_f32_e32 v52, v9, v13
	v_min_f32_e32 v53, v3, v14
	v_min_f32_e32 v55, v7, v8
	v_min_f32_e32 v56, v2, v15
	v_min_f32_e32 v59, v6, v10
	v_min_f32_e32 v60, v5, v16
	v_min_f32_e32 v62, v11, v12
	v_min_f32_e32 v63, v4, v17
	v_max_f32_e32 v3, v3, v14
	v_max_f32_e32 v9, v9, v13
	v_max_f32_e32 v4, v4, v17
	v_max_f32_e32 v11, v11, v12
	v_max_f32_e32 v5, v5, v16
	v_max_f32_e32 v6, v6, v10
	v_max_f32_e32 v2, v2, v15
	v_max_f32_e32 v7, v7, v8
	v_min_f32_e32 v13, v3, v9
	v_min_f32_e32 v12, v4, v11
	v_min_f32_e32 v10, v5, v6
	v_min_f32_e32 v8, v2, v7
	v_max_f32_e32 v7, v2, v7
	v_max_f32_e32 v9, v3, v9
	v_max_f32_e32 v11, v4, v11
	v_max_f32_e32 v6, v5, v6
	global_load_dwordx4 v[2:5], v[50:51], off
	v_min_f32_e32 v54, v52, v53
	v_min_f32_e32 v57, v55, v56
	v_min_f32_e32 v61, v59, v60
	v_min_f32_e32 v64, v62, v63
	v_max_f32_e32 v55, v55, v56
	v_max_f32_e32 v56, v59, v60
	v_max_f32_e32 v16, v62, v63
	v_max_f32_e32 v52, v52, v53
	v_min_f32_e32 v58, v54, v57
	v_min_f32_e32 v65, v61, v64
	v_min_f32_e32 v59, v55, v56
	v_min_f32_e32 v14, v13, v12
	v_min_f32_e32 v15, v10, v8
	v_min_f32_e32 v53, v16, v52
	v_max_f32_e32 v54, v54, v57
	v_max_f32_e32 v57, v61, v64
	v_min_f32_e32 v108, v58, v65
	v_min_f32_e32 v17, v59, v14
	v_min_f32_e32 v60, v15, v53
	v_max_f32_e32 v58, v58, v65
	v_min_f32_e32 v61, v54, v57
	v_max_f32_e32 v15, v15, v53
	v_max_f32_e32 v64, v55, v56
	v_max_f32_e32 v8, v10, v8
	v_max_f32_e32 v10, v16, v52
	v_max_f32_e32 v90, v54, v57
	global_load_dwordx4 v[52:55], v[50:51], off offset:1024
	v_min_f32_e32 v62, v17, v60
	v_min_f32_e32 v63, v58, v61
	v_max_f32_e32 v17, v17, v60
	v_max_f32_e32 v58, v58, v61
	v_min_f32_e32 v109, v62, v63
	v_max_f32_e32 v62, v62, v63
	v_min_f32_e32 v60, v17, v58
	v_min_f32_e32 v110, v62, v60
	v_max_f32_e32 v60, v62, v60
	v_max_f32_e32 v12, v13, v12
	v_min_f32_e32 v62, v7, v9
	v_min_f32_e32 v63, v11, v6
	v_min_f32_e32 v13, v64, v12
	v_max_f32_e32 v14, v59, v14
	v_min_f32_e32 v16, v8, v10
	v_min_f32_e32 v65, v62, v63
	v_min_f32_e32 v56, v15, v13
	v_min_f32_e32 v59, v14, v16
	v_max_f32_e32 v17, v17, v58
	v_min_f32_e32 v57, v65, v90
	v_min_f32_e32 v61, v56, v59
	v_min_f32_e32 v58, v17, v57
	v_min_f32_e32 v91, v61, v58
	v_max_f32_e32 v56, v56, v59
	v_max_f32_e32 v17, v17, v57
	v_min_f32_e32 v111, v60, v91
	v_max_f32_e32 v127, v60, v91
	v_min_f32_e32 v91, v56, v17
	v_max_f32_e32 v92, v61, v58
	v_max_f32_e32 v17, v56, v17
	global_load_dwordx4 v[56:59], v[50:51], off offset:2048
	v_max_f32_e32 v98, v62, v63
	global_load_dwordx4 v[60:63], v[50:51], off offset:3072
	v_max_f32_e32 v11, v11, v6
	v_add_co_u32_e64 v6, s[0:1], s0, v66
	v_max_f32_e32 v9, v7, v9
	s_nop 0
	v_addc_co_u32_e64 v7, s[0:1], 0, v67, s[0:1]
	v_max_f32_e32 v94, v65, v90
	v_max_f32_e32 v8, v8, v10
	v_max_f32_e32 v10, v64, v12
	global_load_dwordx4 v[64:67], v[6:7], off
	v_min_f32_e32 v128, v91, v92
	v_max_f32_e32 v130, v91, v92
	global_load_dwordx4 v[90:93], v[6:7], off offset:1024
	v_min_f32_e32 v99, v9, v11
	v_min_f32_e32 v100, v98, v99
	v_min_f32_e32 v12, v8, v10
	v_min_f32_e32 v50, v100, v12
	v_min_f32_e32 v51, v94, v50
	v_max_f32_e32 v50, v94, v50
	global_load_dwordx4 v[94:97], v[6:7], off offset:2048
	v_max_f32_e32 v13, v15, v13
	v_max_f32_e32 v14, v14, v16
	v_min_f32_e32 v15, v13, v14
	v_max_f32_e32 v13, v13, v14
	v_min_f32_e32 v16, v51, v15
	v_min_f32_e32 v14, v50, v13
	v_max_f32_e32 v15, v51, v15
	v_min_f32_e32 v51, v14, v15
	v_max_f32_e32 v14, v14, v15
	v_max_f32_e32 v12, v100, v12
	v_max_f32_e32 v15, v98, v99
	global_load_dwordx4 v[98:101], v[6:7], off offset:3072
	v_max_f32_e32 v8, v8, v10
	v_min_f32_e32 v129, v17, v16
	v_max_f32_e32 v16, v17, v16
	v_min_f32_e32 v10, v15, v8
	v_min_f32_e32 v17, v51, v16
	v_max_f32_e32 v13, v50, v13
	v_min_f32_e32 v6, v12, v10
	v_min_f32_e32 v125, v120, v121
	v_min_f32_e32 v126, v68, v122
	v_min_f32_e32 v7, v13, v6
	v_max_f32_e32 v6, v13, v6
	v_max_f32_e32 v8, v15, v8
	v_max3_f32 v13, v112, v114, v108
	v_max_f32_e32 v15, v123, v109
	v_max3_f32 v50, v113, v102, v110
	v_max3_f32 v17, v117, v119, v17
	v_max3_f32 v16, v107, v51, v16
	v_max3_f32 v14, v118, v69, v14
	v_max_f32_e32 v102, v104, v111
	v_max_f32_e32 v104, v105, v128
	v_max3_f32 v105, v106, v129, v130
	v_max_f32_e32 v51, v124, v7
	v_max3_f32 v69, v120, v121, v6
	v_max3_f32 v106, v125, v12, v10
	v_max3_f32 v68, v68, v122, v8
	v_max3_f32 v107, v126, v9, v11
	v_max_f32_e32 v108, v13, v17
	v_min_f32_e32 v109, v13, v17
	v_max_f32_e32 v110, v15, v16
	v_min_f32_e32 v111, v15, v16
	v_max_f32_e32 v112, v50, v14
	v_min_f32_e32 v50, v50, v14
	s_waitcnt vmcnt(7)
; __device__ __forceinline__ int crow(int r, int hi) { return (r & 3) + 8 * (r >> 2) + 4 * hi; }
; #define PEER_CE(i, j) do { const unsigned mx_ = kmax(a[i], a[j]), mn_ = kmin(a[i], a[j]); a[i] = mx_; a[j] = mn_; } while (0)
; __device__ __forceinline__ void sort16_desc(unsigned (&a)[16]) {
;     ...
;     PEER_CE(0, 13); PEER_CE(1, 12); PEER_CE(2, 15); PEER_CE(3, 14); PEER_CE(4, 8); PEER_CE(5, 6); PEER_CE(7, 11); PEER_CE(9, 10);
;     PEER_CE(0, 5); PEER_CE(1, 7); PEER_CE(2, 9); PEER_CE(3, 4); PEER_CE(6, 13); PEER_CE(8, 14); PEER_CE(10, 15); PEER_CE(11, 12);
;     PEER_CE(0, 1); PEER_CE(2, 3); PEER_CE(4, 5); PEER_CE(6, 8); PEER_CE(7, 9); PEER_CE(10, 11); PEER_CE(12, 13); PEER_CE(14, 15);
;     PEER_CE(0, 2); PEER_CE(1, 3); PEER_CE(4, 10); PEER_CE(5, 11); PEER_CE(6, 7); PEER_CE(8, 9); PEER_CE(12, 14); PEER_CE(13, 15);
;     PEER_CE(1, 2); PEER_CE(3, 12); PEER_CE(4, 6); PEER_CE(5, 7); PEER_CE(8, 10); PEER_CE(9, 11); PEER_CE(13, 14);
;     PEER_CE(1, 4); PEER_CE(2, 6); PEER_CE(5, 8); PEER_CE(7, 10); PEER_CE(9, 13); PEER_CE(11, 14);
;     PEER_CE(2, 4); PEER_CE(3, 6); PEER_CE(9, 12); PEER_CE(11, 13);
;     PEER_CE(3, 5); PEER_CE(6, 8); PEER_CE(7, 9); PEER_CE(10, 12);
;     PEER_CE(3, 4); PEER_CE(5, 6); PEER_CE(7, 8); PEER_CE(9, 10); PEER_CE(11, 12);
;     PEER_CE(6, 7); PEER_CE(8, 9);
;     ...
; }
; __device__ __forceinline__ void topk_p_lds(const bf16* __restrict__ skf, const char* qlds, int r32, int hi, unsigned (&Lst)[16]) {
;     ...
; #pragma unroll
;         for (int ks = 0; ks < 8; ++ks) acc = __builtin_amdgcn_mfma_f32_32x32x16_bf16(a[ks], bq[ks], acc, 0, 0, 0);
;         unsigned S[16];
; #pragma unroll
;         for (int r = 0; r < 16; ++r) S[r] = (__float_as_uint(acc[r]) & ~127u) | (unsigned)(32 * kb + crow(r, hi));
;         sort16_desc(S);
;         if (kb == 0) {
; #pragma unroll
;             for (int r = 0; r < 16; ++r) Lst[r] = S[r];
;         } else merge_top16(Lst, S);
	v_mfma_f32_32x32x16_bf16 v[2:17], v[2:5], v[46:49], 0
	v_min_f32_e32 v131, v129, v130
	v_max3_f32 v103, v103, v116, v127
	v_max3_f32 v89, v115, v89, v131
	v_max_f32_e32 v113, v102, v51
	v_max_f32_e32 v47, v103, v69
	v_min_f32_e32 v48, v103, v69
	v_max_f32_e32 v49, v104, v106
	s_waitcnt vmcnt(6)
	v_mfma_f32_32x32x16_bf16 v[2:17], v[52:55], v[30:33], v[2:17]
	v_max_f32_e32 v69, v89, v68
	v_max_f32_e32 v30, v105, v107
	v_min_f32_e32 v46, v102, v51
	v_min_f32_e32 v51, v104, v106
	v_min_f32_e32 v68, v89, v68
	v_min_f32_e32 v31, v105, v107
	v_max_f32_e32 v32, v108, v47
	s_waitcnt vmcnt(5)
	v_mfma_f32_32x32x16_bf16 v[2:17], v[56:59], v[34:37], v[2:17]
	v_min_f32_e32 v33, v108, v47
	v_max_f32_e32 v47, v110, v49
	v_min_f32_e32 v49, v110, v49
	v_max_f32_e32 v52, v112, v69
	v_min_f32_e32 v34, v112, v69
	v_max_f32_e32 v35, v113, v30
	v_min_f32_e32 v30, v113, v30
	s_waitcnt vmcnt(4)
	v_mfma_f32_32x32x16_bf16 v[2:17], v[60:63], v[18:21], v[2:17]
	v_max_f32_e32 v36, v109, v48
	v_min_f32_e32 v37, v109, v48
	v_max_f32_e32 v48, v111, v51
	v_min_f32_e32 v51, v111, v51
	v_max_f32_e32 v18, v50, v68
	v_min_f32_e32 v19, v50, v68
	v_max_f32_e32 v20, v46, v31
	s_waitcnt vmcnt(3)
	v_mfma_f32_32x32x16_bf16 v[2:17], v[64:67], v[38:41], v[2:17]
	v_min_f32_e32 v21, v46, v31
	v_max_f32_e32 v31, v32, v52
	v_min_f32_e32 v32, v32, v52
	v_max_f32_e32 v38, v33, v34
	v_min_f32_e32 v33, v33, v34
	v_max_f32_e32 v34, v49, v30
	v_min_f32_e32 v30, v49, v30
	s_waitcnt vmcnt(2)
	v_mfma_f32_32x32x16_bf16 v[2:17], v[90:93], v[22:25], v[2:17]
	v_max_f32_e32 v46, v47, v35
	v_min_f32_e32 v35, v47, v35
	v_max_f32_e32 v24, v51, v21
	v_min_f32_e32 v21, v51, v21
	v_max_f32_e32 v22, v48, v20
	v_min_f32_e32 v20, v48, v20
	v_max_f32_e32 v39, v36, v18
	s_waitcnt vmcnt(1)
	v_mfma_f32_32x32x16_bf16 v[2:17], v[94:97], v[42:45], v[2:17]
	v_min_f32_e32 v18, v36, v18
	v_max_f32_e32 v23, v37, v19
	v_min_f32_e32 v19, v37, v19
	v_min_f32_e32 v25, v31, v46
	v_min_f32_e32 v36, v32, v35
	v_min_f32_e32 v37, v38, v34
	v_min_f32_e32 v40, v33, v30
	s_waitcnt vmcnt(0)
	v_mfma_f32_32x32x16_bf16 v[2:17], v[98:101], v[26:29], v[2:17]
	v_min_f32_e32 v41, v39, v22
	v_min_f32_e32 v42, v18, v20
	v_min_f32_e32 v43, v23, v24
	v_min_f32_e32 v44, v19, v21
	s_waitcnt lgkmcnt(0)
	s_nop 7
	v_and_b32_e32 v5, 0xffffff80, v5
	v_and_b32_e32 v16, 0xffffff80, v16
	v_and_b32_e32 v6, 0xffffff80, v6
	v_and_b32_e32 v10, 0xffffff80, v10
	v_and_b32_e32 v2, 0xffffff80, v2
	v_and_b32_e32 v15, 0xffffff80, v15
	v_and_b32_e32 v7, 0xffffff80, v7
	v_and_b32_e32 v8, 0xffffff80, v8
	v_and_b32_e32 v11, 0xffffff80, v11
	v_and_b32_e32 v12, 0xffffff80, v12
	v_and_b32_e32 v4, 0xffffff80, v4
	v_and_b32_e32 v17, 0xffffff80, v17
	v_and_b32_e32 v9, 0xffffff80, v9
	v_and_b32_e32 v13, 0xffffff80, v13
	v_and_b32_e32 v3, 0xffffff80, v3
	v_and_b32_e32 v14, 0xffffff80, v14
	v_or3_b32 v5, v72, v5, s82
	v_or3_b32 v16, v72, v16, s83
	v_or3_b32 v6, v72, v6, s84
	v_or3_b32 v10, v72, v10, s85
	v_or3_b32 v2, v72, v2, s86
	v_or3_b32 v15, v72, v15, s87
	v_or3_b32 v7, v72, v7, s88
	v_or3_b32 v8, v72, v8, s89
	v_or3_b32 v11, v72, v11, s90
	v_or3_b32 v12, v72, v12, s91
	v_or3_b32 v4, v72, v4, s92
	v_or3_b32 v17, v72, v17, s93
	v_or3_b32 v9, v72, v9, s94
	v_or3_b32 v13, v72, v13, s95
	v_or3_b32 v3, v72, v3, s96
	v_or3_b32 v14, v72, v14, s97
	v_max_f32_e32 v16, v16, v16
	v_max_f32_e32 v5, v5, v5
	v_max_f32_e32 v10, v10, v10
	v_max_f32_e32 v6, v6, v6
	v_max_f32_e32 v15, v15, v15
	v_max_f32_e32 v2, v2, v2
	v_max_f32_e32 v8, v8, v8
	v_max_f32_e32 v7, v7, v7
	v_max_f32_e32 v12, v12, v12
	v_max_f32_e32 v11, v11, v11
	v_max_f32_e32 v17, v17, v17
	v_max_f32_e32 v4, v4, v4
	v_max_f32_e32 v13, v13, v13
	v_max_f32_e32 v9, v9, v9
	v_max_f32_e32 v14, v14, v14
	v_max_f32_e32 v3, v3, v3
	v_max_f32_e32 v26, v5, v16
	v_max_f32_e32 v27, v6, v10
	v_max_f32_e32 v29, v2, v15
	v_max_f32_e32 v45, v7, v8
	v_min_f32_e32 v49, v11, v12
	v_min_f32_e32 v50, v4, v17
	v_min_f32_e32 v52, v9, v13
	v_min_f32_e32 v53, v3, v14
	v_min_f32_e32 v7, v7, v8
	v_min_f32_e32 v2, v2, v15
	v_min_f32_e32 v6, v6, v10
	v_min_f32_e32 v5, v5, v16
	v_max_f32_e32 v3, v3, v14
	v_max_f32_e32 v9, v9, v13
	v_max_f32_e32 v4, v4, v17
	v_max_f32_e32 v11, v11, v12
	v_min_f32_e32 v28, v26, v27
	v_min_f32_e32 v47, v29, v45
	v_max_f32_e32 v51, v49, v50
	v_max_f32_e32 v54, v52, v53
	v_max_f32_e32 v8, v7, v2
	v_max_f32_e32 v10, v6, v5
	v_min_f32_e32 v13, v3, v9
	v_min_f32_e32 v12, v4, v11
	v_min_f32_e32 v52, v52, v53
	v_min_f32_e32 v2, v7, v2
	v_min_f32_e32 v5, v6, v5
	v_min_f32_e32 v6, v49, v50
	v_max_f32_e32 v29, v29, v45
	v_max_f32_e32 v3, v3, v9
	v_max_f32_e32 v4, v4, v11
	v_max_f32_e32 v11, v26, v27
	v_min_f32_e32 v48, v28, v47
	v_min_f32_e32 v55, v51, v54
	v_max_f32_e32 v15, v8, v10
	v_max_f32_e32 v14, v13, v12
	v_min_f32_e32 v8, v8, v10
	v_min_f32_e32 v10, v13, v12
	v_max_f32_e32 v13, v28, v47
	v_max_f32_e32 v28, v51, v54
	v_min_f32_e32 v7, v52, v2
	v_min_f32_e32 v49, v5, v6
	v_max_f32_e32 v2, v52, v2
	v_max_f32_e32 v5, v5, v6
	v_min_f32_e32 v9, v29, v3
	v_min_f32_e32 v26, v4, v11
	v_max_f32_e32 v3, v29, v3
	v_max_f32_e32 v4, v4, v11
	v_min_f32_e32 v16, v15, v14
	v_max_f32_e32 v12, v8, v10
	v_min_f32_e32 v47, v13, v28
	v_min_f32_e32 v8, v8, v10
	v_min_f32_e32 v10, v48, v55
	v_max_f32_e32 v50, v7, v49
	v_min_f32_e32 v6, v2, v5
	v_min_f32_e32 v27, v9, v26
	v_max_f32_e32 v9, v9, v26
	v_min_f32_e32 v11, v3, v4
	v_max_f32_e32 v13, v13, v28
	v_max_f32_e32 v14, v15, v14
	v_max_f32_e32 v56, v48, v55
	v_max_f32_e32 v48, v8, v10
	v_max_f32_e32 v52, v50, v6
	v_max_f32_e32 v2, v2, v5
	v_min_f32_e32 v26, v9, v11
	v_min_f32_e32 v15, v13, v14
	v_min_f32_e32 v17, v56, v16
	v_min_f32_e32 v51, v12, v47
	v_max_f32_e32 v53, v48, v52
; __device__ __forceinline__ unsigned kmax(unsigned a, unsigned b) { return __float_as_uint(__builtin_fmaxf(__uint_as_float(a), __uint_as_float(b))); }
; __device__ __forceinline__ void merge_top16(unsigned (&Lst)[16], const unsigned (&S)[16]) {
; #pragma unroll
;     for (int i = 0; i < 16; ++i) Lst[i] = kmax(Lst[i], S[15 - i]);
;     bitonic_merge_desc<16>(Lst);
; }
; __device__ __forceinline__ void topk_p_lds(const bf16* __restrict__ skf, const char* qlds, int r32, int hi, unsigned (&Lst)[16]) {
;     ...
;     unsigned Y[16];
; #pragma unroll
;     for (int s = 0; s < 16; ++s) { auto rr = __builtin_amdgcn_permlane32_swap(Lst[s], Lst[s], false, false); Y[s] = hi ? rr[0] : rr[1]; }
;     merge_top16(Lst, Y);
	v_min_f32_e32 v5, v27, v2
	v_max_f32_e32 v2, v27, v2
	v_min_f32_e32 v27, v26, v15
	v_max_f32_e32 v16, v56, v16
	v_max_f32_e32 v12, v12, v47
	v_max_f32_e32 v54, v17, v51
	v_max_f32_e32 v45, v53, v5
	v_min_f32_e32 v28, v2, v27
	v_min_f32_e32 v29, v16, v12
	v_min_f32_e32 v17, v17, v51
	v_min_f32_e32 v5, v53, v5
	v_max_f32_e32 v2, v2, v27
	v_max_f32_e32 v12, v16, v12
	v_min_f32_e32 v8, v8, v10
	v_min_f32_e32 v6, v50, v6
	v_max_f32_e32 v9, v9, v11
	v_max_f32_e32 v11, v13, v14
	v_max_f32_e32 v55, v54, v45
	v_min_f32_e32 v47, v28, v29
	v_min_f32_e32 v45, v54, v45
	v_max_f32_e32 v51, v17, v5
	v_min_f32_e32 v16, v2, v12
	v_max_f32_e32 v27, v28, v29
	v_max_f32_e32 v10, v8, v6
	v_min_f32_e32 v48, v48, v52
	v_max_f32_e32 v2, v2, v12
	v_max_f32_e32 v12, v26, v15
	v_min_f32_e32 v13, v9, v11
	v_min_f32_e32 v56, v55, v47
	v_max_f32_e32 v53, v45, v51
	v_min_f32_e32 v28, v16, v27
	v_max_f32_e32 v29, v55, v47
	v_max_f32_e32 v50, v10, v48
	v_min_f32_e32 v5, v17, v5
	v_min_f32_e32 v14, v12, v13
	v_min_f32_e32 v54, v56, v53
	v_min_f32_e32 v47, v28, v29
	v_min_f32_e32 v17, v50, v5
	v_max_f32_e32 v5, v50, v5
	v_min_f32_e32 v45, v45, v51
	v_max_f32_e32 v16, v16, v27
	v_min_f32_e32 v15, v2, v14
	v_max_f32_e32 v2, v2, v14
	v_min_f32_e32 v10, v10, v48
	v_min_f32_e32 v6, v8, v6
	v_max_f32_e32 v8, v9, v11
	v_min_f32_e32 v7, v7, v49
	v_max3_f32 v7, v31, v46, v7
	v_max_f32_e32 v6, v25, v6
	v_max3_f32 v9, v32, v35, v10
	v_max_f32_e32 v10, v36, v17
	v_max3_f32 v5, v38, v34, v5
	v_max_f32_e32 v11, v37, v45
	v_max3_f32 v14, v33, v30, v54
	v_max3_f32 v17, v40, v56, v53
	v_max3_f32 v22, v39, v22, v47
	v_max3_f32 v25, v41, v28, v29
	v_max3_f32 v16, v18, v20, v16
	v_max_f32_e32 v15, v42, v15
	v_max3_f32 v2, v23, v24, v2
	v_max3_f32 v12, v43, v12, v13
	v_max3_f32 v8, v19, v21, v8
	v_max3_f32 v3, v44, v3, v4
	v_max_f32_e32 v4, v7, v22
	v_max_f32_e32 v13, v6, v25
	v_max_f32_e32 v18, v9, v16
	v_min_f32_e32 v9, v9, v16
	v_max_f32_e32 v16, v10, v15
	v_min_f32_e32 v10, v10, v15
	v_max_f32_e32 v15, v5, v2
	v_min_f32_e32 v2, v5, v2
	v_max_f32_e32 v5, v11, v12
	v_min_f32_e32 v11, v11, v12
	v_max_f32_e32 v12, v14, v8
	v_min_f32_e32 v8, v14, v8
	v_max_f32_e32 v14, v17, v3
	v_min_f32_e32 v7, v7, v22
	v_min_f32_e32 v6, v6, v25
	v_min_f32_e32 v3, v17, v3
	v_max_f32_e32 v17, v4, v15
	v_min_f32_e32 v4, v4, v15
	v_max_f32_e32 v15, v13, v5
	v_min_f32_e32 v5, v13, v5
	v_max_f32_e32 v13, v18, v12
	v_min_f32_e32 v12, v18, v12
	v_max_f32_e32 v18, v16, v14
	v_min_f32_e32 v14, v16, v14
	v_max_f32_e32 v16, v7, v2
	v_min_f32_e32 v2, v7, v2
	v_max_f32_e32 v7, v6, v11
	v_min_f32_e32 v6, v6, v11
	v_max_f32_e32 v11, v9, v8
	v_min_f32_e32 v8, v9, v8
	v_max_f32_e32 v9, v10, v3
	v_min_f32_e32 v3, v10, v3
	v_max_f32_e32 v10, v17, v13
	v_min_f32_e32 v13, v17, v13
	v_max_f32_e32 v17, v15, v18
	v_min_f32_e32 v15, v15, v18
	v_max_f32_e32 v18, v4, v12
	v_min_f32_e32 v4, v4, v12
	v_max_f32_e32 v12, v5, v14
	v_min_f32_e32 v5, v5, v14
	v_max_f32_e32 v14, v16, v11
	v_min_f32_e32 v11, v16, v11
	v_max_f32_e32 v16, v7, v9
	v_min_f32_e32 v7, v7, v9
	v_max_f32_e32 v9, v2, v8
	v_min_f32_e32 v2, v2, v8
	v_max_f32_e32 v8, v6, v3
	v_min_f32_e32 v3, v6, v3
	v_max_f32_e32 v6, v10, v17
	v_min_f32_e32 v10, v10, v17
	v_max_f32_e32 v17, v13, v15
	v_min_f32_e32 v13, v13, v15
	v_max_f32_e32 v15, v18, v12
	v_min_f32_e32 v12, v18, v12
	v_max_f32_e32 v18, v4, v5
	v_min_f32_e32 v4, v4, v5
	v_max_f32_e32 v5, v14, v16
	v_min_f32_e32 v14, v14, v16
	v_max_f32_e32 v16, v11, v7
	v_min_f32_e32 v7, v11, v7
	v_max_f32_e32 v11, v9, v8
	v_min_f32_e32 v8, v9, v8
	v_max_f32_e32 v9, v2, v3
	v_min_f32_e32 v2, v2, v3
	v_mov_b32_e32 v3, v6
	v_mov_b32_e32 v19, v6
	s_nop 1
	v_permlane32_swap_b32_e32 v3, v19
	v_cndmask_b32_e32 v3, v3, v19, vcc
	v_mov_b32_e32 v19, v10
	v_mov_b32_e32 v20, v10
	s_nop 1
	v_permlane32_swap_b32_e32 v19, v20
	v_cndmask_b32_e32 v19, v19, v20, vcc
	v_mov_b32_e32 v20, v17
	v_mov_b32_e32 v21, v17
	s_nop 1
	v_permlane32_swap_b32_e32 v20, v21
	v_cndmask_b32_e32 v20, v20, v21, vcc
	v_mov_b32_e32 v21, v13
	v_mov_b32_e32 v22, v13
	s_nop 1
	v_permlane32_swap_b32_e32 v21, v22
	v_cndmask_b32_e32 v21, v21, v22, vcc
	v_mov_b32_e32 v22, v15
	v_mov_b32_e32 v23, v15
	s_nop 1
	v_permlane32_swap_b32_e32 v22, v23
	v_cndmask_b32_e32 v22, v22, v23, vcc
	v_mov_b32_e32 v23, v12
	v_mov_b32_e32 v24, v12
	s_nop 1
	v_permlane32_swap_b32_e32 v23, v24
	v_cndmask_b32_e32 v23, v23, v24, vcc
	v_mov_b32_e32 v24, v18
	v_mov_b32_e32 v25, v18
	s_nop 1
	v_permlane32_swap_b32_e32 v24, v25
	v_cndmask_b32_e32 v24, v24, v25, vcc
	v_mov_b32_e32 v25, v4
	v_mov_b32_e32 v26, v4
	s_nop 1
	v_permlane32_swap_b32_e32 v25, v26
	v_cndmask_b32_e32 v25, v25, v26, vcc
	v_mov_b32_e32 v26, v5
	v_mov_b32_e32 v27, v5
	s_nop 1
	v_permlane32_swap_b32_e32 v26, v27
	v_cndmask_b32_e32 v26, v26, v27, vcc
	v_mov_b32_e32 v27, v14
	v_mov_b32_e32 v28, v14
	s_nop 1
	v_permlane32_swap_b32_e32 v27, v28
	v_cndmask_b32_e32 v27, v27, v28, vcc
	v_mov_b32_e32 v28, v16
	v_mov_b32_e32 v29, v16
	s_nop 1
	v_permlane32_swap_b32_e32 v28, v29
	v_cndmask_b32_e32 v28, v28, v29, vcc
	v_mov_b32_e32 v29, v7
	v_mov_b32_e32 v30, v7
	s_nop 1
	v_permlane32_swap_b32_e32 v29, v30
	v_cndmask_b32_e32 v29, v29, v30, vcc
	v_mov_b32_e32 v30, v11
	v_mov_b32_e32 v31, v11
	s_nop 1
	v_permlane32_swap_b32_e32 v30, v31
	v_cndmask_b32_e32 v30, v30, v31, vcc
	v_mov_b32_e32 v31, v8
	v_mov_b32_e32 v32, v8
	s_nop 1
	v_permlane32_swap_b32_e32 v31, v32
	v_cndmask_b32_e32 v31, v31, v32, vcc
	v_mov_b32_e32 v32, v9
	v_mov_b32_e32 v33, v9
	s_nop 1
	v_permlane32_swap_b32_e32 v32, v33
	v_cndmask_b32_e32 v32, v32, v33, vcc
	v_mov_b32_e32 v33, v2
	v_mov_b32_e32 v34, v2
	s_nop 1
	v_permlane32_swap_b32_e32 v33, v34
	v_cndmask_b32_e32 v33, v33, v34, vcc
; #define PEER_CAND(a, b, cid, dst) do { const float sum_ = __uint_as_float(T0[a] & ~127u) + __uint_as_float(T1[b] & ~127u); dst = (__float_as_uint(sum_) & ~63u) | (unsigned)(cid); \
;         tab[(cid) * 64] = (unsigned short)((T0[a] & 127u) * 128u + (T1[b] & 127u)); } while (0)
; __device__ __forceinline__ void topk_p_lds(const bf16* __restrict__ skf, const char* qlds, int r32, int hi, unsigned (&Lst)[16]) {
;     ...
;     merge_top16(Lst, Y);
; __device__ __forceinline__ void select_wave_lds(const bf16* __restrict__ skf_h, char* qtile, int h, int* __restrict__ pidx, float* __restrict__ pgate, int wid, int lane) {
;     ...
;     unsigned short* tab = (unsigned short*)(qtile + wid * 16384) + lane;
;     unsigned C[16], R1[16], X[32];
;     ...
; #pragma unroll
;     for (int b = 0; b < 16; ++b) PEER_CAND(0, b, 15 - b, C[b]);
; #pragma unroll
;     for (int b = 0; b < 16; ++b) { if (b < 8) PEER_CAND(1, b, 23 - b, R1[b]); else R1[b] = KEY_NEG_INF; }
;     {   int xi = 0;
; #pragma unroll
;         for (int a = 2; a < 16; ++a)
; #pragma unroll
;             for (int b = 0; b < 16; ++b) if ((a + 1) * (b + 1) <= 16) { PEER_CAND(a, b, 24 + xi, X[xi]); ++xi; }
	v_max_f32_e32 v33, v33, v33
	v_max_f32_e32 v32, v32, v32
	v_max_f32_e32 v31, v31, v31
	v_max_f32_e32 v30, v30, v30
	v_max_f32_e32 v29, v29, v29
	v_max_f32_e32 v28, v28, v28
	v_max_f32_e32 v27, v27, v27
	v_max_f32_e32 v26, v26, v26
	v_max_f32_e32 v25, v25, v25
	v_max_f32_e32 v24, v24, v24
	v_max_f32_e32 v23, v23, v23
	v_max_f32_e32 v22, v22, v22
	v_max_f32_e32 v21, v21, v21
	v_max_f32_e32 v20, v20, v20
	v_max_f32_e32 v19, v19, v19
	v_max_f32_e32 v3, v3, v3
	v_max_f32_e32 v6, v6, v33
	v_max_f32_e32 v10, v10, v32
	v_max_f32_e32 v17, v17, v31
	v_max_f32_e32 v13, v13, v30
	v_max_f32_e32 v15, v15, v29
	v_max_f32_e32 v12, v12, v28
	v_max_f32_e32 v18, v18, v27
	v_max_f32_e32 v4, v4, v26
	v_max_f32_e32 v5, v5, v25
	v_max_f32_e32 v14, v14, v24
	v_max_f32_e32 v16, v16, v23
	v_max_f32_e32 v7, v7, v22
	v_max_f32_e32 v11, v11, v21
	v_max_f32_e32 v8, v8, v20
	v_max_f32_e32 v9, v9, v19
	v_max_f32_e32 v2, v2, v3
	v_max_f32_e32 v3, v6, v5
	v_min_f32_e32 v5, v6, v5
	v_max_f32_e32 v6, v10, v14
	v_min_f32_e32 v10, v10, v14
	v_max_f32_e32 v14, v17, v16
	v_min_f32_e32 v16, v17, v16
	v_max_f32_e32 v17, v13, v7
	v_min_f32_e32 v7, v13, v7
	v_max_f32_e32 v13, v15, v11
	v_min_f32_e32 v11, v15, v11
	v_max_f32_e32 v15, v12, v8
	v_min_f32_e32 v8, v12, v8
	v_max_f32_e32 v12, v18, v9
	v_min_f32_e32 v9, v18, v9
	v_max_f32_e32 v18, v4, v2
	v_min_f32_e32 v2, v4, v2
	v_max_f32_e32 v4, v3, v13
	v_min_f32_e32 v3, v3, v13
	v_max_f32_e32 v13, v6, v15
	v_min_f32_e32 v6, v6, v15
	v_max_f32_e32 v15, v14, v12
	v_min_f32_e32 v12, v14, v12
	v_max_f32_e32 v14, v17, v18
	v_min_f32_e32 v17, v17, v18
	v_max_f32_e32 v18, v5, v11
	v_min_f32_e32 v5, v5, v11
	v_max_f32_e32 v11, v10, v8
	v_min_f32_e32 v8, v10, v8
	v_max_f32_e32 v10, v16, v9
	v_min_f32_e32 v9, v16, v9
	v_max_f32_e32 v16, v7, v2
	v_min_f32_e32 v2, v7, v2
	v_max_f32_e32 v7, v4, v15
	v_min_f32_e32 v4, v4, v15
	v_max_f32_e32 v15, v13, v14
	v_max_f32_e32 v19, v3, v12
	v_min_f32_e32 v3, v3, v12
	v_max_f32_e32 v12, v6, v17
	v_min_f32_e32 v13, v13, v14
	v_min_f32_e32 v6, v6, v17
	v_max_f32_e32 v20, v18, v10
	v_max_f32_e32 v21, v11, v16
	v_min_f32_e32 v22, v11, v16
	v_max_f32_e32 v17, v7, v15
	v_max_f32_e32 v14, v19, v12
	v_min_f32_e32 v11, v19, v12
	v_lshlrev_b32_e32 v19, 7, v73
	v_min_f32_e32 v10, v18, v10
	v_max_f32_e32 v23, v5, v9
	v_min_f32_e32 v24, v5, v9
	v_max_f32_e32 v9, v8, v2
	v_min_f32_e32 v2, v8, v2
	v_min_f32_e32 v18, v7, v15
	v_max_f32_e32 v16, v4, v13
	v_min_f32_e32 v15, v4, v13
	v_max_f32_e32 v12, v3, v6
	v_min_f32_e32 v13, v3, v6
	v_max_f32_e32 v3, v20, v21
	v_min_f32_e32 v4, v20, v21
	v_and_b32_e32 v19, 0x3f80, v19
	v_and_b32_e32 v20, 0x7f, v17
	v_max_f32_e32 v5, v10, v22
	v_min_f32_e32 v6, v10, v22
	v_max_f32_e32 v7, v23, v9
	v_min_f32_e32 v8, v23, v9
	v_max_f32_e32 v9, v24, v2
	v_min_f32_e32 v10, v24, v2
	v_mad_i32_i24 v2, v70, -14, v71
	v_or_b32_e32 v21, v20, v19
	ds_write_b16 v2, v21 offset:1920
	v_and_b32_e32 v21, 0x7f, v18
	v_or_b32_e32 v22, v21, v19
	ds_write_b16 v2, v22 offset:1792
	v_and_b32_e32 v22, 0x7f, v16
	v_or_b32_e32 v23, v22, v19
	ds_write_b16 v2, v23 offset:1664
	v_and_b32_e32 v23, 0x7f, v15
	v_or_b32_e32 v24, v23, v19
	ds_write_b16 v2, v24 offset:1536
	v_and_b32_e32 v24, 0x7f, v14
	v_or_b32_e32 v25, v24, v19
	ds_write_b16 v2, v25 offset:1408
	v_and_b32_e32 v25, 0x7f, v11
	v_or_b32_e32 v26, v25, v19
	ds_write_b16 v2, v26 offset:1280
	v_and_b32_e32 v26, 0x7f, v12
	v_or_b32_e32 v27, v26, v19
	ds_write_b16 v2, v27 offset:1152
	v_and_b32_e32 v27, 0x7f, v13
	v_or_b32_e32 v28, v27, v19
	ds_write_b16 v2, v28 offset:1024
	v_and_or_b32 v28, v3, s7, v19
	ds_write_b16 v2, v28 offset:896
	v_and_or_b32 v28, v4, s7, v19
	ds_write_b16 v2, v28 offset:768
	v_and_or_b32 v28, v5, s7, v19
	ds_write_b16 v2, v28 offset:640
	v_and_or_b32 v28, v6, s7, v19
	ds_write_b16 v2, v28 offset:512
	v_and_or_b32 v28, v7, s7, v19
	ds_write_b16 v2, v28 offset:384
	v_and_or_b32 v28, v8, s7, v19
	ds_write_b16 v2, v28 offset:256
	v_and_or_b32 v28, v9, s7, v19
	v_and_or_b32 v19, v10, s7, v19
	ds_write_b16 v2, v19
	v_lshlrev_b32_e32 v19, 7, v74
	v_and_b32_e32 v19, 0x3f80, v19
	ds_write_b16 v2, v28 offset:128
	v_or_b32_e32 v28, v20, v19
	ds_write_b16 v2, v28 offset:2944
	v_or_b32_e32 v28, v21, v19
	ds_write_b16 v2, v28 offset:2816
	v_or_b32_e32 v28, v22, v19
	ds_write_b16 v2, v28 offset:2688
	v_or_b32_e32 v28, v23, v19
	v_or_b32_e32 v25, v25, v19
	ds_write_b16 v2, v28 offset:2560
	v_or_b32_e32 v28, v24, v19
	ds_write_b16 v2, v25 offset:2304
	v_or_b32_e32 v25, v26, v19
	v_or_b32_e32 v19, v27, v19
	ds_write_b16 v2, v19 offset:2048
	v_lshlrev_b32_e32 v19, 7, v76
	v_and_b32_e32 v19, 0x3f80, v19
	ds_write_b16 v2, v25 offset:2176
	v_or_b32_e32 v25, v20, v19
	ds_write_b16 v2, v25 offset:3072
	v_or_b32_e32 v25, v21, v19
	ds_write_b16 v2, v25 offset:3200
	v_or_b32_e32 v25, v22, v19
	ds_write_b16 v2, v25 offset:3328
	v_or_b32_e32 v25, v23, v19
	v_or_b32_e32 v19, v24, v19
	ds_write_b16 v2, v19 offset:3584
	v_lshlrev_b32_e32 v19, 7, v80
	v_and_b32_e32 v19, 0x3f80, v19
	v_or_b32_e32 v24, v20, v19
	ds_write_b16 v2, v24 offset:3712
	v_or_b32_e32 v24, v21, v19
	ds_write_b16 v2, v24 offset:3840
	v_or_b32_e32 v24, v22, v19
	v_or_b32_e32 v19, v23, v19
	ds_write_b16 v2, v19 offset:4096
	v_lshlrev_b32_e32 v19, 7, v84
	v_and_b32_e32 v19, 0x3f80, v19
	v_or_b32_e32 v23, v20, v19
	ds_write_b16 v2, v23 offset:4224
	v_or_b32_e32 v23, v21, v19
	v_or_b32_e32 v19, v22, v19
	ds_write_b16 v2, v19 offset:4480
	v_lshlrev_b32_e32 v19, 7, v86
	v_and_b32_e32 v19, 0x3f80, v19
	v_or_b32_e32 v22, v20, v19
	v_or_b32_e32 v19, v21, v19
	ds_write_b16 v2, v19 offset:4736
	v_lshlrev_b32_e32 v19, 7, v88
	v_and_b32_e32 v19, 0x3f80, v19
	ds_write_b16 v2, v22 offset:4608
	v_or_b32_e32 v22, v20, v19
	v_or_b32_e32 v19, v21, v19
	ds_write_b16 v2, v19 offset:4992
	v_lshlrev_b32_e32 v19, 7, v75
	v_and_b32_e32 v19, 0x3f80, v19
	ds_write_b16 v2, v22 offset:4864
	v_or_b32_e32 v22, v20, v19
	v_or_b32_e32 v19, v21, v19
	ds_write_b16 v2, v19 offset:5248
	v_lshlrev_b32_e32 v19, 7, v77
	v_and_or_b32 v19, v19, s6, v20
	ds_write_b16 v2, v19 offset:5376
	v_lshlrev_b32_e32 v19, 7, v78
	v_and_or_b32 v19, v19, s6, v20
	ds_write_b16 v2, v19 offset:5504
	v_lshlrev_b32_e32 v19, 7, v79
	v_and_or_b32 v19, v19, s6, v20
	ds_write_b16 v2, v19 offset:5632
	v_lshlrev_b32_e32 v19, 7, v81
	v_and_or_b32 v19, v19, s6, v20
	ds_write_b16 v2, v19 offset:5760
	v_lshlrev_b32_e32 v19, 7, v82
	v_and_or_b32 v19, v19, s6, v20
	ds_write_b16 v2, v19 offset:5888
	v_lshlrev_b32_e32 v19, 7, v83
	v_and_or_b32 v19, v19, s6, v20
	ds_write_b16 v2, v19 offset:6016
	v_lshlrev_b32_e32 v19, 7, v85
	v_and_or_b32 v19, v19, s6, v20
	ds_write_b16 v2, v19 offset:6144
	v_lshlrev_b32_e32 v19, 7, v87
	v_and_or_b32 v19, v19, s6, v20
	ds_write_b16 v2, v28 offset:2432
	ds_write_b16 v2, v25 offset:3456
	ds_write_b16 v2, v24 offset:3968
	ds_write_b16 v2, v23 offset:4352
	ds_write_b16 v2, v22 offset:5120
	ds_write_b16 v2, v19 offset:6272
	s_waitcnt lgkmcnt(0)
	s_and_saveexec_b64 s[0:1], vcc
	s_cbranch_execz .LBB0_809
; #define PEER_CAND(a, b, cid, dst) do { const float sum_ = __uint_as_float(T0[a] & ~127u) + __uint_as_float(T1[b] & ~127u); dst = (__float_as_uint(sum_) & ~63u) | (unsigned)(cid); \
;         tab[(cid) * 64] = (unsigned short)((T0[a] & 127u) * 128u + (T1[b] & 127u)); } while (0)
; __device__ __forceinline__ void select_wave_lds(const bf16* __restrict__ skf_h, char* qtile, int h, int* __restrict__ pidx, float* __restrict__ pgate, int wid, int lane) {
;     ...
; #pragma unroll
;     for (int b = 0; b < 16; ++b) PEER_CAND(0, b, 15 - b, C[b]);
; #pragma unroll
;     for (int b = 0; b < 16; ++b) { if (b < 8) PEER_CAND(1, b, 23 - b, R1[b]); else R1[b] = KEY_NEG_INF; }
;     {   int xi = 0;
; #pragma unroll
;         for (int a = 2; a < 16; ++a)
; #pragma unroll
;             for (int b = 0; b < 16; ++b) if ((a + 1) * (b + 1) <= 16) { PEER_CAND(a, b, 24 + xi, X[xi]); ++xi; }
; #pragma unroll
;         for (int q = 26; q < 32; ++q) X[q] = KEY_NEG_INF;
;     }
;     ...
;     merge_top16(C, R1);
;     {   unsigned X16[16], Xb[16];
; #pragma unroll
;         for (int q = 0; q < 16; ++q) { X16[q] = X[q]; Xb[q] = X[16 + q]; }
;         sort16_desc(X16); sort16_desc(Xb);
;         merge_top16(X16, Xb);
;         merge_top16(C, X16); }
	v_and_b32_e32 v19, 0xffffff80, v88
	v_and_b32_e32 v18, 0xffffff80, v18
	v_and_b32_e32 v17, 0xffffff80, v17
	v_and_b32_e32 v21, 0xffffff80, v86
	v_and_b32_e32 v23, 0xffffff80, v84
	v_and_b32_e32 v16, 0xffffff80, v16
	v_and_b32_e32 v28, 0xffffff80, v80
	v_and_b32_e32 v15, 0xffffff80, v15
	v_and_b32_e32 v36, 0xffffff80, v76
	v_and_b32_e32 v14, 0xffffff80, v14
	v_add_f32_e32 v20, v19, v18
	v_add_f32_e32 v19, v19, v17
	v_add_f32_e32 v22, v21, v18
	v_add_f32_e32 v21, v21, v17
	v_add_f32_e32 v24, v23, v16
	v_add_f32_e32 v25, v23, v18
	v_add_f32_e32 v23, v23, v17
	v_add_f32_e32 v29, v28, v15
	v_add_f32_e32 v31, v28, v16
	v_add_f32_e32 v33, v28, v18
	v_add_f32_e32 v28, v28, v17
	v_add_f32_e32 v37, v36, v14
	v_add_f32_e32 v39, v36, v15
	v_add_f32_e32 v41, v36, v16
	v_add_f32_e32 v44, v36, v18
	v_add_f32_e32 v36, v36, v17
	v_and_or_b32 v20, v20, s57, 39
	v_and_or_b32 v19, v19, s57, 38
	v_and_or_b32 v22, v22, s57, 37
	v_and_or_b32 v21, v21, s57, 36
	v_and_or_b32 v24, v24, s57, 35
	v_and_or_b32 v25, v25, s57, 34
	v_and_or_b32 v23, v23, s57, 33
	v_and_or_b32 v29, v29, s57, 32
	v_and_or_b32 v31, v31, s57, 31
	v_and_or_b32 v33, v33, s57, 30
	v_and_or_b32 v28, v28, s57, 29
	v_and_or_b32 v37, v37, s57, 28
	v_and_or_b32 v39, v39, s57, 27
	v_and_or_b32 v41, v41, s57, 26
	v_and_or_b32 v44, v44, s57, 25
	v_and_or_b32 v36, v36, s57, 24
	v_max_f32_e32 v22, v22, v22
	v_max_f32_e32 v36, v36, v36
	v_max_f32_e32 v33, v33, v33
	v_max_f32_e32 v28, v28, v28
	v_max_f32_e32 v21, v21, v21
	v_max_f32_e32 v44, v44, v44
	v_max_f32_e32 v24, v24, v24
	v_max_f32_e32 v31, v31, v31
	v_max_f32_e32 v20, v20, v20
	v_max_f32_e32 v41, v41, v41
	v_max_f32_e32 v25, v25, v25
	v_max_f32_e32 v23, v23, v23
	v_max_f32_e32 v19, v19, v19
	v_max_f32_e32 v39, v39, v39
	v_max_f32_e32 v29, v29, v29
	v_max_f32_e32 v37, v37, v37
	v_max_f32_e32 v59, v36, v22
	v_max_f32_e32 v60, v28, v33
	v_max_f32_e32 v62, v44, v21
	v_max_f32_e32 v63, v31, v24
	v_max_f32_e32 v66, v41, v20
	v_max_f32_e32 v67, v23, v25
	v_max_f32_e32 v69, v39, v19
	v_max_f32_e32 v71, v37, v29
	v_min_f32_e32 v23, v23, v25
	v_min_f32_e32 v20, v41, v20
	v_min_f32_e32 v24, v31, v24
	v_min_f32_e32 v21, v44, v21
	v_min_f32_e32 v28, v28, v33
	v_min_f32_e32 v22, v36, v22
	v_min_f32_e32 v29, v37, v29
	v_min_f32_e32 v19, v39, v19
	v_max_f32_e32 v61, v59, v60
	v_max_f32_e32 v64, v62, v63
	v_max_f32_e32 v72, v69, v71
	v_min_f32_e32 v69, v69, v71
	v_min_f32_e32 v59, v59, v60
	v_max_f32_e32 v25, v23, v20
	v_max_f32_e32 v31, v24, v21
	v_max_f32_e32 v33, v28, v22
	v_max_f32_e32 v36, v29, v19
	v_min_f32_e32 v39, v62, v63
	v_min_f32_e32 v62, v66, v67
	v_min_f32_e32 v21, v24, v21
	v_min_f32_e32 v22, v28, v22
	v_min_f32_e32 v19, v29, v19
	v_min_f32_e32 v20, v23, v20
	v_and_b32_e32 v26, 0xffffff80, v87
	v_and_b32_e32 v27, 0xffffff80, v85
	v_and_b32_e32 v30, 0xffffff80, v83
	v_and_b32_e32 v32, 0xffffff80, v82
	v_and_b32_e32 v34, 0xffffff80, v81
	v_and_b32_e32 v35, 0xffffff80, v79
	v_and_b32_e32 v38, 0xffffff80, v78
	v_and_b32_e32 v40, 0xffffff80, v77
	v_and_b32_e32 v42, 0xffffff80, v75
	v_max_f32_e32 v68, v66, v67
	v_min_f32_e32 v60, v69, v59
	v_min_f32_e32 v41, v25, v31
	v_max_f32_e32 v37, v33, v36
	v_min_f32_e32 v33, v33, v36
	v_min_f32_e32 v36, v39, v62
	v_min_f32_e32 v24, v21, v22
	v_min_f32_e32 v23, v19, v20
	v_max_f32_e32 v21, v21, v22
	v_max_f32_e32 v19, v19, v20
	v_add_f32_e32 v26, v26, v17
	v_add_f32_e32 v27, v27, v17
	v_add_f32_e32 v30, v30, v17
	v_add_f32_e32 v32, v32, v17
	v_add_f32_e32 v34, v34, v17
	v_add_f32_e32 v35, v35, v17
	v_add_f32_e32 v38, v38, v17
	v_add_f32_e32 v40, v40, v17
	v_add_f32_e32 v43, v42, v18
	v_add_f32_e32 v42, v42, v17
	v_max_f32_e32 v65, v61, v64
	v_max_f32_e32 v44, v60, v41
	v_max_f32_e32 v63, v39, v62
	v_max_f32_e32 v39, v33, v36
	v_max_f32_e32 v59, v69, v59
	v_max_f32_e32 v25, v25, v31
	v_min_f32_e32 v33, v33, v36
	v_min_f32_e32 v36, v60, v41
	v_max_f32_e32 v28, v24, v23
	v_min_f32_e32 v20, v21, v19
	v_min_f32_e32 v60, v61, v64
	v_min_f32_e32 v61, v68, v72
	v_and_or_b32 v26, v26, s57, 49
	v_and_or_b32 v27, v27, s57, 48
	v_and_or_b32 v30, v30, s57, 47
	v_and_or_b32 v32, v32, s57, 46
	v_and_or_b32 v34, v34, s57, 45
	v_and_or_b32 v35, v35, s57, 44
	v_and_or_b32 v38, v38, s57, 43
	v_and_or_b32 v40, v40, s57, 42
	v_and_or_b32 v43, v43, s57, 41
	v_and_or_b32 v42, v42, s57, 40
	v_min_f32_e32 v66, v37, v63
	v_min_f32_e32 v31, v59, v25
	v_max_f32_e32 v41, v33, v36
	v_max_f32_e32 v22, v28, v20
	v_min_f32_e32 v64, v60, v61
	v_max_f32_e32 v19, v21, v19
	v_max_f32_e32 v32, v32, v32
	v_max_f32_e32 v34, v34, v34
	v_max_f32_e32 v27, v27, v27
	v_max_f32_e32 v35, v35, v35
	v_min_f32_e32 v67, v44, v66
	v_min_f32_e32 v62, v39, v31
	v_max_f32_e32 v29, v41, v22
	v_min_f32_e32 v21, v64, v19
	v_max_f32_e32 v42, v42, v42
	v_max_f32_e32 v43, v43, v43
	v_max_f32_e32 v30, v30, v30
	v_max_f32_e32 v40, v40, v40
	v_max_f32_e32 v26, v26, v26
	v_max_f32_e32 v38, v38, v38
	v_and_b32_e32 v45, 0xffffff80, v74
	v_and_b32_e32 v53, 0xffffff80, v73
	v_max_f32_e32 v73, v68, v72
	v_min_f32_e32 v74, v34, v32
	v_min_f32_e32 v75, v35, v27
	v_max_f32_e32 v69, v67, v62
	v_max_f32_e32 v68, v29, v21
	v_max_f32_e32 v42, 0xff800000, v42
	v_max_f32_e32 v32, v34, v32
	v_max_f32_e32 v43, 0xff800000, v43
	v_max_f32_e32 v30, 0xff800000, v30
	v_max_f32_e32 v40, 0xff800000, v40
	v_max_f32_e32 v26, 0xff800000, v26
	v_max_f32_e32 v38, 0xff800000, v38
	v_max_f32_e32 v27, v35, v27
	v_max_f32_e32 v71, v69, v68
	v_min_f32_e32 v68, v69, v68
	v_max_f32_e32 v34, v42, v32
	v_max_f32_e32 v69, v43, v30
	v_max_f32_e32 v77, v40, v26
	v_max_f32_e32 v35, v38, v27
	v_min_f32_e32 v32, v42, v32
	v_max_f32_e32 v42, 0xff800000, v74
	v_max_f32_e32 v74, 0xff800000, v75
	v_min_f32_e32 v30, v43, v30
; __device__ __forceinline__ unsigned kmax(unsigned a, unsigned b) { return __float_as_uint(__builtin_fmaxf(__uint_as_float(a), __uint_as_float(b))); }
; __device__ __forceinline__ void sort16_desc(unsigned (&a)[16]) {
;     ...
;     PEER_CE(0, 13); PEER_CE(1, 12); PEER_CE(2, 15); PEER_CE(3, 14); PEER_CE(4, 8); PEER_CE(5, 6); PEER_CE(7, 11); PEER_CE(9, 10);
;     PEER_CE(0, 5); PEER_CE(1, 7); PEER_CE(2, 9); PEER_CE(3, 4); PEER_CE(6, 13); PEER_CE(8, 14); PEER_CE(10, 15); PEER_CE(11, 12);
;     PEER_CE(0, 1); PEER_CE(2, 3); PEER_CE(4, 5); PEER_CE(6, 8); PEER_CE(7, 9); PEER_CE(10, 11); PEER_CE(12, 13); PEER_CE(14, 15);
;     PEER_CE(0, 2); PEER_CE(1, 3); PEER_CE(4, 10); PEER_CE(5, 11); PEER_CE(6, 7); PEER_CE(8, 9); PEER_CE(12, 14); PEER_CE(13, 15);
;     PEER_CE(1, 2); PEER_CE(3, 12); PEER_CE(4, 6); PEER_CE(5, 7); PEER_CE(8, 10); PEER_CE(9, 11); PEER_CE(13, 14);
;     PEER_CE(1, 4); PEER_CE(2, 6); PEER_CE(5, 8); PEER_CE(7, 10); PEER_CE(9, 13); PEER_CE(11, 14);
;     PEER_CE(2, 4); PEER_CE(3, 6); PEER_CE(9, 12); PEER_CE(11, 13);
;     PEER_CE(3, 5); PEER_CE(6, 8); PEER_CE(7, 9); PEER_CE(10, 12);
;     PEER_CE(3, 4); PEER_CE(5, 6); PEER_CE(7, 8); PEER_CE(9, 10); PEER_CE(11, 12);
;     PEER_CE(6, 7); PEER_CE(8, 9);
;     ...
; }
; __device__ __forceinline__ void merge_top16(unsigned (&Lst)[16], const unsigned (&S)[16]) {
; #pragma unroll
;     for (int i = 0; i < 16; ++i) Lst[i] = kmax(Lst[i], S[15 - i]);
;     bitonic_merge_desc<16>(Lst);
; }
; __device__ __forceinline__ void select_wave_lds(const bf16* __restrict__ skf_h, char* qtile, int h, int* __restrict__ pidx, float* __restrict__ pgate, int wid, int lane) {
;     ...
; #pragma unroll
;     for (int b = 0; b < 16; ++b) PEER_CAND(0, b, 15 - b, C[b]);
; #pragma unroll
;     for (int b = 0; b < 16; ++b) { if (b < 8) PEER_CAND(1, b, 23 - b, R1[b]); else R1[b] = KEY_NEG_INF; }
;     {   int xi = 0;
; #pragma unroll
;         for (int a = 2; a < 16; ++a)
; #pragma unroll
;             for (int b = 0; b < 16; ++b) if ((a + 1) * (b + 1) <= 16) { PEER_CAND(a, b, 24 + xi, X[xi]); ++xi; }
; #pragma unroll
;         for (int q = 26; q < 32; ++q) X[q] = KEY_NEG_INF;
;     }
;     ...
;     merge_top16(C, R1);
;     {   unsigned X16[16], Xb[16];
; #pragma unroll
;         for (int q = 0; q < 16; ++q) { X16[q] = X[q]; Xb[q] = X[16 + q]; }
;         sort16_desc(X16); sort16_desc(Xb);
;         merge_top16(X16, Xb);
;         merge_top16(C, X16); }
	v_min_f32_e32 v26, v40, v26
	v_max3_f32 v76, v65, v73, s34
	v_max_f32_e32 v60, v60, v61
	v_min_f32_e32 v61, v65, v73
	v_min_f32_e32 v73, v34, v69
	v_min_f32_e32 v78, v77, v35
	v_max_f32_e32 v34, v34, v69
	v_max_f32_e32 v35, v77, v35
	v_min_f32_e32 v27, v38, v27
	v_max_f32_e32 v75, v42, v74
	v_max_f32_e32 v40, v30, v26
	v_min_f32_e32 v79, v73, v78
	v_max_f32_e32 v73, v73, v78
	v_min_f32_e32 v69, v34, v35
	v_max3_f32 v38, v27, v32, s34
	v_max_f32_e32 v43, v75, v40
	v_min_f32_e32 v27, v27, v32
	v_max_f32_e32 v25, v59, v25
	v_max_f32_e32 v37, v37, v63
	v_min_f32_e32 v77, v73, v69
	v_min_f32_e32 v78, v38, v43
	v_max_f32_e32 v27, 0xff800000, v27
	v_min_f32_e32 v32, v75, v40
	v_min_f32_e32 v42, v42, v74
	v_min_f32_e32 v26, v30, v26
	v_max_f32_e32 v19, v64, v19
	v_min_f32_e32 v64, v60, v61
	v_min_f32_e32 v59, v25, v37
	v_max_f32_e32 v79, 0xff800000, v79
	v_min_f32_e32 v80, v77, v78
	v_max_f32_e32 v40, v27, v32
	v_max3_f32 v30, v42, v26, s34
	v_min_f32_e32 v27, v27, v32
	v_min_f32_e32 v26, v42, v26
	v_min_f32_e32 v63, v64, v59
	v_max_f32_e32 v44, v44, v66
	v_max_f32_e32 v31, v39, v31
	v_max_f32_e32 v81, v79, v80
	v_max_f32_e32 v74, v40, v30
	v_min_f32_e32 v79, v79, v80
	v_min_f32_e32 v30, v40, v30
	v_max_f32_e32 v27, 0xff800000, v27
	v_max_f32_e32 v26, 0xff800000, v26
	v_and_b32_e32 v13, 0xffffff80, v13
	v_and_b32_e32 v12, 0xffffff80, v12
	v_and_b32_e32 v11, 0xffffff80, v11
	v_and_b32_e32 v10, 0xffffff80, v10
	v_and_b32_e32 v9, 0xffffff80, v9
	v_and_b32_e32 v8, 0xffffff80, v8
	v_and_b32_e32 v7, 0xffffff80, v7
	v_and_b32_e32 v6, 0xffffff80, v6
	v_and_b32_e32 v5, 0xffffff80, v5
	v_and_b32_e32 v4, 0xffffff80, v4
	v_and_b32_e32 v3, 0xffffff80, v3
	v_min_f32_e32 v65, v19, v63
	v_min_f32_e32 v39, v44, v31
	v_min_f32_e32 v62, v67, v62
	v_min_f32_e32 v21, v29, v21
	v_max_f32_e32 v40, v79, v30
	v_max_f32_e32 v32, v27, v26
	v_min_f32_e32 v30, v79, v30
	v_max_f32_e32 v19, v19, v63
	v_max_f32_e32 v31, v44, v31
	v_max_f32_e32 v60, v60, v61
	v_max_f32_e32 v25, v25, v37
	v_min_f32_e32 v33, v33, v36
	v_min_f32_e32 v20, v28, v20
	v_max_f32_e32 v69, v73, v69
	v_max_f32_e32 v38, v38, v43
	v_min_f32_e32 v26, v27, v26
	v_add_f32_e32 v46, v45, v13
	v_add_f32_e32 v47, v45, v12
	v_add_f32_e32 v48, v45, v11
	v_add_f32_e32 v49, v45, v14
	v_add_f32_e32 v50, v45, v15
	v_add_f32_e32 v51, v45, v16
	v_add_f32_e32 v52, v45, v18
	v_add_f32_e32 v45, v45, v17
	v_add_f32_e32 v10, v53, v10
	v_add_f32_e32 v9, v53, v9
	v_add_f32_e32 v8, v53, v8
	v_add_f32_e32 v7, v53, v7
	v_add_f32_e32 v6, v53, v6
	v_add_f32_e32 v5, v53, v5
	v_add_f32_e32 v4, v53, v4
	v_add_f32_e32 v3, v53, v3
	v_add_f32_e32 v13, v53, v13
	v_add_f32_e32 v12, v53, v12
	v_add_f32_e32 v11, v53, v11
	v_add_f32_e32 v14, v53, v14
	v_add_f32_e32 v15, v53, v15
	v_add_f32_e32 v16, v53, v16
	v_add_f32_e32 v18, v53, v18
	v_add_f32_e32 v17, v53, v17
	v_min_f32_e32 v66, v65, v39
	v_max_f32_e32 v29, v62, v21
	v_min_f32_e32 v75, v81, v74
	v_max_f32_e32 v42, v32, v30
	v_max_f32_e32 v44, v19, v31
	v_max_f32_e32 v59, v64, v59
	v_min_f32_e32 v37, v60, v25
	v_max_f32_e32 v28, v33, v20
	v_min_f32_e32 v22, v41, v22
	v_max_f32_e32 v64, v77, v78
	v_min_f32_e32 v43, v69, v38
	v_min_f32_e32 v19, v19, v31
	v_max_f32_e32 v31, v65, v39
	v_min_f32_e32 v30, v32, v30
	v_max_f32_e32 v26, 0xff800000, v26
	v_and_or_b32 v46, v46, s57, 16
	v_and_or_b32 v47, v47, s57, 17
	v_and_or_b32 v48, v48, s57, 18
	v_and_or_b32 v49, v49, s57, 19
	v_and_or_b32 v50, v50, s57, 20
	v_and_or_b32 v51, v51, s57, 21
	v_and_or_b32 v52, v52, s57, 22
	v_and_or_b32 v45, v45, s57, 23
	v_and_b32_e32 v10, 0xffffffc0, v10
	v_and_or_b32 v9, v9, s57, 1
	v_and_or_b32 v8, v8, s57, 2
	v_and_or_b32 v7, v7, s57, 3
	v_and_or_b32 v6, v6, s57, 4
	v_and_or_b32 v5, v5, s57, 5
	v_and_or_b32 v4, v4, s57, 6
	v_and_or_b32 v3, v3, s57, 7
	v_and_or_b32 v13, v13, s57, 8
	v_and_or_b32 v12, v12, s57, 9
	v_and_or_b32 v11, v11, s57, 10
	v_and_or_b32 v14, v14, s57, 11
	v_and_or_b32 v15, v15, s57, 12
	v_and_or_b32 v16, v16, s57, 13
	v_and_or_b32 v18, v18, s57, 14
	v_and_or_b32 v17, v17, s57, 15
	v_min_f32_e32 v72, v71, v66
	v_max_f32_e32 v67, v68, v29
	v_min_f32_e32 v80, v75, v40
	v_min_f32_e32 v61, v59, v37
	v_max_f32_e32 v36, v28, v22
	v_min_f32_e32 v21, v62, v21
	v_max_f32_e32 v62, v81, v74
	v_min_f32_e32 v73, v64, v43
	v_max3_f32 v37, v59, v37, s34
	v_min_f32_e32 v39, v19, v31
	v_max_f32_e32 v59, v71, v66
	v_min_f32_e32 v27, v30, v26
	v_min_f32_e32 v22, v28, v22
	v_max_f32_e32 v17, v17, v17
	v_max_f32_e32 v46, v46, v46
	v_max_f32_e32 v3, v3, v3
	v_max_f32_e32 v14, v14, v14
	v_max_f32_e32 v50, v50, v50
	v_max_f32_e32 v7, v7, v7
	v_max_f32_e32 v16, v16, v16
	v_max_f32_e32 v48, v48, v48
	v_max_f32_e32 v5, v5, v5
	v_max_f32_e32 v12, v12, v12
	v_max_f32_e32 v52, v52, v52
	v_max_f32_e32 v9, v9, v9
	v_max_f32_e32 v18, v18, v18
	v_max_f32_e32 v47, v47, v47
	v_max_f32_e32 v4, v4, v4
	v_max_f32_e32 v11, v11, v11
	v_max_f32_e32 v51, v51, v51
	v_max_f32_e32 v8, v8, v8
	v_max_f32_e32 v15, v15, v15
	v_max_f32_e32 v49, v49, v49
	v_max_f32_e32 v6, v6, v6
	v_max_f32_e32 v13, v13, v13
	v_max_f32_e32 v45, v45, v45
	v_max_f32_e32 v10, v10, v10
	v_min_f32_e32 v79, v80, v42
	v_min_f32_e32 v63, v44, v61
	v_min_f32_e32 v41, v36, v21
	v_min_f32_e32 v29, v68, v29
	v_max3_f32 v27, v39, v59, v27
	v_min_f32_e32 v20, v33, v20
	v_max3_f32 v25, v60, v25, s34
	v_min_f32_e32 v60, v72, v67
	v_max3_f32 v22, v22, v64, v43
	v_max3_f32 v43, v44, v61, s34
	v_min_f32_e32 v44, v62, v73
	v_min_f32_e32 v39, v39, v59
	v_min_f32_e32 v23, v24, v23
	v_max_f32_e32 v17, 0xff800000, v17
	v_max_f32_e32 v3, v3, v46
	v_max_f32_e32 v14, 0xff800000, v14
	v_max_f32_e32 v7, v7, v50
	v_max_f32_e32 v16, 0xff800000, v16
	v_max_f32_e32 v5, v5, v48
; __device__ __forceinline__ unsigned kmax(unsigned a, unsigned b) { return __float_as_uint(__builtin_fmaxf(__uint_as_float(a), __uint_as_float(b))); }
; __device__ __forceinline__ unsigned kmin(unsigned a, unsigned b) { return __float_as_uint(__builtin_fminf(__uint_as_float(a), __uint_as_float(b))); }
; template <int N> __device__ __forceinline__ void bitonic_merge_desc(unsigned (&a)[N]) {
; #pragma unroll
;     for (int j = N >> 1; j > 0; j >>= 1)
; #pragma unroll
;         for (int i = 0; i < N; ++i) { const int l = i ^ j;
;             if (l > i) { const unsigned mx = kmax(a[i], a[l]), mn = kmin(a[i], a[l]); a[i] = mx; a[l] = mn; } }
; }
; __device__ __forceinline__ void sort16_desc(unsigned (&a)[16]) {
;     ...
;     PEER_CE(0, 13); PEER_CE(1, 12); PEER_CE(2, 15); PEER_CE(3, 14); PEER_CE(4, 8); PEER_CE(5, 6); PEER_CE(7, 11); PEER_CE(9, 10);
;     PEER_CE(0, 5); PEER_CE(1, 7); PEER_CE(2, 9); PEER_CE(3, 4); PEER_CE(6, 13); PEER_CE(8, 14); PEER_CE(10, 15); PEER_CE(11, 12);
;     PEER_CE(0, 1); PEER_CE(2, 3); PEER_CE(4, 5); PEER_CE(6, 8); PEER_CE(7, 9); PEER_CE(10, 11); PEER_CE(12, 13); PEER_CE(14, 15);
;     PEER_CE(0, 2); PEER_CE(1, 3); PEER_CE(4, 10); PEER_CE(5, 11); PEER_CE(6, 7); PEER_CE(8, 9); PEER_CE(12, 14); PEER_CE(13, 15);
;     PEER_CE(1, 2); PEER_CE(3, 12); PEER_CE(4, 6); PEER_CE(5, 7); PEER_CE(8, 10); PEER_CE(9, 11); PEER_CE(13, 14);
;     PEER_CE(1, 4); PEER_CE(2, 6); PEER_CE(5, 8); PEER_CE(7, 10); PEER_CE(9, 13); PEER_CE(11, 14);
;     PEER_CE(2, 4); PEER_CE(3, 6); PEER_CE(9, 12); PEER_CE(11, 13);
;     PEER_CE(3, 5); PEER_CE(6, 8); PEER_CE(7, 9); PEER_CE(10, 12);
;     PEER_CE(3, 4); PEER_CE(5, 6); PEER_CE(7, 8); PEER_CE(9, 10); PEER_CE(11, 12);
;     PEER_CE(6, 7); PEER_CE(8, 9);
;     ...
; }
; __device__ __forceinline__ void merge_top16(unsigned (&Lst)[16], const unsigned (&S)[16]) {
; #pragma unroll
;     for (int i = 0; i < 16; ++i) Lst[i] = kmax(Lst[i], S[15 - i]);
;     bitonic_merge_desc<16>(Lst);
; }
; __device__ __forceinline__ void select_wave_lds(const bf16* __restrict__ skf_h, char* qtile, int h, int* __restrict__ pidx, float* __restrict__ pgate, int wid, int lane) {
;     ...
;     merge_top16(C, R1);
;     {   unsigned X16[16], Xb[16];
; #pragma unroll
;         for (int q = 0; q < 16; ++q) { X16[q] = X[q]; Xb[q] = X[16 + q]; }
;         sort16_desc(X16); sort16_desc(Xb);
;         merge_top16(X16, Xb);
;         merge_top16(C, X16); }
	v_max_f32_e32 v12, 0xff800000, v12
	v_max_f32_e32 v9, v9, v52
	v_max_f32_e32 v18, 0xff800000, v18
	v_max_f32_e32 v4, v4, v47
	v_max_f32_e32 v11, 0xff800000, v11
	v_max_f32_e32 v8, v8, v51
	v_max_f32_e32 v15, 0xff800000, v15
	v_max_f32_e32 v6, v6, v49
	v_max_f32_e32 v13, 0xff800000, v13
	v_max_f32_e32 v10, v10, v45
	v_max3_f32 v79, v72, v67, v79
	v_max_f32_e32 v63, 0xff800000, v63
	v_max3_f32 v41, v41, v62, v73
	v_max3_f32 v29, v29, v75, v40
	v_max3_f32 v20, v20, v69, v38
	v_max3_f32 v42, v60, v80, v42
	v_max3_f32 v19, v19, v31, s34
	v_max3_f32 v21, v36, v21, v44
	v_max3_f32 v26, v39, v30, v26
	v_max3_f32 v23, v23, v34, v35
	v_max_f32_e32 v46, v17, v3
	v_max_f32_e32 v50, v14, v7
	v_max_f32_e32 v48, v16, v5
	v_max_f32_e32 v52, v12, v9
	v_max_f32_e32 v47, v18, v4
	v_max_f32_e32 v51, v11, v8
	v_max_f32_e32 v49, v15, v6
	v_max_f32_e32 v45, v13, v10
	v_min_f32_e32 v40, v37, v29
	v_min_f32_e32 v32, v27, v20
	v_min_f32_e32 v60, v25, v42
	v_min_f32_e32 v28, v19, v22
	v_min_f32_e32 v36, v43, v21
	v_min_f32_e32 v24, v26, v23
	v_min_f32_e32 v3, v17, v3
	v_min_f32_e32 v7, v14, v7
	v_min_f32_e32 v5, v16, v5
	v_min_f32_e32 v9, v12, v9
	v_min_f32_e32 v4, v18, v4
	v_min_f32_e32 v8, v11, v8
	v_min_f32_e32 v6, v15, v6
	v_min_f32_e32 v10, v13, v10
	v_max_f32_e32 v17, v76, v79
	v_max_f32_e32 v18, v63, v41
	v_max_f32_e32 v29, v37, v29
	v_max_f32_e32 v20, v27, v20
	v_max_f32_e32 v25, v25, v42
	v_max_f32_e32 v19, v19, v22
	v_max_f32_e32 v21, v43, v21
	v_max_f32_e32 v23, v26, v23
	v_max_f32_e32 v14, v3, v7
	v_max_f32_e32 v12, v5, v9
	v_max_f32_e32 v11, v4, v8
	v_max_f32_e32 v13, v6, v10
	v_min_f32_e32 v39, v17, v18
	v_min_f32_e32 v27, v29, v20
	v_min_f32_e32 v22, v25, v19
	v_min_f32_e32 v26, v21, v23
	v_min_f32_e32 v5, v5, v9
	v_min_f32_e32 v6, v6, v10
	v_max_f32_e32 v9, v17, v18
	v_max_f32_e32 v10, v29, v20
	v_max_f32_e32 v18, v25, v19
	v_max_f32_e32 v19, v21, v23
	v_min_f32_e32 v82, v76, v79
	v_min_f32_e32 v74, v63, v41
	v_max_f32_e32 v16, v14, v12
	v_max_f32_e32 v15, v11, v13
	v_min_f32_e32 v37, v39, v27
	v_min_f32_e32 v41, v22, v26
	v_min_f32_e32 v3, v3, v7
	v_min_f32_e32 v4, v4, v8
	v_min_f32_e32 v17, v9, v10
	v_min_f32_e32 v20, v18, v19
	v_min_f32_e32 v12, v14, v12
	v_min_f32_e32 v11, v11, v13
	v_max_f32_e32 v13, v39, v27
	v_max_f32_e32 v14, v22, v26
	v_max_f32_e32 v53, v46, v50
	v_max_f32_e32 v54, v48, v52
	v_max_f32_e32 v56, v47, v51
	v_max_f32_e32 v57, v49, v45
	v_min_f32_e32 v77, v82, v74
	v_min_f32_e32 v33, v40, v32
	v_min_f32_e32 v31, v60, v28
	v_min_f32_e32 v30, v36, v24
	v_min_f32_e32 v42, v37, v41
	v_min_f32_e32 v44, v46, v50
	v_min_f32_e32 v46, v48, v52
	v_min_f32_e32 v47, v47, v51
	v_min_f32_e32 v45, v49, v45
	v_max_f32_e32 v50, v82, v74
	v_max_f32_e32 v32, v40, v32
	v_max_f32_e32 v28, v60, v28
	v_max_f32_e32 v24, v36, v24
	v_max_f32_e32 v7, v3, v5
	v_max_f32_e32 v8, v4, v6
	v_min_f32_e32 v21, v17, v20
	v_min_f32_e32 v22, v13, v14
	v_min_f32_e32 v3, v3, v5
	v_min_f32_e32 v4, v4, v6
	v_max_f32_e32 v5, v9, v10
	v_max_f32_e32 v6, v18, v19
	v_max_f32_e32 v55, v53, v54
	v_max_f32_e32 v58, v56, v57
	v_min_f32_e32 v38, v77, v33
	v_min_f32_e32 v34, v31, v30
	v_max3_f32 v42, v16, v15, v42
	v_max_f32_e32 v48, v44, v46
	v_max_f32_e32 v49, v47, v45
	v_min_f32_e32 v40, v50, v32
	v_min_f32_e32 v36, v28, v24
	v_max3_f32 v21, v7, v8, v21
	v_min_f32_e32 v29, v53, v54
	v_min_f32_e32 v52, v56, v57
	v_max_f32_e32 v33, v77, v33
	v_max_f32_e32 v30, v31, v30
	v_max3_f32 v22, v12, v11, v22
	v_min_f32_e32 v27, v44, v46
	v_min_f32_e32 v39, v47, v45
	v_max_f32_e32 v32, v50, v32
	v_max_f32_e32 v24, v28, v24
	v_min_f32_e32 v9, v5, v6
	v_min_f32_e32 v15, v16, v15
	v_min_f32_e32 v7, v7, v8
	v_min_f32_e32 v11, v12, v11
	v_min_f32_e32 v35, v38, v34
	v_min_f32_e32 v51, v40, v36
	v_min_f32_e32 v31, v33, v30
	v_min_f32_e32 v28, v32, v24
	v_max3_f32 v9, v3, v4, v9
	v_min_f32_e32 v44, v55, v58
	v_max3_f32 v15, v15, v37, v41
	v_min_f32_e32 v37, v48, v49
	v_max3_f32 v7, v7, v17, v20
	v_min_f32_e32 v20, v29, v52
	v_max3_f32 v11, v11, v13, v14
	v_min_f32_e32 v13, v27, v39
	v_min_f32_e32 v3, v3, v4
	v_max3_f32 v35, v55, v58, v35
	v_max3_f32 v51, v48, v49, v51
	v_max3_f32 v31, v29, v52, v31
	v_max3_f32 v28, v27, v39, v28
	v_max3_f32 v34, v44, v38, v34
	v_max3_f32 v36, v37, v40, v36
	v_max3_f32 v20, v20, v33, v30
	v_max3_f32 v13, v13, v32, v24
	v_max3_f32 v3, v3, v5, v6
	v_max_f32_e32 v43, v35, v42
	v_max_f32_e32 v23, v51, v21
	v_max_f32_e32 v26, v31, v22
	v_max_f32_e32 v10, v28, v9
	v_max_f32_e32 v16, v34, v15
	v_max_f32_e32 v8, v36, v7
	v_max_f32_e32 v12, v20, v11
	v_max_f32_e32 v4, v13, v3
	v_max_f32_e32 v25, v43, v23
	v_max_f32_e32 v18, v26, v10
	v_max_f32_e32 v17, v16, v8
	v_max_f32_e32 v5, v12, v4
	v_max_f32_e32 v19, v25, v18
	v_max_f32_e32 v6, v17, v5
	v_min_f32_e32 v18, v25, v18
	v_min_f32_e32 v5, v17, v5
	v_max_f32_e32 v17, v18, v5
	v_min_f32_e32 v18, v18, v5
	v_min_f32_e32 v5, v43, v23
	v_min_f32_e32 v10, v26, v10
	v_min_f32_e32 v8, v16, v8
	v_min_f32_e32 v4, v12, v4
	v_max_f32_e32 v23, v5, v10
	v_max_f32_e32 v12, v8, v4
	v_min_f32_e32 v5, v5, v10
	v_min_f32_e32 v4, v8, v4
	v_max_f32_e32 v32, v5, v4
	v_min_f32_e32 v33, v5, v4
	v_min_f32_e32 v4, v35, v42
	v_min_f32_e32 v5, v51, v21
	v_min_f32_e32 v10, v31, v22
	v_min_f32_e32 v9, v28, v9
	v_min_f32_e32 v15, v34, v15
	v_min_f32_e32 v7, v36, v7
	v_min_f32_e32 v11, v20, v11
	v_min_f32_e32 v3, v13, v3
	v_max_f32_e32 v16, v23, v12
	v_min_f32_e32 v12, v23, v12
	v_max_f32_e32 v8, v4, v5
	v_max_f32_e32 v21, v10, v9
	v_max_f32_e32 v23, v15, v7
	v_max_f32_e32 v13, v11, v3
	v_max_f32_e32 v14, v19, v6
	v_max_f32_e32 v22, v8, v21
	v_max_f32_e32 v20, v23, v13
	v_min_f32_e32 v8, v8, v21
	v_min_f32_e32 v13, v23, v13
	v_min_f32_e32 v4, v4, v5
; __device__ __forceinline__ void select_wave_lds(const bf16* __restrict__ skf_h, char* qtile, int h, int* __restrict__ pidx, float* __restrict__ pgate, int wid, int lane) {
;     ...
;     merge_top16(C, R1);
;     {   unsigned X16[16], Xb[16];
; #pragma unroll
;         for (int q = 0; q < 16; ++q) { X16[q] = X[q]; Xb[q] = X[16 + q]; }
;         sort16_desc(X16); sort16_desc(Xb);
;         merge_top16(X16, Xb);
;         merge_top16(C, X16); }
;     asm volatile("s_waitcnt lgkmcnt(0)" ::: "memory");
;     float v[16]; float sum = 0.f; const float mx = __uint_as_float(C[0] & ~63u);
; #pragma unroll
;     for (int s = 0; s < 16; ++s) { v[s] = __expf(__uint_as_float(C[s] & ~63u) - mx); sum += v[s]; }
;     const float inv = 1.f / sum;
;     int ex[16];
; #pragma unroll
;     for (int s = 0; s < 16; ++s) ex[s] = (int)tab[(C[s] & 63u) * 64];
;     if (hi == 0) {
;         int* pi = pidx + (size_t)(wid * 32 + r32) * 128 + h * 16; float* pg = pgate + (size_t)(wid * 32 + r32) * 128 + h * 16;
; #pragma unroll
;         for (int s = 0; s < 16; s += 4) { *(int4*)(pi + s) = make_int4(ex[s], ex[s + 1], ex[s + 2], ex[s + 3]); *(f32x4*)(pg + s) = (f32x4){v[s] * inv, v[s + 1] * inv, v[s + 2] * inv, v[s + 3] * inv}; }
;     }
	v_min_f32_e32 v5, v10, v9
	v_min_f32_e32 v7, v15, v7
	v_min_f32_e32 v3, v11, v3
	v_min_f32_e32 v19, v19, v6
	v_max_f32_e32 v28, v8, v13
	v_min_f32_e32 v8, v8, v13
	v_max_f32_e32 v9, v4, v5
	v_max_f32_e32 v10, v7, v3
	v_and_b32_e32 v13, 0xffffffc0, v14
	v_and_b32_e32 v6, 0xffffffc0, v19
	v_max_f32_e32 v11, v9, v10
	v_min_f32_e32 v9, v9, v10
	v_sub_f32_e32 v10, v13, v13
	v_mul_f32_e32 v10, 0x3fb8aa3b, v10
	v_sub_f32_e32 v6, v6, v13
	v_max_f32_e32 v30, v22, v20
	v_min_f32_e32 v31, v22, v20
	v_min_f32_e32 v4, v4, v5
	v_min_f32_e32 v3, v7, v3
	v_exp_f32_e32 v20, v10
	v_mul_f32_e32 v6, 0x3fb8aa3b, v6
	v_max_f32_e32 v5, v4, v3
	v_exp_f32_e32 v21, v6
	v_min_f32_e32 v3, v4, v3
	v_and_b32_e32 v4, 0xffffffc0, v3
	v_sub_f32_e32 v4, v4, v13
	v_and_b32_e32 v7, 0xffffffc0, v5
	v_add_f32_e32 v6, 0, v20
	v_mul_f32_e32 v4, 0x3fb8aa3b, v4
	v_add_f32_e32 v15, v21, v6
	v_sub_f32_e32 v6, v7, v13
	v_exp_f32_e32 v23, v4
	v_lshlrev_b32_e32 v4, 7, v5
	v_and_b32_e32 v5, 0xffffffc0, v11
	v_mul_f32_e32 v6, 0x3fb8aa3b, v6
	v_sub_f32_e32 v5, v5, v13
	v_exp_f32_e32 v22, v6
	v_and_b32_e32 v6, 0xffffffc0, v9
	v_mul_f32_e32 v5, 0x3fb8aa3b, v5
	v_exp_f32_e32 v24, v5
	v_sub_f32_e32 v5, v6, v13
	v_mul_f32_e32 v5, 0x3fb8aa3b, v5
	v_exp_f32_e32 v25, v5
	v_lshlrev_b32_e32 v5, 6, v11
	v_and_b32_e32 v5, 0xfc0, v5
	v_lshlrev_b32_e32 v6, 6, v9
	v_lshl_add_u32 v10, v5, 1, v2
	v_and_b32_e32 v5, 0xffffffc0, v28
	v_and_b32_e32 v6, 0xfc0, v6
	v_sub_f32_e32 v5, v5, v13
	v_lshl_add_u32 v9, v6, 1, v2
	v_and_b32_e32 v6, 0xffffffc0, v8
	v_mul_f32_e32 v5, 0x3fb8aa3b, v5
	v_exp_f32_e32 v26, v5
	v_sub_f32_e32 v5, v6, v13
	v_mul_f32_e32 v5, 0x3fb8aa3b, v5
	v_exp_f32_e32 v27, v5
	v_lshlrev_b32_e32 v5, 6, v28
	v_and_b32_e32 v5, 0xfc0, v5
	v_lshlrev_b32_e32 v6, 6, v8
	v_lshl_add_u32 v34, v5, 1, v2
	v_and_b32_e32 v5, 0xffffffc0, v30
	v_and_b32_e32 v6, 0xfc0, v6
	v_sub_f32_e32 v5, v5, v13
	v_lshl_add_u32 v8, v6, 1, v2
	v_and_b32_e32 v6, 0xffffffc0, v31
	v_mul_f32_e32 v5, 0x3fb8aa3b, v5
	v_exp_f32_e32 v28, v5
	v_sub_f32_e32 v5, v6, v13
	v_lshlrev_b32_e32 v3, 7, v3
	v_mul_f32_e32 v5, 0x3fb8aa3b, v5
	v_and_b32_e32 v3, 0x1f80, v3
	v_and_b32_e32 v4, 0x1f80, v4
	v_exp_f32_e32 v29, v5
	v_lshlrev_b32_e32 v5, 6, v30
	v_lshlrev_b32_e32 v6, 6, v31
	v_add_u32_e32 v3, v2, v3
	v_add_u32_e32 v4, v2, v4
	v_and_b32_e32 v5, 0xfc0, v5
	v_and_b32_e32 v6, 0xfc0, v6
	v_lshl_add_u32 v30, v6, 1, v2
	v_lshl_add_u32 v31, v5, 1, v2
	ds_read_u16 v7, v3
	ds_read_u16 v6, v4
	ds_read_u16 v5, v9
	ds_read_u16 v4, v10
	ds_read_u16 v11, v8
	ds_read_u16 v10, v34
	ds_read_u16 v9, v30
	ds_read_u16 v8, v31
	v_and_b32_e32 v3, 0xffffffc0, v32
	v_sub_f32_e32 v3, v3, v13
	v_and_b32_e32 v31, 0xffffffc0, v33
	v_mul_f32_e32 v3, 0x3fb8aa3b, v3
	v_exp_f32_e32 v30, v3
	v_sub_f32_e32 v3, v31, v13
	v_mul_f32_e32 v3, 0x3fb8aa3b, v3
	v_exp_f32_e32 v31, v3
	v_lshlrev_b32_e32 v3, 6, v32
	v_lshlrev_b32_e32 v32, 6, v33
	v_and_b32_e32 v32, 0xfc0, v32
	v_and_b32_e32 v34, 0xffffffc0, v17
	v_lshl_add_u32 v37, v32, 1, v2
	v_and_b32_e32 v32, 0xffffffc0, v16
	v_and_b32_e32 v33, 0xffffffc0, v12
	v_and_b32_e32 v35, 0xffffffc0, v18
	v_sub_f32_e32 v34, v34, v13
	v_sub_f32_e32 v32, v32, v13
	v_sub_f32_e32 v33, v33, v13
	v_mul_f32_e32 v34, 0x3fb8aa3b, v34
	v_sub_f32_e32 v13, v35, v13
	v_exp_f32_e32 v34, v34
	v_mul_f32_e32 v13, 0x3fb8aa3b, v13
	v_mul_f32_e32 v32, 0x3fb8aa3b, v32
	v_exp_f32_e32 v35, v13
	v_exp_f32_e32 v32, v32
	v_mul_f32_e32 v33, 0x3fb8aa3b, v33
	v_exp_f32_e32 v33, v33
	v_add_f32_e32 v15, v34, v15
	v_add_f32_e32 v15, v35, v15
	v_add_f32_e32 v15, v32, v15
	v_add_f32_e32 v15, v33, v15
	v_add_f32_e32 v15, v30, v15
	v_add_f32_e32 v15, v31, v15
	v_add_f32_e32 v15, v28, v15
	v_add_f32_e32 v15, v29, v15
	v_add_f32_e32 v15, v26, v15
	v_add_f32_e32 v15, v27, v15
	v_add_f32_e32 v15, v24, v15
	v_add_f32_e32 v15, v25, v15
	v_add_f32_e32 v15, v22, v15
	v_lshlrev_b32_e32 v16, 6, v16
	v_add_f32_e32 v15, v23, v15
	v_and_b32_e32 v13, 0xfc0, v16
	v_div_scale_f32 v16, s[40:41], v15, v15, 1.0
	v_rcp_f32_e32 v36, v16
	v_lshl_add_u32 v38, v13, 1, v2
	v_lshlrev_b32_e32 v12, 6, v12
	s_lshl_b64 s[36:37], s[24:25], 17
	v_fma_f32 v13, -v16, v36, 1.0
	v_fmac_f32_e32 v36, v13, v36
	v_div_scale_f32 v13, vcc, 1.0, v15, 1.0
	v_mul_f32_e32 v39, v13, v36
	v_fma_f32 v40, -v16, v39, v13
	v_fmac_f32_e32 v39, v40, v36
	v_fma_f32 v13, -v16, v39, v13
	v_div_fmas_f32 v13, v13, v36, v39
	v_div_fixup_f32 v36, v13, v15, 1.0
	v_lshlrev_b32_e32 v13, 6, v17
	v_and_b32_e32 v13, 0xfc0, v13
	v_lshl_add_u32 v17, v13, 1, v2
	v_lshlrev_b32_e32 v13, 7, v19
	v_and_b32_e32 v13, 0x1f80, v13
	v_lshlrev_b32_e32 v15, 6, v18
	v_add_u32_e32 v39, v2, v13
	v_lshlrev_b32_e32 v13, 7, v14
	v_readlane_b32 s3, v240, 26
	v_and_b32_e32 v3, 0xfc0, v3
	v_and_b32_e32 v12, 0xfc0, v12
	v_and_b32_e32 v15, 0xfc0, v15
	v_and_b32_e32 v13, 0x1f80, v13
	s_add_u32 s16, s3, s36
	v_readlane_b32 s3, v240, 27
	v_lshl_add_u32 v3, v3, 1, v2
	v_lshl_add_u32 v12, v12, 1, v2
	v_lshl_add_u32 v16, v15, 1, v2
	v_add_u32_e32 v2, v2, v13
	s_addc_u32 s17, s3, s37
	v_readlane_b32 s3, v240, 10
	ds_read_u16 v15, v37
	ds_read_u16 v14, v3
	ds_read_u16 v13, v12
	ds_read_u16 v12, v38
	ds_read_u16 v19, v16
	ds_read_u16 v18, v17
	ds_read_u16 v17, v39
	ds_read_u16 v16, v2
	v_lshl_or_b32 v2, s72, 5, v70
	s_add_u32 s36, s3, s36
	v_readlane_b32 s3, v240, 6
	v_ashrrev_i32_e32 v3, 31, v2
	s_addc_u32 s37, s3, s37
	v_lshlrev_b64 v[2:3], 9, v[2:3]
	v_lshl_add_u64 v[38:39], s[36:37], 0, v[2:3]
	s_lshl_b32 s36, s22, 4
	s_ashr_i32 s37, s36, 31
	s_lshl_b64 s[36:37], s[36:37], 2
	v_lshl_add_u64 v[38:39], v[38:39], 0, s[36:37]
	v_lshl_add_u64 v[2:3], s[16:17], 0, v[2:3]
	v_lshl_add_u64 v[40:41], v[2:3], 0, s[36:37]
	s_waitcnt lgkmcnt(0)
	global_store_dwordx4 v[38:39], v[16:19], off
	v_pk_mul_f32 v[2:3], v[24:25], v[36:37] op_sel_hi:[1,0]
	s_nop 0
	v_pk_mul_f32 v[18:19], v[34:35], v[36:37] op_sel_hi:[1,0]
	v_pk_mul_f32 v[16:17], v[20:21], v[36:37] op_sel_hi:[1,0]
	global_store_dwordx4 v[40:41], v[16:19], off
	global_store_dwordx4 v[38:39], v[12:15], off offset:16
	s_nop 1
	v_pk_mul_f32 v[14:15], v[30:31], v[36:37] op_sel_hi:[1,0]
	v_pk_mul_f32 v[12:13], v[32:33], v[36:37] op_sel_hi:[1,0]
	global_store_dwordx4 v[40:41], v[12:15], off offset:16
	global_store_dwordx4 v[38:39], v[8:11], off offset:32
	s_nop 1
	v_pk_mul_f32 v[10:11], v[26:27], v[36:37] op_sel_hi:[1,0]
	v_pk_mul_f32 v[8:9], v[28:29], v[36:37] op_sel_hi:[1,0]
	global_store_dwordx4 v[40:41], v[8:11], off offset:32
	global_store_dwordx4 v[38:39], v[4:7], off offset:48
	s_nop 1
	v_pk_mul_f32 v[4:5], v[22:23], v[36:37] op_sel_hi:[1,0]
	global_store_dwordx4 v[40:41], v[2:5], off offset:48
; __device__ __forceinline__ void quant_h2_wave(int t0w, int c, const bf16* __restrict__ x1a, const float* __restrict__ ssq, const float* __restrict__ mod,
;                                               unsigned char* __restrict__ HQ, float* __restrict__ HS, int lane) {
;     const int s = lane & 7, k0 = 256 * c + 32 * s;
; #pragma unroll
;     for (int pass = 0; pass < 2; ++pass) {
;         const int t = t0w + pass * 8 + (lane >> 3), b = t >> 11;
;         const f32x4 s0 = *(const f32x4*)(ssq + (size_t)t * 16), s1 = *(const f32x4*)(ssq + (size_t)t * 16 + 4), s2 = *(const f32x4*)(ssq + (size_t)t * 16 + 8), s3 = *(const f32x4*)(ssq + (size_t)t * 16 + 12);
;         const float tot = ((s0.x + s0.y) + (s0.z + s0.w)) + ((s1.x + s1.y) + (s1.z + s1.w)) + ((s2.x + s2.y) + (s2.z + s2.w)) + ((s3.x + s3.y) + (s3.z + s3.w));
;         const float rstd = rsqrtf(tot * (1.f / 1024.f) + 1e-6f);
;         const float* be = mod + (size_t)b * 6144 + 3 * 1024 + k0;
;         f32x4 hv[8]; float am = 0.f;
; #pragma unroll
;         for (int u = 0; u < 4; ++u) { const v4u xa = *(const v4u*)(x1a + (size_t)t * 1024 + k0 + 8 * u);
; #pragma unroll
;             for (int hh = 0; hh < 2; ++hh) { const unsigned w0 = xa[2 * hh], w1 = xa[2 * hh + 1];
;                 const f32x4 xv = {__builtin_bit_cast(float, w0 << 16), __builtin_bit_cast(float, w0 & 0xffff0000u), __builtin_bit_cast(float, w1 << 16), __builtin_bit_cast(float, w1 & 0xffff0000u)};
;                 const f32x4 h = xv * rstd + *(const f32x4*)(be + 8 * u + 4 * hh); hv[2 * u + hh] = h;
.LBB0_809:
	s_or_b64 exec, exec, s[0:1]
	s_lshl_b32 s0, s24, 8
	s_lshl_b32 s1, s22, 7
	s_and_b32 s1, s1, 0x80
	s_add_i32 s0, s0, s50
	s_add_i32 s3, s0, s1
	v_or_b32_e32 v30, s3, v1
	v_ashrrev_i32_e32 v31, 31, v30
	v_lshlrev_b64 v[2:3], 6, v[30:31]
	v_lshl_add_u64 v[14:15], s[8:9], 0, v[2:3]
	global_load_dwordx4 v[64:67], v[14:15], off offset:48
	global_load_dwordx4 v[60:63], v[14:15], off offset:32
	global_load_dwordx4 v[56:59], v[14:15], off offset:16
	global_load_dwordx4 v[52:55], v[14:15], off
	global_load_dwordx4 v[80:83], v[14:15], off offset:560
	global_load_dwordx4 v[76:79], v[14:15], off offset:544
	global_load_dwordx4 v[72:75], v[14:15], off offset:528
	global_load_dwordx4 v[68:71], v[14:15], off offset:512
	s_ashr_i32 s0, s22, 1
	v_lshl_or_b32 v18, s0, 8, v146
	s_ashr_i32 s1, s0, 31
	v_ashrrev_i32_e32 v19, 31, v18
	s_lshl_b64 s[16:17], s[0:1], 14
	s_ashr_i32 s0, s3, 11
	v_lshl_add_u64 v[28:29], v[18:19], 1, s[44:45]
	s_mul_hi_i32 s1, s0, 0x6000
	s_mulk_i32 s0, 0x6000
	s_add_u32 s0, s28, s0
	s_addc_u32 s1, s29, s1
	v_lshl_add_u64 v[18:19], v[18:19], 2, s[0:1]
	s_mov_b64 s[0:1], 0x3000
	v_lshl_add_u64 v[26:27], v[18:19], 0, s[0:1]
	v_lshlrev_b64 v[200:201], 11, v[30:31]
	v_lshl_add_u64 v[200:201], v[28:29], 0, v[200:201]
	s_mov_b64 s[40:41], 0x4000
	v_lshl_add_u64 v[202:203], v[200:201], 0, s[40:41]
	global_load_dwordx4 v[96:99], v[200:201], off offset:48
	global_load_dwordx4 v[92:95], v[200:201], off offset:32
	global_load_dwordx4 v[88:91], v[200:201], off offset:16
	global_load_dwordx4 v[84:87], v[200:201], off
	global_load_dwordx4 v[112:115], v[202:203], off offset:48
	global_load_dwordx4 v[108:111], v[202:203], off offset:32
	global_load_dwordx4 v[104:107], v[202:203], off offset:16
	global_load_dwordx4 v[100:103], v[202:203], off
	global_load_dwordx4 v[168:171], v[26:27], off
	global_load_dwordx4 v[172:175], v[26:27], off offset:16
	global_load_dwordx4 v[176:179], v[26:27], off offset:32
	global_load_dwordx4 v[180:183], v[26:27], off offset:48
	global_load_dwordx4 v[184:187], v[26:27], off offset:64
	global_load_dwordx4 v[188:191], v[26:27], off offset:80
	global_load_dwordx4 v[192:195], v[26:27], off offset:96
	global_load_dwordx4 v[196:199], v[26:27], off offset:112
	s_waitcnt vmcnt(0)
	v_mov_b32_e32 v2, v64
	v_mov_b32_e32 v3, v65
	v_mov_b32_e32 v4, v66
	v_mov_b32_e32 v5, v67
	v_mov_b32_e32 v6, v60
	v_mov_b32_e32 v7, v61
	v_mov_b32_e32 v8, v62
	v_mov_b32_e32 v9, v63
	v_mov_b32_e32 v10, v56
	v_mov_b32_e32 v11, v57
	v_mov_b32_e32 v12, v58
	v_mov_b32_e32 v13, v59
	v_mov_b32_e32 v14, v52
	v_mov_b32_e32 v15, v53
	v_mov_b32_e32 v16, v54
	v_mov_b32_e32 v17, v55
	s_waitcnt vmcnt(2)
	v_add_f32_e32 v6, v6, v7
	v_add_f32_e32 v8, v8, v9
	s_waitcnt vmcnt(0)
	v_mov_b32_e32 v20, v15
	v_mov_b32_e32 v21, v16
	v_mov_b32_e32 v15, v17
	v_mov_b32_e32 v16, v11
	v_mov_b32_e32 v17, v12
	v_mov_b32_e32 v11, v13
	v_pk_add_f32 v[14:15], v[20:21], v[14:15]
	v_pk_add_f32 v[10:11], v[16:17], v[10:11]
	v_pk_add_f32 v[14:15], v[14:15], v[14:15] op_sel:[0,1] op_sel_hi:[1,0]
	v_pk_add_f32 v[10:11], v[10:11], v[10:11] op_sel:[0,1] op_sel_hi:[1,0]
	v_mov_b32_e32 v15, v2
	v_mov_b32_e32 v11, v3
	v_mov_b32_e32 v7, v4
	v_mov_b32_e32 v9, v5
	v_pk_add_f32 v[2:3], v[14:15], v[10:11]
	v_pk_add_f32 v[4:5], v[6:7], v[8:9]
	s_nop 0
	v_pk_add_f32 v[2:3], v[2:3], v[4:5]
	s_nop 0
	v_add_f32_e32 v2, v2, v3
	v_fmamk_f32 v2, v2, 0x3a800000, v147
	v_cmp_gt_f32_e32 vcc, s59, v2
	v_mul_f32_e32 v3, 0x4b800000, v2
	s_nop 0
	v_cndmask_b32_e32 v2, v2, v3, vcc
	v_rsq_f32_e32 v2, v2
	s_nop 0
	v_mul_f32_e32 v3, 0x45800000, v2
	v_cndmask_b32_e32 v38, v2, v3, vcc
	v_lshlrev_b64 v[2:3], 11, v[30:31]
	v_lshl_add_u64 v[14:15], v[28:29], 0, v[2:3]
	v_mov_b32_e32 v2, v96
	v_mov_b32_e32 v3, v97
	v_mov_b32_e32 v4, v98
	v_mov_b32_e32 v5, v99
	v_mov_b32_e32 v6, v92
	v_mov_b32_e32 v7, v93
	v_mov_b32_e32 v8, v94
	v_mov_b32_e32 v9, v95
	v_mov_b32_e32 v10, v88
	v_mov_b32_e32 v11, v89
	v_mov_b32_e32 v12, v90
	v_mov_b32_e32 v13, v91
	s_nop 0
	v_mov_b32_e32 v14, v84
	v_mov_b32_e32 v15, v85
	v_mov_b32_e32 v16, v86
	v_mov_b32_e32 v17, v87
	v_add_co_u32_e32 v18, vcc, s19, v18
	s_waitcnt vmcnt(2)
	v_lshlrev_b32_e32 v50, 16, v6
	v_addc_co_u32_e32 v19, vcc, 0, v19, vcc
	v_mov_b32_e32 v18, v168
	v_mov_b32_e32 v19, v169
	v_mov_b32_e32 v20, v170
	v_mov_b32_e32 v21, v171
	s_nop 0
	v_mov_b32_e32 v22, v180
	v_mov_b32_e32 v23, v181
	v_mov_b32_e32 v24, v182
	v_mov_b32_e32 v25, v183
	v_mov_b32_e32 v32, v176
	v_mov_b32_e32 v33, v177
	v_mov_b32_e32 v34, v178
	v_mov_b32_e32 v35, v179
	v_mov_b32_e32 v40, v172
	v_mov_b32_e32 v41, v173
	v_mov_b32_e32 v42, v174
	v_mov_b32_e32 v43, v175
	s_waitcnt vmcnt(4)
	v_lshlrev_b32_e32 v36, 16, v14
	v_and_b32_e32 v37, 0xffff0000, v14
	v_lshlrev_b32_e32 v14, 16, v15
	v_and_b32_e32 v15, 0xffff0000, v15
	v_and_b32_e32 v51, 0xffff0000, v6
	v_lshlrev_b32_e32 v6, 16, v7
	v_and_b32_e32 v7, 0xffff0000, v7
	s_waitcnt vmcnt(3)
	v_pk_fma_f32 v[46:47], v[38:39], v[14:15], v[20:21] op_sel_hi:[0,1,1]
	v_pk_fma_f32 v[48:49], v[38:39], v[36:37], v[18:19] op_sel_hi:[0,1,1]
	v_max_f32_e64 v14, |v46|, |v47|
	v_max3_f32 v18, |v48|, |v49|, v14
	v_lshlrev_b32_e32 v14, 16, v16
	v_and_b32_e32 v15, 0xffff0000, v16
	v_lshlrev_b32_e32 v16, 16, v17
	v_and_b32_e32 v17, 0xffff0000, v17
	s_waitcnt vmcnt(0)
; __device__ __forceinline__ void quant_h2_wave(int t0w, int c, const bf16* __restrict__ x1a, const float* __restrict__ ssq, const float* __restrict__ mod,
;                                               unsigned char* __restrict__ HQ, float* __restrict__ HS, int lane) {
;     ...
;         for (int u = 0; u < 4; ++u) { const v4u xa = *(const v4u*)(x1a + (size_t)t * 1024 + k0 + 8 * u);
; #pragma unroll
;             for (int hh = 0; hh < 2; ++hh) { const unsigned w0 = xa[2 * hh], w1 = xa[2 * hh + 1];
;                 const f32x4 xv = {__builtin_bit_cast(float, w0 << 16), __builtin_bit_cast(float, w0 & 0xffff0000u), __builtin_bit_cast(float, w1 << 16), __builtin_bit_cast(float, w1 & 0xffff0000u)};
;                 const f32x4 h = xv * rstd + *(const f32x4*)(be + 8 * u + 4 * hh); hv[2 * u + hh] = h;
;                 am = fmaxf(am, fmaxf(fmaxf(fabsf(h.x), fabsf(h.y)), fmaxf(fabsf(h.z), fabsf(h.w)))); } }
;         am = max8_dpp(am);
;         const float sc = am > 0.f ? 119.f / am : 0.f;
;         v4u oa, ob;
; #pragma unroll
;         for (int k = 0; k < 4; ++k) { unsigned wa = 0u, wb = 0u;
; #pragma unroll
;             for (int i = 0; i < 8; ++i) { const float f = (i < 4) ? hv[2 * k][i] : hv[2 * k + 1][i - 4]; const int q = (int)rintf(f * sc); const int ahi = (q + 8) >> 4, blo = q - 16 * ahi;
;                 wa |= ((unsigned)ahi & 15u) << (4 * i); wb |= ((unsigned)blo & 15u) << (4 * i); }
;             oa[k] = wa; ob[k] = wb; }
	v_pk_fma_f32 v[42:43], v[38:39], v[16:17], v[42:43] op_sel_hi:[0,1,1]
	v_pk_fma_f32 v[44:45], v[38:39], v[14:15], v[40:41] op_sel_hi:[0,1,1]
	v_max_f32_e64 v14, |v42|, |v43|
	v_max3_f32 v14, |v44|, |v45|, v14
	v_max3_f32 v16, v18, 0, v14
	v_lshlrev_b32_e32 v14, 16, v10
	v_and_b32_e32 v15, 0xffff0000, v10
	v_lshlrev_b32_e32 v10, 16, v11
	v_and_b32_e32 v11, 0xffff0000, v11
	v_pk_fma_f32 v[36:37], v[38:39], v[10:11], v[34:35] op_sel_hi:[0,1,1]
	v_pk_fma_f32 v[40:41], v[38:39], v[14:15], v[32:33] op_sel_hi:[0,1,1]
	v_max_f32_e64 v10, |v36|, |v37|
	v_max3_f32 v14, |v40|, |v41|, v10
	v_lshlrev_b32_e32 v10, 16, v12
	v_and_b32_e32 v11, 0xffff0000, v12
	v_lshlrev_b32_e32 v12, 16, v13
	v_and_b32_e32 v13, 0xffff0000, v13
	v_pk_fma_f32 v[32:33], v[38:39], v[12:13], v[24:25] op_sel_hi:[0,1,1]
	v_pk_fma_f32 v[34:35], v[38:39], v[10:11], v[22:23] op_sel_hi:[0,1,1]
	v_max_f32_e64 v10, |v32|, |v33|
	v_max3_f32 v10, |v34|, |v35|, v10
	v_max3_f32 v39, v16, v14, v10
	v_mov_b32_e32 v10, v196
	v_mov_b32_e32 v11, v197
	v_mov_b32_e32 v12, v198
	v_mov_b32_e32 v13, v199
	v_mov_b32_e32 v14, v192
	v_mov_b32_e32 v15, v193
	v_mov_b32_e32 v16, v194
	v_mov_b32_e32 v17, v195
	v_mov_b32_e32 v18, v188
	v_mov_b32_e32 v19, v189
	v_mov_b32_e32 v20, v190
	v_mov_b32_e32 v21, v191
	v_mov_b32_e32 v22, v184
	v_mov_b32_e32 v23, v185
	v_mov_b32_e32 v24, v186
	v_mov_b32_e32 v25, v187
	s_waitcnt vmcnt(0)
	v_pk_fma_f32 v[24:25], v[38:39], v[6:7], v[24:25] op_sel_hi:[0,1,1]
	v_pk_fma_f32 v[22:23], v[38:39], v[50:51], v[22:23] op_sel_hi:[0,1,1]
	v_max_f32_e64 v6, |v24|, |v25|
	v_max3_f32 v50, |v22|, |v23|, v6
	v_lshlrev_b32_e32 v6, 16, v8
	v_and_b32_e32 v7, 0xffff0000, v8
	v_lshlrev_b32_e32 v8, 16, v9
	v_and_b32_e32 v9, 0xffff0000, v9
	v_pk_fma_f32 v[8:9], v[38:39], v[8:9], v[20:21] op_sel_hi:[0,1,1]
	v_pk_fma_f32 v[18:19], v[38:39], v[6:7], v[18:19] op_sel_hi:[0,1,1]
	v_max_f32_e64 v6, |v8|, |v9|
	v_max3_f32 v6, |v18|, |v19|, v6
	v_max3_f32 v20, v39, v50, v6
	v_lshlrev_b32_e32 v6, 16, v2
	v_and_b32_e32 v7, 0xffff0000, v2
	v_lshlrev_b32_e32 v2, 16, v3
	v_and_b32_e32 v3, 0xffff0000, v3
	v_pk_fma_f32 v[16:17], v[38:39], v[2:3], v[16:17] op_sel_hi:[0,1,1]
	v_pk_fma_f32 v[14:15], v[38:39], v[6:7], v[14:15] op_sel_hi:[0,1,1]
	v_max_f32_e64 v2, |v16|, |v17|
	v_max3_f32 v6, |v14|, |v15|, v2
	v_lshlrev_b32_e32 v2, 16, v4
	v_and_b32_e32 v3, 0xffff0000, v4
	v_lshlrev_b32_e32 v4, 16, v5
	v_and_b32_e32 v5, 0xffff0000, v5
	v_pk_fma_f32 v[12:13], v[38:39], v[4:5], v[12:13] op_sel_hi:[0,1,1]
	v_pk_fma_f32 v[10:11], v[38:39], v[2:3], v[10:11] op_sel_hi:[0,1,1]
	v_max_f32_e64 v2, |v12|, |v13|
	v_max3_f32 v2, |v10|, |v11|, v2
	v_max3_f32 v2, v20, v6, v2
	s_nop 1
	v_mov_b32_dpp v3, v2 quad_perm:[1,0,3,2] row_mask:0xf bank_mask:0xf bound_ctrl:1
	v_max_f32_e32 v3, v3, v3
	v_max_f32_e32 v2, v2, v3
	s_nop 1
	v_mov_b32_dpp v3, v2 quad_perm:[2,3,0,1] row_mask:0xf bank_mask:0xf bound_ctrl:1
	v_max_f32_e32 v3, v3, v3
	v_max_f32_e32 v2, v2, v3
	s_nop 1
	v_mov_b32_dpp v3, v2 row_half_mirror row_mask:0xf bank_mask:0xf bound_ctrl:1
	v_max_f32_e32 v3, v3, v3
	v_max_f32_e32 v20, v2, v3
	v_div_scale_f32 v2, s[36:37], v20, v20, s35
	v_rcp_f32_e32 v3, v2
	v_cmp_lt_f32_e64 s[0:1], 0, v20
	v_fma_f32 v4, -v2, v3, 1.0
	v_fmac_f32_e32 v3, v4, v3
	v_div_scale_f32 v4, vcc, s35, v20, s35
	v_mul_f32_e32 v5, v4, v3
	v_fma_f32 v6, -v2, v5, v4
	v_fmac_f32_e32 v5, v6, v3
	v_fma_f32 v2, -v2, v5, v4
	v_div_fmas_f32 v2, v2, v3, v5
	v_div_fixup_f32 v2, v2, v20, s35
	v_cndmask_b32_e64 v5, 0, v2, s[0:1]
	v_mul_f32_e32 v2, v48, v5
	v_rndne_f32_e32 v2, v2
	v_cvt_i32_f32_e32 v2, v2
	v_mul_f32_e32 v15, v15, v5
	v_rndne_f32_e32 v15, v15
	v_cvt_i32_f32_e32 v15, v15
	v_add_u32_e32 v3, 8, v2
	v_and_b32_e32 v4, 15, v2
	v_mul_f32_e32 v2, v49, v5
	v_rndne_f32_e32 v2, v2
	v_cvt_i32_f32_e32 v2, v2
	v_lshrrev_b32_e32 v3, 4, v3
	v_mul_f32_e32 v16, v16, v5
	v_mul_f32_e32 v17, v17, v5
	v_add_u32_e32 v6, 8, v2
	v_and_b32_e32 v6, 0xf0, v6
	v_lshlrev_b32_e32 v2, 4, v2
	v_and_or_b32 v3, v3, 15, v6
	v_and_b32_e32 v6, 0xf0, v2
	v_mul_f32_e32 v2, v46, v5
	v_rndne_f32_e32 v2, v2
	v_cvt_i32_f32_e32 v2, v2
	v_rndne_f32_e32 v16, v16
	v_rndne_f32_e32 v17, v17
	v_cvt_i32_f32_e32 v16, v16
	v_lshl_add_u32 v7, v2, 4, v161
	v_lshlrev_b32_e32 v2, 8, v2
	v_and_b32_e32 v21, 0xf00, v2
	v_mul_f32_e32 v2, v47, v5
	v_rndne_f32_e32 v2, v2
	v_cvt_i32_f32_e32 v2, v2
	v_and_b32_e32 v7, 0xf00, v7
	v_cvt_i32_f32_e32 v17, v17
	v_mul_f32_e32 v10, v10, v5
	v_lshl_add_u32 v38, v2, 8, v162
	v_and_b32_e32 v38, 0xf000, v38
	v_lshlrev_b32_e32 v2, 12, v2
	v_or3_b32 v3, v3, v7, v38
	v_and_b32_e32 v7, 0xf000, v2
	v_mul_f32_e32 v2, v44, v5
	v_rndne_f32_e32 v2, v2
	v_cvt_i32_f32_e32 v2, v2
	v_mul_f32_e32 v11, v11, v5
	v_rndne_f32_e32 v10, v10
	v_rndne_f32_e32 v11, v11
	v_lshl_add_u32 v38, v2, 12, v163
	v_lshlrev_b32_e32 v2, 16, v2
	v_and_b32_e32 v39, 0xf0000, v2
	v_mul_f32_e32 v2, v45, v5
	v_rndne_f32_e32 v2, v2
	v_cvt_i32_f32_e32 v2, v2
	v_and_b32_e32 v38, 0xf0000, v38
	v_mul_f32_e32 v12, v12, v5
	v_cvt_i32_f32_e32 v10, v10
	v_lshl_add_u32 v44, v2, 16, v164
	v_and_b32_e32 v44, 0xf00000, v44
	v_lshlrev_b32_e32 v2, 20, v2
	v_or3_b32 v3, v3, v38, v44
	v_and_b32_e32 v38, 0xf00000, v2
	v_mul_f32_e32 v2, v42, v5
	v_rndne_f32_e32 v2, v2
	v_cvt_i32_f32_e32 v2, v2
	v_cvt_i32_f32_e32 v11, v11
	v_rndne_f32_e32 v12, v12
	v_cvt_i32_f32_e32 v12, v12
	v_lshl_add_u32 v42, v2, 20, v165
	v_lshlrev_b32_e32 v2, 24, v2
	v_and_b32_e32 v44, 0xf000000, v2
	v_mul_f32_e32 v2, v43, v5
	v_rndne_f32_e32 v2, v2
	v_cvt_i32_f32_e32 v43, v2
	v_and_b32_e32 v42, 0xf000000, v42
	v_lshl_add_u32 v2, v43, 24, v166
	v_and_b32_e32 v2, 0xf0000000, v2
	v_or3_b32 v2, v3, v42, v2
	v_lshl_or_b32 v3, v43, 28, v4
	v_or3_b32 v3, v3, v6, v21
; __device__ __forceinline__ void quant_h2_wave(int t0w, int c, const bf16* __restrict__ x1a, const float* __restrict__ ssq, const float* __restrict__ mod,
;                                               unsigned char* __restrict__ HQ, float* __restrict__ HS, int lane) {
;     ...
;         const float sc = am > 0.f ? 119.f / am : 0.f;
;         v4u oa, ob;
; #pragma unroll
;         for (int k = 0; k < 4; ++k) { unsigned wa = 0u, wb = 0u;
; #pragma unroll
;             for (int i = 0; i < 8; ++i) { const float f = (i < 4) ? hv[2 * k][i] : hv[2 * k + 1][i - 4]; const int q = (int)rintf(f * sc); const int ahi = (q + 8) >> 4, blo = q - 16 * ahi;
;                 wa |= ((unsigned)ahi & 15u) << (4 * i); wb |= ((unsigned)blo & 15u) << (4 * i); }
;             oa[k] = wa; ob[k] = wb; }
;         unsigned char* dst = HQ + ((size_t)c * 16384 + t) * 256 + 32 * s;
;         *(v4u*)dst = oa; *(v4u*)(dst + 16) = ob;
;         if (s == 0) HS[(size_t)c * 16384 + t] = am * (1.f / 119.f);
	v_or3_b32 v3, v3, v7, v39
	v_or3_b32 v6, v3, v38, v44
	v_mul_f32_e32 v3, v40, v5
	v_rndne_f32_e32 v3, v3
	v_cvt_i32_f32_e32 v3, v3
	v_add_u32_e32 v4, 8, v3
	v_and_b32_e32 v7, 15, v3
	v_mul_f32_e32 v3, v41, v5
	v_rndne_f32_e32 v3, v3
	v_cvt_i32_f32_e32 v3, v3
	v_lshrrev_b32_e32 v4, 4, v4
	v_add_u32_e32 v21, 8, v3
	v_and_b32_e32 v21, 0xf0, v21
	v_lshlrev_b32_e32 v3, 4, v3
	v_and_or_b32 v4, v4, 15, v21
	v_and_b32_e32 v21, 0xf0, v3
	v_mul_f32_e32 v3, v36, v5
	v_rndne_f32_e32 v3, v3
	v_cvt_i32_f32_e32 v3, v3
	v_lshl_add_u32 v36, v3, 4, v161
	v_lshlrev_b32_e32 v3, 8, v3
	v_and_b32_e32 v38, 0xf00, v3
	v_mul_f32_e32 v3, v37, v5
	v_rndne_f32_e32 v3, v3
	v_cvt_i32_f32_e32 v3, v3
	v_and_b32_e32 v36, 0xf00, v36
	v_lshl_add_u32 v37, v3, 8, v162
	v_and_b32_e32 v37, 0xf000, v37
	v_lshlrev_b32_e32 v3, 12, v3
	v_or3_b32 v4, v4, v36, v37
	v_and_b32_e32 v36, 0xf000, v3
	v_mul_f32_e32 v3, v34, v5
	v_rndne_f32_e32 v3, v3
	v_cvt_i32_f32_e32 v3, v3
	v_lshl_add_u32 v34, v3, 12, v163
	v_lshlrev_b32_e32 v3, 16, v3
	v_and_b32_e32 v37, 0xf0000, v3
	v_mul_f32_e32 v3, v35, v5
	v_rndne_f32_e32 v3, v3
	v_cvt_i32_f32_e32 v3, v3
	v_and_b32_e32 v34, 0xf0000, v34
	v_lshl_add_u32 v35, v3, 16, v164
	v_and_b32_e32 v35, 0xf00000, v35
	v_lshlrev_b32_e32 v3, 20, v3
	v_or3_b32 v4, v4, v34, v35
	v_and_b32_e32 v34, 0xf00000, v3
	v_mul_f32_e32 v3, v32, v5
	v_rndne_f32_e32 v3, v3
	v_cvt_i32_f32_e32 v3, v3
	v_lshl_add_u32 v32, v3, 20, v165
	v_lshlrev_b32_e32 v3, 24, v3
	v_and_b32_e32 v35, 0xf000000, v3
	v_mul_f32_e32 v3, v33, v5
	v_rndne_f32_e32 v3, v3
	v_cvt_i32_f32_e32 v33, v3
	v_and_b32_e32 v32, 0xf000000, v32
	v_lshl_add_u32 v3, v33, 24, v166
	v_and_b32_e32 v3, 0xf0000000, v3
	v_or3_b32 v3, v4, v32, v3
	v_lshl_or_b32 v4, v33, 28, v7
	v_or3_b32 v4, v4, v21, v38
	v_or3_b32 v4, v4, v36, v37
	v_or3_b32 v7, v4, v34, v35
	v_mul_f32_e32 v4, v22, v5
	v_rndne_f32_e32 v4, v4
	v_cvt_i32_f32_e32 v4, v4
	v_add_u32_e32 v21, 8, v4
	v_and_b32_e32 v22, 15, v4
	v_mul_f32_e32 v4, v23, v5
	v_rndne_f32_e32 v4, v4
	v_cvt_i32_f32_e32 v4, v4
	v_lshrrev_b32_e32 v21, 4, v21
	v_add_u32_e32 v23, 8, v4
	v_and_b32_e32 v23, 0xf0, v23
	v_lshlrev_b32_e32 v4, 4, v4
	v_and_or_b32 v21, v21, 15, v23
	v_and_b32_e32 v23, 0xf0, v4
	v_mul_f32_e32 v4, v24, v5
	v_rndne_f32_e32 v4, v4
	v_cvt_i32_f32_e32 v4, v4
	v_lshl_add_u32 v24, v4, 4, v161
	v_lshlrev_b32_e32 v4, 8, v4
	v_and_b32_e32 v32, 0xf00, v4
	v_mul_f32_e32 v4, v25, v5
	v_rndne_f32_e32 v4, v4
	v_cvt_i32_f32_e32 v4, v4
	v_and_b32_e32 v24, 0xf00, v24
	v_lshl_add_u32 v25, v4, 8, v162
	v_and_b32_e32 v25, 0xf000, v25
	v_lshlrev_b32_e32 v4, 12, v4
	v_or3_b32 v21, v21, v24, v25
	v_and_b32_e32 v24, 0xf000, v4
	v_mul_f32_e32 v4, v18, v5
	v_rndne_f32_e32 v4, v4
	v_cvt_i32_f32_e32 v4, v4
	v_lshl_add_u32 v18, v4, 12, v163
	v_lshlrev_b32_e32 v4, 16, v4
	v_and_b32_e32 v25, 0xf0000, v4
	v_mul_f32_e32 v4, v19, v5
	v_rndne_f32_e32 v4, v4
	v_cvt_i32_f32_e32 v4, v4
	v_and_b32_e32 v18, 0xf0000, v18
	v_lshl_add_u32 v19, v4, 16, v164
	v_and_b32_e32 v19, 0xf00000, v19
	v_lshlrev_b32_e32 v4, 20, v4
	v_or3_b32 v18, v21, v18, v19
	v_and_b32_e32 v19, 0xf00000, v4
	v_mul_f32_e32 v4, v8, v5
	v_rndne_f32_e32 v4, v4
	v_cvt_i32_f32_e32 v4, v4
	v_lshl_add_u32 v8, v4, 20, v165
	v_lshlrev_b32_e32 v4, 24, v4
	v_and_b32_e32 v21, 0xf000000, v4
	v_mul_f32_e32 v4, v9, v5
	v_rndne_f32_e32 v4, v4
	v_cvt_i32_f32_e32 v9, v4
	v_and_b32_e32 v8, 0xf000000, v8
	v_lshl_add_u32 v4, v9, 24, v166
	v_and_b32_e32 v4, 0xf0000000, v4
	v_or3_b32 v4, v18, v8, v4
	v_lshl_or_b32 v8, v9, 28, v22
	v_mul_f32_e32 v9, v14, v5
	v_rndne_f32_e32 v9, v9
	v_cvt_i32_f32_e32 v9, v9
	v_mul_f32_e32 v5, v13, v5
	v_or3_b32 v8, v8, v23, v32
	v_add_u32_e32 v18, 8, v15
	v_add_u32_e32 v14, 8, v9
	v_rndne_f32_e32 v5, v5
	v_or3_b32 v8, v8, v24, v25
	v_lshrrev_b32_e32 v14, 4, v14
	v_and_b32_e32 v18, 0xf0, v18
	v_cvt_i32_f32_e32 v13, v5
	v_or3_b32 v8, v8, v19, v21
	v_and_or_b32 v14, v14, 15, v18
	v_lshl_add_u32 v18, v16, 4, v161
	v_lshl_add_u32 v19, v17, 8, v162
	v_and_b32_e32 v18, 0xf00, v18
	v_and_b32_e32 v19, 0xf000, v19
	v_and_b32_e32 v9, 15, v9
	v_lshlrev_b32_e32 v15, 4, v15
	v_lshlrev_b32_e32 v16, 8, v16
	v_or3_b32 v14, v14, v18, v19
	v_lshl_add_u32 v18, v10, 12, v163
	v_lshl_add_u32 v19, v11, 16, v164
	v_and_b32_e32 v15, 0xf0, v15
	v_and_b32_e32 v16, 0xf00, v16
	v_lshlrev_b32_e32 v17, 12, v17
	v_and_b32_e32 v18, 0xf0000, v18
	v_lshlrev_b32_e32 v10, 16, v10
	v_and_b32_e32 v19, 0xf00000, v19
	v_lshl_or_b32 v9, v13, 28, v9
	v_and_b32_e32 v17, 0xf000, v17
	v_and_b32_e32 v10, 0xf0000, v10
	v_or3_b32 v14, v14, v18, v19
	v_lshlrev_b32_e32 v11, 20, v11
	v_lshl_add_u32 v18, v12, 20, v165
	v_lshlrev_b32_e32 v12, 24, v12
	v_or3_b32 v9, v9, v15, v16
	v_and_b32_e32 v11, 0xf00000, v11
	v_and_b32_e32 v12, 0xf000000, v12
	v_or3_b32 v9, v9, v17, v10
	v_lshl_add_u32 v5, v13, 24, v166
	v_or3_b32 v9, v9, v11, v12
	v_lshl_add_u64 v[10:11], s[16:17], 0, v[30:31]
	v_and_b32_e32 v18, 0xf000000, v18
	v_and_b32_e32 v5, 0xf0000000, v5
	v_lshlrev_b64 v[12:13], 8, v[10:11]
	v_or3_b32 v5, v14, v18, v5
	v_lshl_add_u64 v[12:13], v[150:151], 0, v[12:13]
	global_store_dwordx4 v[12:13], v[2:5], off
	global_store_dwordx4 v[12:13], v[6:9], off offset:16
	s_and_saveexec_b64 s[0:1], s[4:5]
	s_cbranch_execz .LBB0_811
	v_mul_f32_e32 v4, 0x3c09ae41, v20
	v_lshl_add_u64 v[2:3], v[10:11], 2, s[10:11]
	global_store_dword v[2:3], v4, off
; __device__ __forceinline__ void quant_h2_wave(int t0w, int c, const bf16* __restrict__ x1a, const float* __restrict__ ssq, const float* __restrict__ mod,
;                                               unsigned char* __restrict__ HQ, float* __restrict__ HS, int lane) {
;     ...
;     for (int pass = 0; pass < 2; ++pass) {
;         const int t = t0w + pass * 8 + (lane >> 3), b = t >> 11;
;         const f32x4 s0 = *(const f32x4*)(ssq + (size_t)t * 16), s1 = *(const f32x4*)(ssq + (size_t)t * 16 + 4), s2 = *(const f32x4*)(ssq + (size_t)t * 16 + 8), s3 = *(const f32x4*)(ssq + (size_t)t * 16 + 12);
;         const float tot = ((s0.x + s0.y) + (s0.z + s0.w)) + ((s1.x + s1.y) + (s1.z + s1.w)) + ((s2.x + s2.y) + (s2.z + s2.w)) + ((s3.x + s3.y) + (s3.z + s3.w));
;         const float rstd = rsqrtf(tot * (1.f / 1024.f) + 1e-6f);
;         const float* be = mod + (size_t)b * 6144 + 3 * 1024 + k0;
;         f32x4 hv[8]; float am = 0.f;
; #pragma unroll
;         for (int u = 0; u < 4; ++u) { const v4u xa = *(const v4u*)(x1a + (size_t)t * 1024 + k0 + 8 * u);
; #pragma unroll
;             for (int hh = 0; hh < 2; ++hh) { const unsigned w0 = xa[2 * hh], w1 = xa[2 * hh + 1];
;                 const f32x4 xv = {__builtin_bit_cast(float, w0 << 16), __builtin_bit_cast(float, w0 & 0xffff0000u), __builtin_bit_cast(float, w1 << 16), __builtin_bit_cast(float, w1 & 0xffff0000u)};
;                 const f32x4 h = xv * rstd + *(const f32x4*)(be + 8 * u + 4 * hh); hv[2 * u + hh] = h;
;                 am = fmaxf(am, fmaxf(fmaxf(fabsf(h.x), fabsf(h.y)), fmaxf(fabsf(h.z), fabsf(h.w)))); } }
;         am = max8_dpp(am);
.LBB0_811:
	s_or_b64 exec, exec, s[0:1]
	v_or_b32_e32 v20, 8, v30
	v_ashrrev_i32_e32 v21, 31, v20
	v_lshlrev_b64 v[2:3], 6, v[20:21]
	v_lshl_add_u64 v[14:15], s[8:9], 0, v[2:3]
	v_mov_b32_e32 v2, v80
	v_mov_b32_e32 v3, v81
	v_mov_b32_e32 v4, v82
	v_mov_b32_e32 v5, v83
	v_mov_b32_e32 v6, v76
	v_mov_b32_e32 v7, v77
	v_mov_b32_e32 v8, v78
	v_mov_b32_e32 v9, v79
	v_mov_b32_e32 v10, v72
	v_mov_b32_e32 v11, v73
	v_mov_b32_e32 v12, v74
	v_mov_b32_e32 v13, v75
	s_nop 0
	v_mov_b32_e32 v14, v68
	v_mov_b32_e32 v15, v69
	v_mov_b32_e32 v16, v70
	v_mov_b32_e32 v17, v71
	s_waitcnt vmcnt(2)
	v_add_f32_e32 v6, v6, v7
	v_add_f32_e32 v8, v8, v9
	s_waitcnt vmcnt(0)
	v_mov_b32_e32 v18, v15
	v_mov_b32_e32 v19, v16
	v_mov_b32_e32 v15, v17
	v_mov_b32_e32 v16, v11
	v_mov_b32_e32 v17, v12
	v_mov_b32_e32 v11, v13
	v_pk_add_f32 v[14:15], v[18:19], v[14:15]
	v_pk_add_f32 v[10:11], v[16:17], v[10:11]
	v_pk_add_f32 v[14:15], v[14:15], v[14:15] op_sel:[0,1] op_sel_hi:[1,0]
	v_pk_add_f32 v[10:11], v[10:11], v[10:11] op_sel:[0,1] op_sel_hi:[1,0]
	v_mov_b32_e32 v15, v2
	v_mov_b32_e32 v11, v3
	v_mov_b32_e32 v7, v4
	v_mov_b32_e32 v9, v5
	v_pk_add_f32 v[2:3], v[14:15], v[10:11]
	v_pk_add_f32 v[4:5], v[6:7], v[8:9]
	s_nop 0
	v_pk_add_f32 v[2:3], v[2:3], v[4:5]
	s_nop 0
	v_add_f32_e32 v2, v2, v3
	v_fmamk_f32 v2, v2, 0x3a800000, v147
	v_cmp_gt_f32_e32 vcc, s59, v2
	v_mul_f32_e32 v3, 0x4b800000, v2
	s_nop 0
	v_cndmask_b32_e32 v2, v2, v3, vcc
	v_rsq_f32_e32 v2, v2
	s_nop 0
	v_mul_f32_e32 v3, 0x45800000, v2
	v_cndmask_b32_e32 v38, v2, v3, vcc
	v_lshlrev_b64 v[2:3], 11, v[20:21]
	v_lshl_add_u64 v[10:11], v[28:29], 0, v[2:3]
	v_mov_b32_e32 v2, v112
	v_mov_b32_e32 v3, v113
	v_mov_b32_e32 v4, v114
	v_mov_b32_e32 v5, v115
	v_mov_b32_e32 v12, v108
	v_mov_b32_e32 v13, v109
	v_mov_b32_e32 v14, v110
	v_mov_b32_e32 v15, v111
	v_mov_b32_e32 v6, v104
	v_mov_b32_e32 v7, v105
	v_mov_b32_e32 v8, v106
	v_mov_b32_e32 v9, v107
	v_mov_b32_e32 v16, v100
	v_mov_b32_e32 v17, v101
	v_mov_b32_e32 v18, v102
	v_mov_b32_e32 v19, v103
	v_mov_b32_e32 v46, v180
	v_mov_b32_e32 v47, v181
	v_mov_b32_e32 v48, v182
	v_mov_b32_e32 v49, v183
	v_mov_b32_e32 v22, v176
	v_mov_b32_e32 v23, v177
	v_mov_b32_e32 v24, v178
	v_mov_b32_e32 v25, v179
	v_mov_b32_e32 v28, v172
	v_mov_b32_e32 v29, v173
	v_mov_b32_e32 v30, v174
	v_mov_b32_e32 v31, v175
	v_mov_b32_e32 v32, v168
	v_mov_b32_e32 v33, v169
	v_mov_b32_e32 v34, v170
	v_mov_b32_e32 v35, v171
	s_waitcnt vmcnt(6)
	v_lshlrev_b32_e32 v36, 16, v13
	v_and_b32_e32 v37, 0xffff0000, v13
	s_waitcnt vmcnt(4)
	v_lshlrev_b32_e32 v10, 16, v16
	v_and_b32_e32 v11, 0xffff0000, v16
	v_lshlrev_b32_e32 v16, 16, v17
	v_and_b32_e32 v17, 0xffff0000, v17
	s_waitcnt vmcnt(0)
	v_pk_fma_f32 v[42:43], v[38:39], v[16:17], v[34:35] op_sel_hi:[0,1,1]
	v_pk_fma_f32 v[44:45], v[38:39], v[10:11], v[32:33] op_sel_hi:[0,1,1]
	v_max_f32_e64 v10, |v42|, |v43|
	v_lshlrev_b32_e32 v16, 16, v19
	v_and_b32_e32 v17, 0xffff0000, v19
	v_max3_f32 v32, |v44|, |v45|, v10
	v_lshlrev_b32_e32 v10, 16, v18
	v_and_b32_e32 v11, 0xffff0000, v18
	v_pk_fma_f32 v[34:35], v[38:39], v[16:17], v[30:31] op_sel_hi:[0,1,1]
	v_pk_fma_f32 v[40:41], v[38:39], v[10:11], v[28:29] op_sel_hi:[0,1,1]
	v_max_f32_e64 v10, |v34|, |v35|
	v_max3_f32 v10, |v40|, |v41|, v10
	v_max3_f32 v16, v32, 0, v10
	v_lshlrev_b32_e32 v10, 16, v6
	v_and_b32_e32 v11, 0xffff0000, v6
	v_lshlrev_b32_e32 v6, 16, v7
	v_and_b32_e32 v7, 0xffff0000, v7
	v_pk_fma_f32 v[28:29], v[38:39], v[6:7], v[24:25] op_sel_hi:[0,1,1]
	v_pk_fma_f32 v[32:33], v[38:39], v[10:11], v[22:23] op_sel_hi:[0,1,1]
	v_max_f32_e64 v6, |v28|, |v29|
	v_max3_f32 v10, |v32|, |v33|, v6
	v_lshlrev_b32_e32 v6, 16, v8
	v_and_b32_e32 v7, 0xffff0000, v8
	v_lshlrev_b32_e32 v8, 16, v9
	v_and_b32_e32 v9, 0xffff0000, v9
	v_pk_fma_f32 v[22:23], v[38:39], v[8:9], v[48:49] op_sel_hi:[0,1,1]
	v_pk_fma_f32 v[24:25], v[38:39], v[6:7], v[46:47] op_sel_hi:[0,1,1]
	v_max_f32_e64 v6, |v22|, |v23|
	v_max3_f32 v6, |v24|, |v25|, v6
	v_max3_f32 v39, v16, v10, v6
	v_lshlrev_b32_e32 v30, 16, v12
	v_and_b32_e32 v31, 0xffff0000, v12
	v_mov_b32_e32 v6, v196
	v_mov_b32_e32 v7, v197
	v_mov_b32_e32 v8, v198
	v_mov_b32_e32 v9, v199
	v_mov_b32_e32 v10, v192
	v_mov_b32_e32 v11, v193
	v_mov_b32_e32 v12, v194
	v_mov_b32_e32 v13, v195
	v_mov_b32_e32 v16, v188
	v_mov_b32_e32 v17, v189
	v_mov_b32_e32 v18, v190
	v_mov_b32_e32 v19, v191
	v_mov_b32_e32 v46, v184
	v_mov_b32_e32 v47, v185
	v_mov_b32_e32 v48, v186
	v_mov_b32_e32 v49, v187
	s_waitcnt vmcnt(0)
; __device__ __forceinline__ void quant_h2_wave(int t0w, int c, const bf16* __restrict__ x1a, const float* __restrict__ ssq, const float* __restrict__ mod,
;                                               unsigned char* __restrict__ HQ, float* __restrict__ HS, int lane) {
;     ...
;         f32x4 hv[8]; float am = 0.f;
; #pragma unroll
;         for (int u = 0; u < 4; ++u) { const v4u xa = *(const v4u*)(x1a + (size_t)t * 1024 + k0 + 8 * u);
; #pragma unroll
;             for (int hh = 0; hh < 2; ++hh) { const unsigned w0 = xa[2 * hh], w1 = xa[2 * hh + 1];
;                 const f32x4 xv = {__builtin_bit_cast(float, w0 << 16), __builtin_bit_cast(float, w0 & 0xffff0000u), __builtin_bit_cast(float, w1 << 16), __builtin_bit_cast(float, w1 & 0xffff0000u)};
;                 const f32x4 h = xv * rstd + *(const f32x4*)(be + 8 * u + 4 * hh); hv[2 * u + hh] = h;
;                 am = fmaxf(am, fmaxf(fmaxf(fabsf(h.x), fabsf(h.y)), fmaxf(fabsf(h.z), fabsf(h.w)))); } }
;         am = max8_dpp(am);
;         const float sc = am > 0.f ? 119.f / am : 0.f;
;         v4u oa, ob;
; #pragma unroll
;         for (int k = 0; k < 4; ++k) { unsigned wa = 0u, wb = 0u;
; #pragma unroll
;             for (int i = 0; i < 8; ++i) { const float f = (i < 4) ? hv[2 * k][i] : hv[2 * k + 1][i - 4]; const int q = (int)rintf(f * sc); const int ahi = (q + 8) >> 4, blo = q - 16 * ahi;
;                 wa |= ((unsigned)ahi & 15u) << (4 * i); wb |= ((unsigned)blo & 15u) << (4 * i); }
;             oa[k] = wa; ob[k] = wb; }
	v_pk_fma_f32 v[26:27], v[38:39], v[36:37], v[48:49] op_sel_hi:[0,1,1]
	v_pk_fma_f32 v[30:31], v[38:39], v[30:31], v[46:47] op_sel_hi:[0,1,1]
	v_max_f32_e64 v36, |v26|, |v27|
	v_max3_f32 v46, |v30|, |v31|, v36
	v_lshlrev_b32_e32 v36, 16, v14
	v_and_b32_e32 v37, 0xffff0000, v14
	v_lshlrev_b32_e32 v14, 16, v15
	v_and_b32_e32 v15, 0xffff0000, v15
	v_pk_fma_f32 v[14:15], v[38:39], v[14:15], v[18:19] op_sel_hi:[0,1,1]
	v_pk_fma_f32 v[16:17], v[38:39], v[36:37], v[16:17] op_sel_hi:[0,1,1]
	v_max_f32_e64 v18, |v14|, |v15|
	v_max3_f32 v18, |v16|, |v17|, v18
	v_max3_f32 v39, v39, v46, v18
	v_lshlrev_b32_e32 v18, 16, v2
	v_and_b32_e32 v19, 0xffff0000, v2
	v_lshlrev_b32_e32 v2, 16, v3
	v_and_b32_e32 v3, 0xffff0000, v3
	v_pk_fma_f32 v[12:13], v[38:39], v[2:3], v[12:13] op_sel_hi:[0,1,1]
	v_pk_fma_f32 v[36:37], v[38:39], v[18:19], v[10:11] op_sel_hi:[0,1,1]
	v_max_f32_e64 v2, |v12|, |v13|
	v_max3_f32 v46, |v36|, |v37|, v2
	v_lshlrev_b32_e32 v2, 16, v4
	v_and_b32_e32 v3, 0xffff0000, v4
	v_lshlrev_b32_e32 v4, 16, v5
	v_and_b32_e32 v5, 0xffff0000, v5
	v_pk_fma_f32 v[10:11], v[38:39], v[4:5], v[8:9] op_sel_hi:[0,1,1]
	v_pk_fma_f32 v[18:19], v[38:39], v[2:3], v[6:7] op_sel_hi:[0,1,1]
	v_max_f32_e64 v2, |v10|, |v11|
	v_max3_f32 v2, |v18|, |v19|, v2
	v_max3_f32 v2, v39, v46, v2
	s_nop 1
	v_mov_b32_dpp v3, v2 quad_perm:[1,0,3,2] row_mask:0xf bank_mask:0xf bound_ctrl:1
	v_max_f32_e32 v3, v3, v3
	v_max_f32_e32 v2, v2, v3
	s_nop 1
	v_mov_b32_dpp v3, v2 quad_perm:[2,3,0,1] row_mask:0xf bank_mask:0xf bound_ctrl:1
	v_max_f32_e32 v3, v3, v3
	v_max_f32_e32 v2, v2, v3
	s_nop 1
	v_mov_b32_dpp v3, v2 row_half_mirror row_mask:0xf bank_mask:0xf bound_ctrl:1
	v_max_f32_e32 v3, v3, v3
	v_max_f32_e32 v38, v2, v3
	v_div_scale_f32 v2, s[36:37], v38, v38, s35
	v_rcp_f32_e32 v3, v2
	v_cmp_lt_f32_e64 s[0:1], 0, v38
	v_fma_f32 v4, -v2, v3, 1.0
	v_fmac_f32_e32 v3, v4, v3
	v_div_scale_f32 v4, vcc, s35, v38, s35
	v_mul_f32_e32 v5, v4, v3
	v_fma_f32 v6, -v2, v5, v4
	v_fmac_f32_e32 v5, v6, v3
	v_fma_f32 v2, -v2, v5, v4
	v_div_fmas_f32 v2, v2, v3, v5
	v_div_fixup_f32 v2, v2, v38, s35
	v_cndmask_b32_e64 v5, 0, v2, s[0:1]
	v_mul_f32_e32 v2, v44, v5
	v_rndne_f32_e32 v2, v2
	v_cvt_i32_f32_e32 v2, v2
	v_mul_f32_e32 v12, v12, v5
	v_mul_f32_e32 v13, v13, v5
	v_rndne_f32_e32 v12, v12
	v_add_u32_e32 v3, 8, v2
	v_and_b32_e32 v4, 15, v2
	v_mul_f32_e32 v2, v45, v5
	v_rndne_f32_e32 v2, v2
	v_cvt_i32_f32_e32 v2, v2
	v_lshrrev_b32_e32 v3, 4, v3
	v_rndne_f32_e32 v13, v13
	v_cvt_i32_f32_e32 v12, v12
	v_add_u32_e32 v6, 8, v2
	v_and_b32_e32 v6, 0xf0, v6
	v_lshlrev_b32_e32 v2, 4, v2
	v_and_or_b32 v3, v3, 15, v6
	v_and_b32_e32 v6, 0xf0, v2
	v_mul_f32_e32 v2, v42, v5
	v_rndne_f32_e32 v2, v2
	v_cvt_i32_f32_e32 v2, v2
	v_cvt_i32_f32_e32 v13, v13
	v_mul_f32_e32 v10, v10, v5
	v_rndne_f32_e32 v10, v10
	v_lshl_add_u32 v7, v2, 4, v161
	v_lshlrev_b32_e32 v2, 8, v2
	v_and_b32_e32 v8, 0xf00, v2
	v_mul_f32_e32 v2, v43, v5
	v_rndne_f32_e32 v2, v2
	v_cvt_i32_f32_e32 v2, v2
	v_and_b32_e32 v7, 0xf00, v7
	v_cvt_i32_f32_e32 v10, v10
	v_lshl_add_u32 v9, v2, 8, v162
	v_and_b32_e32 v9, 0xf000, v9
	v_lshlrev_b32_e32 v2, 12, v2
	v_or3_b32 v3, v3, v7, v9
	v_and_b32_e32 v7, 0xf000, v2
	v_mul_f32_e32 v2, v40, v5
	v_rndne_f32_e32 v2, v2
	v_cvt_i32_f32_e32 v2, v2
	v_lshl_add_u32 v9, v2, 12, v163
	v_lshlrev_b32_e32 v2, 16, v2
	v_and_b32_e32 v39, 0xf0000, v2
	v_mul_f32_e32 v2, v41, v5
	v_rndne_f32_e32 v2, v2
	v_cvt_i32_f32_e32 v2, v2
	v_and_b32_e32 v9, 0xf0000, v9
	v_lshl_add_u32 v40, v2, 16, v164
	v_and_b32_e32 v40, 0xf00000, v40
	v_lshlrev_b32_e32 v2, 20, v2
	v_or3_b32 v3, v3, v9, v40
	v_and_b32_e32 v9, 0xf00000, v2
	v_mul_f32_e32 v2, v34, v5
	v_rndne_f32_e32 v2, v2
	v_cvt_i32_f32_e32 v2, v2
	v_lshl_add_u32 v34, v2, 20, v165
	v_lshlrev_b32_e32 v2, 24, v2
	v_and_b32_e32 v40, 0xf000000, v2
	v_mul_f32_e32 v2, v35, v5
	v_rndne_f32_e32 v2, v2
	v_cvt_i32_f32_e32 v35, v2
	v_and_b32_e32 v34, 0xf000000, v34
	v_lshl_add_u32 v2, v35, 24, v166
	v_and_b32_e32 v2, 0xf0000000, v2
	v_or3_b32 v2, v3, v34, v2
	v_lshl_or_b32 v3, v35, 28, v4
	v_or3_b32 v3, v3, v6, v8
	v_or3_b32 v3, v3, v7, v39
	v_or3_b32 v6, v3, v9, v40
	v_mul_f32_e32 v3, v32, v5
	v_rndne_f32_e32 v3, v3
	v_cvt_i32_f32_e32 v3, v3
	v_add_u32_e32 v4, 8, v3
	v_and_b32_e32 v7, 15, v3
	v_mul_f32_e32 v3, v33, v5
	v_rndne_f32_e32 v3, v3
	v_cvt_i32_f32_e32 v3, v3
	v_lshrrev_b32_e32 v4, 4, v4
	v_add_u32_e32 v8, 8, v3
	v_and_b32_e32 v8, 0xf0, v8
	v_lshlrev_b32_e32 v3, 4, v3
	v_and_or_b32 v4, v4, 15, v8
	v_and_b32_e32 v8, 0xf0, v3
	v_mul_f32_e32 v3, v28, v5
	v_rndne_f32_e32 v3, v3
	v_cvt_i32_f32_e32 v3, v3
	v_lshl_add_u32 v9, v3, 4, v161
	v_lshlrev_b32_e32 v3, 8, v3
	v_and_b32_e32 v28, 0xf00, v3
	v_mul_f32_e32 v3, v29, v5
	v_rndne_f32_e32 v3, v3
	v_cvt_i32_f32_e32 v3, v3
	v_and_b32_e32 v9, 0xf00, v9
	v_lshl_add_u32 v29, v3, 8, v162
	v_and_b32_e32 v29, 0xf000, v29
; __device__ __forceinline__ void quant_h2_wave(int t0w, int c, const bf16* __restrict__ x1a, const float* __restrict__ ssq, const float* __restrict__ mod,
;                                               unsigned char* __restrict__ HQ, float* __restrict__ HS, int lane) {
;     ...
;         for (int k = 0; k < 4; ++k) { unsigned wa = 0u, wb = 0u;
; #pragma unroll
;             for (int i = 0; i < 8; ++i) { const float f = (i < 4) ? hv[2 * k][i] : hv[2 * k + 1][i - 4]; const int q = (int)rintf(f * sc); const int ahi = (q + 8) >> 4, blo = q - 16 * ahi;
;                 wa |= ((unsigned)ahi & 15u) << (4 * i); wb |= ((unsigned)blo & 15u) << (4 * i); }
;             oa[k] = wa; ob[k] = wb; }
;         unsigned char* dst = HQ + ((size_t)c * 16384 + t) * 256 + 32 * s;
;         *(v4u*)dst = oa; *(v4u*)(dst + 16) = ob;
;         if (s == 0) HS[(size_t)c * 16384 + t] = am * (1.f / 119.f);
	v_lshlrev_b32_e32 v3, 12, v3
	v_or3_b32 v4, v4, v9, v29
	v_and_b32_e32 v9, 0xf000, v3
	v_mul_f32_e32 v3, v24, v5
	v_rndne_f32_e32 v3, v3
	v_cvt_i32_f32_e32 v3, v3
	v_lshl_add_u32 v24, v3, 12, v163
	v_lshlrev_b32_e32 v3, 16, v3
	v_and_b32_e32 v29, 0xf0000, v3
	v_mul_f32_e32 v3, v25, v5
	v_rndne_f32_e32 v3, v3
	v_cvt_i32_f32_e32 v3, v3
	v_and_b32_e32 v24, 0xf0000, v24
	v_lshl_add_u32 v25, v3, 16, v164
	v_and_b32_e32 v25, 0xf00000, v25
	v_lshlrev_b32_e32 v3, 20, v3
	v_or3_b32 v4, v4, v24, v25
	v_and_b32_e32 v24, 0xf00000, v3
	v_mul_f32_e32 v3, v22, v5
	v_rndne_f32_e32 v3, v3
	v_cvt_i32_f32_e32 v3, v3
	v_lshl_add_u32 v22, v3, 20, v165
	v_lshlrev_b32_e32 v3, 24, v3
	v_and_b32_e32 v25, 0xf000000, v3
	v_mul_f32_e32 v3, v23, v5
	v_rndne_f32_e32 v3, v3
	v_cvt_i32_f32_e32 v23, v3
	v_and_b32_e32 v22, 0xf000000, v22
	v_lshl_add_u32 v3, v23, 24, v166
	v_and_b32_e32 v3, 0xf0000000, v3
	v_or3_b32 v3, v4, v22, v3
	v_lshl_or_b32 v4, v23, 28, v7
	v_or3_b32 v4, v4, v8, v28
	v_or3_b32 v4, v4, v9, v29
	v_or3_b32 v7, v4, v24, v25
	v_mul_f32_e32 v4, v30, v5
	v_rndne_f32_e32 v4, v4
	v_cvt_i32_f32_e32 v4, v4
	v_add_u32_e32 v8, 8, v4
	v_and_b32_e32 v9, 15, v4
	v_mul_f32_e32 v4, v31, v5
	v_rndne_f32_e32 v4, v4
	v_cvt_i32_f32_e32 v4, v4
	v_lshrrev_b32_e32 v8, 4, v8
	v_add_u32_e32 v22, 8, v4
	v_and_b32_e32 v22, 0xf0, v22
	v_lshlrev_b32_e32 v4, 4, v4
	v_and_or_b32 v8, v8, 15, v22
	v_and_b32_e32 v22, 0xf0, v4
	v_mul_f32_e32 v4, v26, v5
	v_rndne_f32_e32 v4, v4
	v_cvt_i32_f32_e32 v4, v4
	v_lshl_add_u32 v23, v4, 4, v161
	v_lshlrev_b32_e32 v4, 8, v4
	v_and_b32_e32 v24, 0xf00, v4
	v_mul_f32_e32 v4, v27, v5
	v_rndne_f32_e32 v4, v4
	v_cvt_i32_f32_e32 v4, v4
	v_and_b32_e32 v23, 0xf00, v23
	v_lshl_add_u32 v25, v4, 8, v162
	v_and_b32_e32 v25, 0xf000, v25
	v_lshlrev_b32_e32 v4, 12, v4
	v_or3_b32 v8, v8, v23, v25
	v_and_b32_e32 v23, 0xf000, v4
	v_mul_f32_e32 v4, v16, v5
	v_rndne_f32_e32 v4, v4
	v_cvt_i32_f32_e32 v4, v4
	v_lshl_add_u32 v16, v4, 12, v163
	v_lshlrev_b32_e32 v4, 16, v4
	v_and_b32_e32 v25, 0xf0000, v4
	v_mul_f32_e32 v4, v17, v5
	v_rndne_f32_e32 v4, v4
	v_cvt_i32_f32_e32 v4, v4
	v_and_b32_e32 v16, 0xf0000, v16
	v_lshl_add_u32 v17, v4, 16, v164
	v_and_b32_e32 v17, 0xf00000, v17
	v_lshlrev_b32_e32 v4, 20, v4
	v_or3_b32 v8, v8, v16, v17
	v_and_b32_e32 v16, 0xf00000, v4
	v_mul_f32_e32 v4, v14, v5
	v_rndne_f32_e32 v4, v4
	v_cvt_i32_f32_e32 v4, v4
	v_lshl_add_u32 v14, v4, 20, v165
	v_lshlrev_b32_e32 v4, 24, v4
	v_and_b32_e32 v17, 0xf000000, v4
	v_mul_f32_e32 v4, v15, v5
	v_rndne_f32_e32 v4, v4
	v_cvt_i32_f32_e32 v15, v4
	v_and_b32_e32 v14, 0xf000000, v14
	v_lshl_add_u32 v4, v15, 24, v166
	v_and_b32_e32 v4, 0xf0000000, v4
	v_or3_b32 v4, v8, v14, v4
	v_lshl_or_b32 v8, v15, 28, v9
	v_mul_f32_e32 v9, v36, v5
	v_mul_f32_e32 v15, v37, v5
	v_rndne_f32_e32 v9, v9
	v_rndne_f32_e32 v15, v15
	v_cvt_i32_f32_e32 v9, v9
	v_cvt_i32_f32_e32 v15, v15
	v_or3_b32 v8, v8, v22, v24
	v_or3_b32 v8, v8, v23, v25
	v_or3_b32 v8, v8, v16, v17
	v_add_u32_e32 v14, 8, v9
	v_add_u32_e32 v16, 8, v15
	v_lshrrev_b32_e32 v14, 4, v14
	v_and_b32_e32 v16, 0xf0, v16
	v_and_or_b32 v14, v14, 15, v16
	v_lshl_add_u32 v16, v12, 4, v161
	v_lshl_add_u32 v17, v13, 8, v162
	v_and_b32_e32 v16, 0xf00, v16
	v_and_b32_e32 v17, 0xf000, v17
	v_or3_b32 v14, v14, v16, v17
	v_mul_f32_e32 v16, v18, v5
	v_mul_f32_e32 v18, v19, v5
	v_rndne_f32_e32 v16, v16
	v_rndne_f32_e32 v18, v18
	v_mul_f32_e32 v5, v11, v5
	v_cvt_i32_f32_e32 v16, v16
	v_cvt_i32_f32_e32 v18, v18
	v_rndne_f32_e32 v5, v5
	v_cvt_i32_f32_e32 v11, v5
	v_and_b32_e32 v9, 15, v9
	v_lshlrev_b32_e32 v15, 4, v15
	v_lshlrev_b32_e32 v12, 8, v12
	v_lshl_add_u32 v17, v16, 12, v163
	v_lshl_add_u32 v19, v18, 16, v164
	v_and_b32_e32 v15, 0xf0, v15
	v_and_b32_e32 v12, 0xf00, v12
	v_lshlrev_b32_e32 v13, 12, v13
	v_and_b32_e32 v17, 0xf0000, v17
	v_lshlrev_b32_e32 v16, 16, v16
	v_and_b32_e32 v19, 0xf00000, v19
	v_lshl_or_b32 v9, v11, 28, v9
	v_and_b32_e32 v13, 0xf000, v13
	v_and_b32_e32 v16, 0xf0000, v16
	v_or3_b32 v14, v14, v17, v19
	v_lshlrev_b32_e32 v17, 20, v18
	v_lshl_add_u32 v18, v10, 20, v165
	v_lshlrev_b32_e32 v10, 24, v10
	v_or3_b32 v9, v9, v15, v12
	v_and_b32_e32 v17, 0xf00000, v17
	v_and_b32_e32 v10, 0xf000000, v10
	v_or3_b32 v9, v9, v13, v16
	v_lshl_add_u32 v5, v11, 24, v166
	v_or3_b32 v9, v9, v17, v10
	v_lshl_add_u64 v[10:11], s[16:17], 0, v[20:21]
	v_and_b32_e32 v18, 0xf000000, v18
	v_and_b32_e32 v5, 0xf0000000, v5
	v_lshlrev_b64 v[12:13], 8, v[10:11]
	v_or3_b32 v5, v14, v18, v5
	v_lshl_add_u64 v[12:13], v[150:151], 0, v[12:13]
	global_store_dwordx4 v[12:13], v[2:5], off
	global_store_dwordx4 v[12:13], v[6:9], off offset:16
	s_and_saveexec_b64 s[0:1], s[4:5]
	s_cbranch_execz .LBB0_792
	v_mul_f32_e32 v4, 0x3c09ae41, v38
	v_lshl_add_u64 v[2:3], v[10:11], 2, s[10:11]
	global_store_dword v[2:3], v4, off
	s_branch .LBB0_792
